# w_in gelu epilogue packed (pk_mul/pk_fma, batched exp/rcp) + rstd via v_rsq_f32 in w_in/uq/ukv/out-proj epilogues instead of serial IEEE sqrt+div chains
# speedup vs baseline: 1.0237x; 1.0058x over previous
; __device__ __forceinline__ float sq4(f32x4 a) { return (a.x * a.x + a.y * a.y) + (a.z * a.z + a.w * a.w); }
; __device__ __forceinline__ u32x4 pack8(f32x4 a, f32x4 b) { u32x4 o; o.x = cvt_pk(a.x, a.y); o.y = cvt_pk(a.z, a.w); o.z = cvt_pk(b.x, b.y); o.w = cvt_pk(b.z, b.w); return o; }
; __device__ __forceinline__ float rstd_of(const float* SS, int row, float invw) { return 1.0f / sqrtf(SS[row] * invw + EPS); }
; __device__ __forceinline__ void row_stat_add(float* SS, int row, float v, int fq) {
;     v += __shfl_xor(v, 16); v += __shfl_xor(v, 32);
;     if (fq == 0) unsafeAtomicAdd(SS + row, v);
; }
;     __device__ __forceinline__ void operator()(const f32x4 (&acc)[2][2][4][2], const pg8::Unit& u, int wr, int wc, int fr, int fq) const {
;     ...
;         } else if (u.pn == 4) {
; #pragma unroll
;             for (int ai = 0; ai < 2; ++ai)
; #pragma unroll
;                 for (int m = 0; m < 4; ++m) {
;                     const int row = row0 + ai * 128 + m * 16; const float r = rstd_of(SS1, row, 1.f / 1024.f); float ssq = 0.f;
; #pragma unroll
;                     for (int bj = 0; bj < 2; ++bj) {
;                         const f32x4 a = acc[ai][bj][m][0] * r, b = acc[ai][bj][m][1] * r; ssq += sq4(a) + sq4(b);
;                         *(u32x4*)(CQ + (size_t)row * 256 + bj * 128 + colw) = pack8(a, b);
;                     }
;                     row_stat_add(SSQ, row, ssq, fq);
;                 }
.LBB0_348:
	v_lshl_add_u32 v152, s0, 8, v167
	s_mov_b64 s[0:1], -1
	s_cmp_gt_i32 s58, 3
	v_ashrrev_i32_e32 v153, 31, v152
	s_cbranch_scc0 .LBB0_403
	v_lshl_add_u64 v[154:155], v[152:153], 2, s[48:49]
	global_load_dword v156, v[154:155], off
	global_load_dword v200, v[154:155], off offset:64
	global_load_dword v201, v[154:155], off offset:128
	global_load_dword v202, v[154:155], off offset:192
	global_load_dword v203, v[154:155], off offset:512
	global_load_dword v204, v[154:155], off offset:576
	global_load_dword v205, v[154:155], off offset:640
	global_load_dword v206, v[154:155], off offset:704
	s_cmp_eq_u32 s58, 4
	s_waitcnt vmcnt(0)
	v_fmamk_f32 v156, v156, 0x3a800000, v172
	s_mov_b64 s[0:1], -1
	v_rsq_f32_e32 v156, v156
	s_nop 0
	v_mov_b32_e32 v157, v156
	v_pk_mul_f32 v[160:161], v[124:125], v[156:157]
	v_pk_mul_f32 v[158:159], v[120:121], v[156:157]
	s_cbranch_scc1 .LBB0_383
	v_mov_b32_e32 v162, v156
	v_mov_b32_e32 v163, v156
	v_pk_mul_f32 v[164:165], v[126:127], v[162:163]
	v_pk_mul_f32 v[182:183], v[122:123], v[162:163]
	v_mul_f32_e32 v162, v161, v161
	v_mul_f32_e32 v163, v165, v165
	v_fmac_f32_e32 v162, v160, v160
	v_fmac_f32_e32 v163, v164, v164
	v_add_f32_e32 v162, v162, v163
	v_mul_f32_e32 v163, v159, v159
	v_mul_f32_e32 v175, v183, v183
	v_fmac_f32_e32 v163, v158, v158
	v_fmac_f32_e32 v175, v182, v182
	v_add_f32_e32 v163, v163, v175
	v_and_b32_e32 v175, 64, v174
	v_add_f32_e32 v162, v162, v163
	v_xor_b32_e32 v163, 16, v174
	v_add_u32_e32 v176, 64, v175
	v_cmp_lt_i32_e32 vcc, v163, v176
	v_cvt_pk_bf16_f32 v178, v160, v161
	v_cvt_pk_bf16_f32 v179, v164, v165
	v_lshlrev_b64 v[164:165], 8, v[152:153]
	v_lshl_add_u64 v[164:165], v[138:139], 0, v[164:165]
	v_cndmask_b32_e32 v163, v174, v163, vcc
	v_lshlrev_b32_e32 v175, 2, v163
	ds_bpermute_b32 v163, v175, v162
	v_cvt_pk_bf16_f32 v180, v158, v159
	v_cvt_pk_bf16_f32 v181, v182, v183
	global_store_dwordx4 v[164:165], v[178:181], off
	s_waitcnt lgkmcnt(0)
	v_add_f32_e32 v162, v162, v163
	v_xor_b32_e32 v163, 32, v174
	v_cmp_lt_i32_e32 vcc, v163, v176
	s_nop 1
	v_cndmask_b32_e32 v163, v174, v163, vcc
	v_lshlrev_b32_e32 v176, 2, v163
	ds_bpermute_b32 v163, v176, v162
	s_and_saveexec_b64 s[0:1], s[38:39]
	s_cbranch_execz .LBB0_352
	v_lshl_add_u64 v[164:165], v[152:153], 2, s[44:45]
	s_waitcnt lgkmcnt(0)
	v_add_f32_e32 v162, v162, v163
	global_atomic_add_f32 v[164:165], v162, off

; __device__ __forceinline__ float sq4(f32x4 a) { return (a.x * a.x + a.y * a.y) + (a.z * a.z + a.w * a.w); }
; __device__ __forceinline__ u32x4 pack8(f32x4 a, f32x4 b) { u32x4 o; o.x = cvt_pk(a.x, a.y); o.y = cvt_pk(a.z, a.w); o.z = cvt_pk(b.x, b.y); o.w = cvt_pk(b.z, b.w); return o; }
; __device__ __forceinline__ float rstd_of(const float* SS, int row, float invw) { return 1.0f / sqrtf(SS[row] * invw + EPS); }
;     __device__ __forceinline__ void operator()(const f32x4 (&acc)[2][2][4][2], const pg8::Unit& u, int wr, int wc, int fr, int fq) const {
;     ...
;                     const int row = row0 + ai * 128 + m * 16; const float r = rstd_of(SS1, row, 1.f / 1024.f); float ssq = 0.f;
; #pragma unroll
;                     for (int bj = 0; bj < 2; ++bj) {
;                         const f32x4 a = acc[ai][bj][m][0] * r, b = acc[ai][bj][m][1] * r; ssq += sq4(a) + sq4(b);
;                         *(u32x4*)(CQ + (size_t)row * 256 + bj * 128 + colw) = pack8(a, b);
;                     }
;                     row_stat_add(SSQ, row, ssq, fq);
.LBB0_354:
	s_nop 1
	v_or_b32_e32 v162, 16, v152
	s_waitcnt lgkmcnt(0)
	v_ashrrev_i32_e32 v163, 31, v162
	v_lshl_add_u64 v[164:165], v[162:163], 2, s[48:49]
	s_nop 1
	v_mov_b32_e32 v164, v200
	v_fmamk_f32 v164, v164, 0x3a800000, v172
	v_rsq_f32_e32 v164, v164
	s_nop 0
	v_pk_mul_f32 v[180:181], v[110:111], v[164:165] op_sel_hi:[1,0]
	v_pk_mul_f32 v[178:179], v[108:109], v[164:165] op_sel_hi:[1,0]
	v_pk_mul_f32 v[182:183], v[106:107], v[164:165] op_sel_hi:[1,0]
	v_pk_mul_f32 v[184:185], v[104:105], v[164:165] op_sel_hi:[1,0]
	v_mul_f32_e32 v165, v179, v179
	v_mul_f32_e32 v177, v181, v181
	v_mul_f32_e32 v186, v185, v185
	v_mul_f32_e32 v187, v183, v183
	v_fmac_f32_e32 v165, v178, v178
	v_fmac_f32_e32 v177, v180, v180
	v_fmac_f32_e32 v186, v184, v184
	v_fmac_f32_e32 v187, v182, v182
	v_add_f32_e32 v165, v165, v177
	v_add_f32_e32 v177, v186, v187
	v_add_f32_e32 v165, v165, v177
	ds_bpermute_b32 v177, v175, v165
	v_cvt_pk_bf16_f32 v178, v178, v179
	v_cvt_pk_bf16_f32 v179, v180, v181
	v_cvt_pk_bf16_f32 v180, v184, v185
	v_cvt_pk_bf16_f32 v181, v182, v183
	s_waitcnt lgkmcnt(0)
	v_add_f32_e32 v165, v165, v177
	ds_bpermute_b32 v177, v176, v165
	v_lshlrev_b64 v[182:183], 8, v[162:163]
	v_lshl_add_u64 v[182:183], v[138:139], 0, v[182:183]
	global_store_dwordx4 v[182:183], v[178:181], off
	s_and_saveexec_b64 s[0:1], s[38:39]
	s_cbranch_execz .LBB0_356
	v_lshl_add_u64 v[178:179], v[162:163], 2, s[44:45]
	s_waitcnt lgkmcnt(0)
	v_add_f32_e32 v165, v165, v177
	global_atomic_add_f32 v[178:179], v165, off

; __device__ __forceinline__ float sq4(f32x4 a) { return (a.x * a.x + a.y * a.y) + (a.z * a.z + a.w * a.w); }
; __device__ __forceinline__ u32x4 pack8(f32x4 a, f32x4 b) { u32x4 o; o.x = cvt_pk(a.x, a.y); o.y = cvt_pk(a.z, a.w); o.z = cvt_pk(b.x, b.y); o.w = cvt_pk(b.z, b.w); return o; }
; __device__ __forceinline__ float rstd_of(const float* SS, int row, float invw) { return 1.0f / sqrtf(SS[row] * invw + EPS); }
;     __device__ __forceinline__ void operator()(const f32x4 (&acc)[2][2][4][2], const pg8::Unit& u, int wr, int wc, int fr, int fq) const {
;     ...
;                     const int row = row0 + ai * 128 + m * 16; const float r = rstd_of(SS1, row, 1.f / 1024.f); float ssq = 0.f;
; #pragma unroll
;                     for (int bj = 0; bj < 2; ++bj) {
;                         const f32x4 a = acc[ai][bj][m][0] * r, b = acc[ai][bj][m][1] * r; ssq += sq4(a) + sq4(b);
;                         *(u32x4*)(CQ + (size_t)row * 256 + bj * 128 + colw) = pack8(a, b);
;                     }
;                     row_stat_add(SSQ, row, ssq, fq);
.LBB0_358:
	v_or_b32_e32 v162, 32, v152
	v_ashrrev_i32_e32 v163, 31, v162
	v_lshl_add_u64 v[164:165], v[162:163], 2, s[48:49]
	s_nop 1
	v_mov_b32_e32 v164, v201
	v_fmamk_f32 v164, v164, 0x3a800000, v172
	s_waitcnt lgkmcnt(0)
	v_rsq_f32_e32 v164, v164
	s_nop 0
	v_pk_mul_f32 v[180:181], v[94:95], v[164:165] op_sel_hi:[1,0]
	v_pk_mul_f32 v[178:179], v[92:93], v[164:165] op_sel_hi:[1,0]
	v_pk_mul_f32 v[182:183], v[90:91], v[164:165] op_sel_hi:[1,0]
	v_pk_mul_f32 v[184:185], v[88:89], v[164:165] op_sel_hi:[1,0]
	v_mul_f32_e32 v165, v179, v179
	v_mul_f32_e32 v177, v181, v181
	v_mul_f32_e32 v186, v185, v185
	v_mul_f32_e32 v187, v183, v183
	v_fmac_f32_e32 v165, v178, v178
	v_fmac_f32_e32 v177, v180, v180
	v_fmac_f32_e32 v186, v184, v184
	v_fmac_f32_e32 v187, v182, v182
	v_add_f32_e32 v165, v165, v177
	v_add_f32_e32 v177, v186, v187
	v_add_f32_e32 v165, v165, v177
	ds_bpermute_b32 v177, v175, v165
	v_cvt_pk_bf16_f32 v178, v178, v179
	v_cvt_pk_bf16_f32 v179, v180, v181
	v_cvt_pk_bf16_f32 v180, v184, v185
	v_cvt_pk_bf16_f32 v181, v182, v183
	s_waitcnt lgkmcnt(0)
	v_add_f32_e32 v165, v165, v177
	ds_bpermute_b32 v177, v176, v165
	v_lshlrev_b64 v[182:183], 8, v[162:163]
	v_lshl_add_u64 v[182:183], v[138:139], 0, v[182:183]
	global_store_dwordx4 v[182:183], v[178:181], off
	s_and_saveexec_b64 s[0:1], s[38:39]
	s_cbranch_execz .LBB0_360
	v_lshl_add_u64 v[178:179], v[162:163], 2, s[44:45]
	s_waitcnt lgkmcnt(0)
	v_add_f32_e32 v165, v165, v177
	global_atomic_add_f32 v[178:179], v165, off

; __device__ __forceinline__ float sq4(f32x4 a) { return (a.x * a.x + a.y * a.y) + (a.z * a.z + a.w * a.w); }
; __device__ __forceinline__ u32x4 pack8(f32x4 a, f32x4 b) { u32x4 o; o.x = cvt_pk(a.x, a.y); o.y = cvt_pk(a.z, a.w); o.z = cvt_pk(b.x, b.y); o.w = cvt_pk(b.z, b.w); return o; }
; __device__ __forceinline__ float rstd_of(const float* SS, int row, float invw) { return 1.0f / sqrtf(SS[row] * invw + EPS); }
;     __device__ __forceinline__ void operator()(const f32x4 (&acc)[2][2][4][2], const pg8::Unit& u, int wr, int wc, int fr, int fq) const {
;     ...
;                     const int row = row0 + ai * 128 + m * 16; const float r = rstd_of(SS1, row, 1.f / 1024.f); float ssq = 0.f;
; #pragma unroll
;                     for (int bj = 0; bj < 2; ++bj) {
;                         const f32x4 a = acc[ai][bj][m][0] * r, b = acc[ai][bj][m][1] * r; ssq += sq4(a) + sq4(b);
;                         *(u32x4*)(CQ + (size_t)row * 256 + bj * 128 + colw) = pack8(a, b);
;                     }
;                     row_stat_add(SSQ, row, ssq, fq);
.LBB0_362:
	v_or_b32_e32 v162, 48, v152
	v_ashrrev_i32_e32 v163, 31, v162
	v_lshl_add_u64 v[164:165], v[162:163], 2, s[48:49]
	s_nop 1
	v_mov_b32_e32 v164, v202
	v_fmamk_f32 v164, v164, 0x3a800000, v172
	s_waitcnt lgkmcnt(0)
	v_rsq_f32_e32 v164, v164
	s_nop 0
	v_pk_mul_f32 v[180:181], v[78:79], v[164:165] op_sel_hi:[1,0]
	v_pk_mul_f32 v[178:179], v[76:77], v[164:165] op_sel_hi:[1,0]
	v_pk_mul_f32 v[182:183], v[74:75], v[164:165] op_sel_hi:[1,0]
	v_pk_mul_f32 v[184:185], v[72:73], v[164:165] op_sel_hi:[1,0]
	v_mul_f32_e32 v165, v179, v179
	v_mul_f32_e32 v177, v181, v181
	v_mul_f32_e32 v186, v185, v185
	v_mul_f32_e32 v187, v183, v183
	v_fmac_f32_e32 v165, v178, v178
	v_fmac_f32_e32 v177, v180, v180
	v_fmac_f32_e32 v186, v184, v184
	v_fmac_f32_e32 v187, v182, v182
	v_add_f32_e32 v165, v165, v177
	v_add_f32_e32 v177, v186, v187
	v_add_f32_e32 v165, v165, v177
	ds_bpermute_b32 v177, v175, v165
	v_cvt_pk_bf16_f32 v178, v178, v179
	v_cvt_pk_bf16_f32 v179, v180, v181
	v_cvt_pk_bf16_f32 v180, v184, v185
	v_cvt_pk_bf16_f32 v181, v182, v183
	s_waitcnt lgkmcnt(0)
	v_add_f32_e32 v165, v165, v177
	ds_bpermute_b32 v177, v176, v165
	v_lshlrev_b64 v[182:183], 8, v[162:163]
	v_lshl_add_u64 v[182:183], v[138:139], 0, v[182:183]
	global_store_dwordx4 v[182:183], v[178:181], off
	s_and_saveexec_b64 s[0:1], s[38:39]
	s_cbranch_execz .LBB0_364
	v_lshl_add_u64 v[178:179], v[162:163], 2, s[44:45]
	s_waitcnt lgkmcnt(0)
	v_add_f32_e32 v165, v165, v177
	global_atomic_add_f32 v[178:179], v165, off

; __device__ __forceinline__ float sq4(f32x4 a) { return (a.x * a.x + a.y * a.y) + (a.z * a.z + a.w * a.w); }
; __device__ __forceinline__ u32x4 pack8(f32x4 a, f32x4 b) { u32x4 o; o.x = cvt_pk(a.x, a.y); o.y = cvt_pk(a.z, a.w); o.z = cvt_pk(b.x, b.y); o.w = cvt_pk(b.z, b.w); return o; }
; __device__ __forceinline__ float rstd_of(const float* SS, int row, float invw) { return 1.0f / sqrtf(SS[row] * invw + EPS); }
;     __device__ __forceinline__ void operator()(const f32x4 (&acc)[2][2][4][2], const pg8::Unit& u, int wr, int wc, int fr, int fq) const {
;     ...
;                     const int row = row0 + ai * 128 + m * 16; const float r = rstd_of(SS1, row, 1.f / 1024.f); float ssq = 0.f;
; #pragma unroll
;                     for (int bj = 0; bj < 2; ++bj) {
;                         const f32x4 a = acc[ai][bj][m][0] * r, b = acc[ai][bj][m][1] * r; ssq += sq4(a) + sq4(b);
;                         *(u32x4*)(CQ + (size_t)row * 256 + bj * 128 + colw) = pack8(a, b);
;                     }
;                     row_stat_add(SSQ, row, ssq, fq);
.LBB0_366:
	s_nop 1
	v_mov_b32_e32 v162, v203
	v_fmamk_f32 v162, v162, 0x3a800000, v172
	v_rsq_f32_e32 v164, v162
	s_nop 0
	s_waitcnt lgkmcnt(0)
	v_add_u32_e32 v162, 0x80, v152
	v_pk_mul_f32 v[180:181], v[62:63], v[164:165] op_sel_hi:[1,0]
	v_pk_mul_f32 v[178:179], v[60:61], v[164:165] op_sel_hi:[1,0]
	v_pk_mul_f32 v[182:183], v[58:59], v[164:165] op_sel_hi:[1,0]
	v_pk_mul_f32 v[184:185], v[56:57], v[164:165] op_sel_hi:[1,0]
	v_mul_f32_e32 v163, v179, v179
	v_mul_f32_e32 v165, v181, v181
	v_mul_f32_e32 v177, v185, v185
	v_mul_f32_e32 v186, v183, v183
	v_fmac_f32_e32 v163, v178, v178
	v_fmac_f32_e32 v165, v180, v180
	v_fmac_f32_e32 v177, v184, v184
	v_fmac_f32_e32 v186, v182, v182
	v_add_f32_e32 v163, v163, v165
	v_add_f32_e32 v165, v177, v186
	v_add_f32_e32 v165, v163, v165
	ds_bpermute_b32 v177, v175, v165
	v_ashrrev_i32_e32 v163, 31, v162
	v_cvt_pk_bf16_f32 v178, v178, v179
	v_cvt_pk_bf16_f32 v179, v180, v181
	v_cvt_pk_bf16_f32 v180, v184, v185
	s_waitcnt lgkmcnt(0)
	v_add_f32_e32 v165, v165, v177
	ds_bpermute_b32 v177, v176, v165
	v_cvt_pk_bf16_f32 v181, v182, v183
	v_lshlrev_b64 v[182:183], 8, v[162:163]
	v_lshl_add_u64 v[182:183], v[138:139], 0, v[182:183]
	global_store_dwordx4 v[182:183], v[178:181], off
	s_and_saveexec_b64 s[0:1], s[38:39]
	s_cbranch_execz .LBB0_368
	v_lshl_add_u64 v[178:179], v[162:163], 2, s[44:45]
	s_waitcnt lgkmcnt(0)
	v_add_f32_e32 v165, v165, v177
	global_atomic_add_f32 v[178:179], v165, off

; __device__ __forceinline__ float sq4(f32x4 a) { return (a.x * a.x + a.y * a.y) + (a.z * a.z + a.w * a.w); }
; __device__ __forceinline__ u32x4 pack8(f32x4 a, f32x4 b) { u32x4 o; o.x = cvt_pk(a.x, a.y); o.y = cvt_pk(a.z, a.w); o.z = cvt_pk(b.x, b.y); o.w = cvt_pk(b.z, b.w); return o; }
; __device__ __forceinline__ float rstd_of(const float* SS, int row, float invw) { return 1.0f / sqrtf(SS[row] * invw + EPS); }
;     __device__ __forceinline__ void operator()(const f32x4 (&acc)[2][2][4][2], const pg8::Unit& u, int wr, int wc, int fr, int fq) const {
;     ...
;                     const int row = row0 + ai * 128 + m * 16; const float r = rstd_of(SS1, row, 1.f / 1024.f); float ssq = 0.f;
; #pragma unroll
;                     for (int bj = 0; bj < 2; ++bj) {
;                         const f32x4 a = acc[ai][bj][m][0] * r, b = acc[ai][bj][m][1] * r; ssq += sq4(a) + sq4(b);
;                         *(u32x4*)(CQ + (size_t)row * 256 + bj * 128 + colw) = pack8(a, b);
;                     }
;                     row_stat_add(SSQ, row, ssq, fq);
.LBB0_370:
	s_nop 1
	v_mov_b32_e32 v162, v204
	v_fmamk_f32 v162, v162, 0x3a800000, v172
	v_rsq_f32_e32 v164, v162
	s_nop 0
	s_waitcnt lgkmcnt(0)
	v_add_u32_e32 v162, 0x90, v152
	v_pk_mul_f32 v[180:181], v[46:47], v[164:165] op_sel_hi:[1,0]
	v_pk_mul_f32 v[178:179], v[44:45], v[164:165] op_sel_hi:[1,0]
	v_pk_mul_f32 v[182:183], v[42:43], v[164:165] op_sel_hi:[1,0]
	v_pk_mul_f32 v[184:185], v[40:41], v[164:165] op_sel_hi:[1,0]
	v_mul_f32_e32 v163, v179, v179
	v_mul_f32_e32 v165, v181, v181
	v_mul_f32_e32 v177, v185, v185
	v_mul_f32_e32 v186, v183, v183
	v_fmac_f32_e32 v163, v178, v178
	v_fmac_f32_e32 v165, v180, v180
	v_fmac_f32_e32 v177, v184, v184
	v_fmac_f32_e32 v186, v182, v182
	v_add_f32_e32 v163, v163, v165
	v_add_f32_e32 v165, v177, v186
	v_add_f32_e32 v165, v163, v165
	ds_bpermute_b32 v177, v175, v165
	v_ashrrev_i32_e32 v163, 31, v162
	v_cvt_pk_bf16_f32 v178, v178, v179
	v_cvt_pk_bf16_f32 v179, v180, v181
	v_cvt_pk_bf16_f32 v180, v184, v185
	s_waitcnt lgkmcnt(0)
	v_add_f32_e32 v165, v165, v177
	ds_bpermute_b32 v177, v176, v165
	v_cvt_pk_bf16_f32 v181, v182, v183
	v_lshlrev_b64 v[182:183], 8, v[162:163]
	v_lshl_add_u64 v[182:183], v[138:139], 0, v[182:183]
	global_store_dwordx4 v[182:183], v[178:181], off
	s_and_saveexec_b64 s[0:1], s[38:39]
	s_cbranch_execz .LBB0_372
	v_lshl_add_u64 v[178:179], v[162:163], 2, s[44:45]
	s_waitcnt lgkmcnt(0)
	v_add_f32_e32 v165, v165, v177
	global_atomic_add_f32 v[178:179], v165, off

; __device__ __forceinline__ float sq4(f32x4 a) { return (a.x * a.x + a.y * a.y) + (a.z * a.z + a.w * a.w); }
; __device__ __forceinline__ u32x4 pack8(f32x4 a, f32x4 b) { u32x4 o; o.x = cvt_pk(a.x, a.y); o.y = cvt_pk(a.z, a.w); o.z = cvt_pk(b.x, b.y); o.w = cvt_pk(b.z, b.w); return o; }
; __device__ __forceinline__ float rstd_of(const float* SS, int row, float invw) { return 1.0f / sqrtf(SS[row] * invw + EPS); }
; __device__ __forceinline__ void row_stat_add(float* SS, int row, float v, int fq) {
;     v += __shfl_xor(v, 16); v += __shfl_xor(v, 32);
;     if (fq == 0) unsafeAtomicAdd(SS + row, v);
; }
;     __device__ __forceinline__ void operator()(const f32x4 (&acc)[2][2][4][2], const pg8::Unit& u, int wr, int wc, int fr, int fq) const {
;     ...
; #pragma unroll
;             for (int ai = 0; ai < 2; ++ai)
; #pragma unroll
;                 for (int m = 0; m < 4; ++m) {
;                     const int row = row0 + ai * 128 + m * 16; const float r = rstd_of(SS1, row, 1.f / 1024.f);
;                     const f32x4 a = acc[ai][0][m][0] * r, b = acc[ai][0][m][1] * r;
;                     *(u32x4*)(CKV + (size_t)row * 128 + colw) = pack8(a, b);
;                     row_stat_add(SSKV, row, sq4(a) + sq4(b), fq);
;                     if (wc == 0) { float* d = KR + (size_t)row * 32 + 8 * fq; *(f32x4*)d = acc[ai][1][m][0] * r; *(f32x4*)(d + 4) = acc[ai][1][m][1] * r; }
;                 }
.LBB0_374:
	s_nop 1
	v_mov_b32_e32 v162, v205
	v_fmamk_f32 v162, v162, 0x3a800000, v172
	v_rsq_f32_e32 v164, v162
	s_nop 0
	s_waitcnt lgkmcnt(0)
	v_add_u32_e32 v162, 0xa0, v152
	v_pk_mul_f32 v[180:181], v[30:31], v[164:165] op_sel_hi:[1,0]
	v_pk_mul_f32 v[178:179], v[28:29], v[164:165] op_sel_hi:[1,0]
	v_pk_mul_f32 v[182:183], v[26:27], v[164:165] op_sel_hi:[1,0]
	v_pk_mul_f32 v[184:185], v[24:25], v[164:165] op_sel_hi:[1,0]
	v_mul_f32_e32 v163, v179, v179
	v_mul_f32_e32 v165, v181, v181
	v_mul_f32_e32 v177, v185, v185
	v_mul_f32_e32 v186, v183, v183
	v_fmac_f32_e32 v163, v178, v178
	v_fmac_f32_e32 v165, v180, v180
	v_fmac_f32_e32 v177, v184, v184
	v_fmac_f32_e32 v186, v182, v182
	v_add_f32_e32 v163, v163, v165
	v_add_f32_e32 v165, v177, v186
	v_add_f32_e32 v165, v163, v165
	ds_bpermute_b32 v177, v175, v165
	v_ashrrev_i32_e32 v163, 31, v162
	v_cvt_pk_bf16_f32 v178, v178, v179
	v_cvt_pk_bf16_f32 v179, v180, v181
	v_cvt_pk_bf16_f32 v180, v184, v185
	s_waitcnt lgkmcnt(0)
	v_add_f32_e32 v165, v165, v177
	ds_bpermute_b32 v177, v176, v165
	v_cvt_pk_bf16_f32 v181, v182, v183
	v_lshlrev_b64 v[182:183], 8, v[162:163]
	v_lshl_add_u64 v[182:183], v[138:139], 0, v[182:183]
	global_store_dwordx4 v[182:183], v[178:181], off
	s_and_saveexec_b64 s[0:1], s[38:39]
	s_cbranch_execz .LBB0_376
	v_lshl_add_u64 v[178:179], v[162:163], 2, s[44:45]
	s_waitcnt lgkmcnt(0)
	v_add_f32_e32 v165, v165, v177
	global_atomic_add_f32 v[178:179], v165, off

; __device__ __forceinline__ float sq4(f32x4 a) { return (a.x * a.x + a.y * a.y) + (a.z * a.z + a.w * a.w); }
; __device__ __forceinline__ u32x4 pack8(f32x4 a, f32x4 b) { u32x4 o; o.x = cvt_pk(a.x, a.y); o.y = cvt_pk(a.z, a.w); o.z = cvt_pk(b.x, b.y); o.w = cvt_pk(b.z, b.w); return o; }
; __device__ __forceinline__ float rstd_of(const float* SS, int row, float invw) { return 1.0f / sqrtf(SS[row] * invw + EPS); }
; __device__ __forceinline__ void row_stat_add(float* SS, int row, float v, int fq) {
;     v += __shfl_xor(v, 16); v += __shfl_xor(v, 32);
;     if (fq == 0) unsafeAtomicAdd(SS + row, v);
; }
;     __device__ __forceinline__ void operator()(const f32x4 (&acc)[2][2][4][2], const pg8::Unit& u, int wr, int wc, int fr, int fq) const {
;     ...
; #pragma unroll
;             for (int ai = 0; ai < 2; ++ai)
; #pragma unroll
;                 for (int m = 0; m < 4; ++m) {
;                     const int row = row0 + ai * 128 + m * 16; const float r = rstd_of(SS1, row, 1.f / 1024.f);
;                     const f32x4 a = acc[ai][0][m][0] * r, b = acc[ai][0][m][1] * r;
;                     *(u32x4*)(CKV + (size_t)row * 128 + colw) = pack8(a, b);
;                     row_stat_add(SSKV, row, sq4(a) + sq4(b), fq);
;                     if (wc == 0) { float* d = KR + (size_t)row * 32 + 8 * fq; *(f32x4*)d = acc[ai][1][m][0] * r; *(f32x4*)(d + 4) = acc[ai][1][m][1] * r; }
;                 }
.LBB0_378:
	s_nop 1
	v_mov_b32_e32 v162, v206
	v_fmamk_f32 v162, v162, 0x3a800000, v172
	v_rsq_f32_e32 v164, v162
	s_nop 0
	s_waitcnt lgkmcnt(0)
	v_add_u32_e32 v162, 0xb0, v152
	v_pk_mul_f32 v[180:181], v[14:15], v[164:165] op_sel_hi:[1,0]
	v_pk_mul_f32 v[178:179], v[12:13], v[164:165] op_sel_hi:[1,0]
	v_pk_mul_f32 v[182:183], v[10:11], v[164:165] op_sel_hi:[1,0]
	v_pk_mul_f32 v[184:185], v[8:9], v[164:165] op_sel_hi:[1,0]
	v_mul_f32_e32 v163, v179, v179
	v_mul_f32_e32 v165, v181, v181
	v_mul_f32_e32 v177, v185, v185
	v_mul_f32_e32 v186, v183, v183
	v_fmac_f32_e32 v163, v178, v178
	v_fmac_f32_e32 v165, v180, v180
	v_fmac_f32_e32 v177, v184, v184
	v_fmac_f32_e32 v186, v182, v182
	v_add_f32_e32 v163, v163, v165
	v_add_f32_e32 v165, v177, v186
	v_add_f32_e32 v165, v163, v165
	ds_bpermute_b32 v175, v175, v165
	v_ashrrev_i32_e32 v163, 31, v162
	v_cvt_pk_bf16_f32 v178, v178, v179
	v_cvt_pk_bf16_f32 v179, v180, v181
	v_cvt_pk_bf16_f32 v180, v184, v185
	s_waitcnt lgkmcnt(0)
	v_add_f32_e32 v165, v165, v175
	ds_bpermute_b32 v175, v176, v165
	v_lshlrev_b64 v[176:177], 8, v[162:163]
	v_lshl_add_u64 v[176:177], v[138:139], 0, v[176:177]
	v_cvt_pk_bf16_f32 v181, v182, v183
	global_store_dwordx4 v[176:177], v[178:181], off
	s_and_saveexec_b64 s[0:1], s[38:39]
	s_cbranch_execz .LBB0_380
	v_lshl_add_u64 v[176:177], v[162:163], 2, s[44:45]
	s_waitcnt lgkmcnt(0)
	v_add_f32_e32 v165, v165, v175
	global_atomic_add_f32 v[176:177], v165, off

; __device__ __forceinline__ float sq4(f32x4 a) { return (a.x * a.x + a.y * a.y) + (a.z * a.z + a.w * a.w); }
; __device__ __forceinline__ u32x4 pack8(f32x4 a, f32x4 b) { u32x4 o; o.x = cvt_pk(a.x, a.y); o.y = cvt_pk(a.z, a.w); o.z = cvt_pk(b.x, b.y); o.w = cvt_pk(b.z, b.w); return o; }
; __device__ __forceinline__ float rstd_of(const float* SS, int row, float invw) { return 1.0f / sqrtf(SS[row] * invw + EPS); }
; __device__ __forceinline__ void row_stat_add(float* SS, int row, float v, int fq) {
;     v += __shfl_xor(v, 16); v += __shfl_xor(v, 32);
;     if (fq == 0) unsafeAtomicAdd(SS + row, v);
; }
;     __device__ __forceinline__ void operator()(const f32x4 (&acc)[2][2][4][2], const pg8::Unit& u, int wr, int wc, int fr, int fq) const {
;     ...
; #pragma unroll
;             for (int ai = 0; ai < 2; ++ai)
; #pragma unroll
;                 for (int m = 0; m < 4; ++m) {
;                     const int row = row0 + ai * 128 + m * 16; const float r = rstd_of(SS1, row, 1.f / 1024.f); float ssq = 0.f;
; #pragma unroll
;                     for (int bj = 0; bj < 2; ++bj) {
;                         const f32x4 a = acc[ai][bj][m][0] * r, b = acc[ai][bj][m][1] * r; ssq += sq4(a) + sq4(b);
;                         *(u32x4*)(CQ + (size_t)row * 256 + bj * 128 + colw) = pack8(a, b);
;                     }
;                     row_stat_add(SSQ, row, ssq, fq);
;                 }
.LBB0_386:
	s_or_b64 exec, exec, s[0:1]
	v_or_b32_e32 v156, 16, v152
	s_waitcnt lgkmcnt(0)
	v_ashrrev_i32_e32 v157, 31, v156
	v_lshl_add_u64 v[160:161], v[156:157], 2, s[48:49]
	s_nop 1
	v_mov_b32_e32 v160, v200
	v_lshlrev_b64 v[176:177], 9, v[156:157]
	v_lshl_add_u64 v[176:177], v[142:143], 0, v[176:177]
	v_fmamk_f32 v160, v160, 0x3a800000, v172
	v_rsq_f32_e32 v164, v160
	s_nop 0
	v_pk_mul_f32 v[162:163], v[110:111], v[164:165] op_sel_hi:[1,0]
	v_pk_mul_f32 v[160:161], v[108:109], v[164:165] op_sel_hi:[1,0]
	v_pk_mul_f32 v[178:179], v[106:107], v[164:165] op_sel_hi:[1,0]
	v_pk_mul_f32 v[180:181], v[104:105], v[164:165] op_sel_hi:[1,0]
	v_mul_f32_e32 v165, v161, v161
	v_mul_f32_e32 v175, v163, v163
	v_fmac_f32_e32 v165, v160, v160
	v_fmac_f32_e32 v175, v162, v162
	v_add_f32_e32 v165, v165, v175
	v_mul_f32_e32 v175, v181, v181
	v_mul_f32_e32 v182, v179, v179
	v_cvt_pk_bf16_f32 v160, v160, v161
	v_cvt_pk_bf16_f32 v161, v162, v163
	v_cvt_pk_bf16_f32 v162, v180, v181
	v_cvt_pk_bf16_f32 v163, v178, v179
	v_fmac_f32_e32 v175, v180, v180
	v_fmac_f32_e32 v182, v178, v178
	global_store_dwordx4 v[176:177], v[160:163], off
	v_add_f32_e32 v175, v175, v182
	v_add_f32_e32 v175, v165, v175
	v_pk_mul_f32 v[162:163], v[102:103], v[164:165] op_sel_hi:[1,0]
	v_pk_mul_f32 v[160:161], v[100:101], v[164:165] op_sel_hi:[1,0]
	v_mul_f32_e32 v181, v163, v163
	v_mul_f32_e32 v180, v161, v161
	v_pk_mul_f32 v[178:179], v[98:99], v[164:165] op_sel_hi:[1,0]
	v_pk_mul_f32 v[164:165], v[96:97], v[164:165] op_sel_hi:[1,0]
	v_fmac_f32_e32 v180, v160, v160
	v_fmac_f32_e32 v181, v162, v162
	v_add_f32_e32 v180, v180, v181
	v_mul_f32_e32 v181, v165, v165
	v_mul_f32_e32 v182, v179, v179
	v_fmac_f32_e32 v181, v164, v164
	v_fmac_f32_e32 v182, v178, v178
	v_add_f32_e32 v181, v181, v182
	v_add_f32_e32 v180, v180, v181
	v_add_f32_e32 v175, v175, v180
	v_cvt_pk_bf16_f32 v160, v160, v161
	v_cvt_pk_bf16_f32 v161, v162, v163
	v_cvt_pk_bf16_f32 v162, v164, v165
	v_cvt_pk_bf16_f32 v163, v178, v179
	global_store_dwordx4 v[176:177], v[160:163], off offset:256
	ds_bpermute_b32 v160, v158, v175
	s_waitcnt lgkmcnt(0)
	v_add_f32_e32 v160, v175, v160
	ds_bpermute_b32 v161, v159, v160
	s_and_saveexec_b64 s[0:1], s[38:39]
	s_cbranch_execz .LBB0_388
	v_lshl_add_u64 v[156:157], v[156:157], 2, s[46:47]
	s_waitcnt lgkmcnt(0)
	v_add_f32_e32 v160, v160, v161
	global_atomic_add_f32 v[156:157], v160, off
.LBB0_388:
	s_or_b64 exec, exec, s[0:1]
	v_or_b32_e32 v156, 32, v152
	v_ashrrev_i32_e32 v157, 31, v156
	s_waitcnt lgkmcnt(0)
	v_lshl_add_u64 v[160:161], v[156:157], 2, s[48:49]
	s_nop 1
	v_mov_b32_e32 v160, v201
	v_lshlrev_b64 v[176:177], 9, v[156:157]
	v_lshl_add_u64 v[176:177], v[142:143], 0, v[176:177]
	v_fmamk_f32 v160, v160, 0x3a800000, v172
	v_rsq_f32_e32 v164, v160
	s_nop 0
	v_pk_mul_f32 v[162:163], v[94:95], v[164:165] op_sel_hi:[1,0]
	v_pk_mul_f32 v[160:161], v[92:93], v[164:165] op_sel_hi:[1,0]
	v_pk_mul_f32 v[178:179], v[90:91], v[164:165] op_sel_hi:[1,0]
	v_pk_mul_f32 v[180:181], v[88:89], v[164:165] op_sel_hi:[1,0]
	v_mul_f32_e32 v165, v161, v161
	v_mul_f32_e32 v175, v163, v163
	v_fmac_f32_e32 v165, v160, v160
	v_fmac_f32_e32 v175, v162, v162
	v_add_f32_e32 v165, v165, v175
	v_mul_f32_e32 v175, v181, v181
	v_mul_f32_e32 v182, v179, v179
	v_cvt_pk_bf16_f32 v160, v160, v161
	v_cvt_pk_bf16_f32 v161, v162, v163
	v_cvt_pk_bf16_f32 v162, v180, v181
	v_cvt_pk_bf16_f32 v163, v178, v179
	v_fmac_f32_e32 v175, v180, v180
	v_fmac_f32_e32 v182, v178, v178
	global_store_dwordx4 v[176:177], v[160:163], off
	v_add_f32_e32 v175, v175, v182
	v_add_f32_e32 v175, v165, v175
	v_pk_mul_f32 v[162:163], v[86:87], v[164:165] op_sel_hi:[1,0]
	v_pk_mul_f32 v[160:161], v[84:85], v[164:165] op_sel_hi:[1,0]
	v_mul_f32_e32 v181, v163, v163
	v_mul_f32_e32 v180, v161, v161
	v_pk_mul_f32 v[178:179], v[82:83], v[164:165] op_sel_hi:[1,0]
	v_pk_mul_f32 v[164:165], v[80:81], v[164:165] op_sel_hi:[1,0]
	v_fmac_f32_e32 v180, v160, v160
	v_fmac_f32_e32 v181, v162, v162
	v_add_f32_e32 v180, v180, v181
	v_mul_f32_e32 v181, v165, v165
	v_mul_f32_e32 v182, v179, v179
	v_fmac_f32_e32 v181, v164, v164
	v_fmac_f32_e32 v182, v178, v178
	v_add_f32_e32 v181, v181, v182
	v_add_f32_e32 v180, v180, v181
	v_add_f32_e32 v175, v175, v180
	v_cvt_pk_bf16_f32 v160, v160, v161
	v_cvt_pk_bf16_f32 v161, v162, v163
	v_cvt_pk_bf16_f32 v162, v164, v165
	v_cvt_pk_bf16_f32 v163, v178, v179
	global_store_dwordx4 v[176:177], v[160:163], off offset:256
	ds_bpermute_b32 v160, v158, v175
	s_waitcnt lgkmcnt(0)
	v_add_f32_e32 v160, v175, v160
	ds_bpermute_b32 v161, v159, v160
	s_and_saveexec_b64 s[0:1], s[38:39]
	s_cbranch_execz .LBB0_390
	v_lshl_add_u64 v[156:157], v[156:157], 2, s[46:47]
	s_waitcnt lgkmcnt(0)
	v_add_f32_e32 v160, v160, v161
	global_atomic_add_f32 v[156:157], v160, off
; __device__ __forceinline__ float sq4(f32x4 a) { return (a.x * a.x + a.y * a.y) + (a.z * a.z + a.w * a.w); }
; __device__ __forceinline__ u32x4 pack8(f32x4 a, f32x4 b) { u32x4 o; o.x = cvt_pk(a.x, a.y); o.y = cvt_pk(a.z, a.w); o.z = cvt_pk(b.x, b.y); o.w = cvt_pk(b.z, b.w); return o; }
; __device__ __forceinline__ float rstd_of(const float* SS, int row, float invw) { return 1.0f / sqrtf(SS[row] * invw + EPS); }
; __device__ __forceinline__ void row_stat_add(float* SS, int row, float v, int fq) {
;     v += __shfl_xor(v, 16); v += __shfl_xor(v, 32);
;     if (fq == 0) unsafeAtomicAdd(SS + row, v);
; }
;     __device__ __forceinline__ void operator()(const f32x4 (&acc)[2][2][4][2], const pg8::Unit& u, int wr, int wc, int fr, int fq) const {
;     ...
; #pragma unroll
;             for (int ai = 0; ai < 2; ++ai)
; #pragma unroll
;                 for (int m = 0; m < 4; ++m) {
;                     const int row = row0 + ai * 128 + m * 16; const float r = rstd_of(SS1, row, 1.f / 1024.f); float ssq = 0.f;
; #pragma unroll
;                     for (int bj = 0; bj < 2; ++bj) {
;                         const f32x4 a = acc[ai][bj][m][0] * r, b = acc[ai][bj][m][1] * r; ssq += sq4(a) + sq4(b);
;                         *(u32x4*)(CQ + (size_t)row * 256 + bj * 128 + colw) = pack8(a, b);
;                     }
;                     row_stat_add(SSQ, row, ssq, fq);
;                 }
.LBB0_390:
	s_or_b64 exec, exec, s[0:1]
	v_or_b32_e32 v156, 48, v152
	v_ashrrev_i32_e32 v157, 31, v156
	s_waitcnt lgkmcnt(0)
	v_lshl_add_u64 v[160:161], v[156:157], 2, s[48:49]
	s_nop 1
	v_mov_b32_e32 v160, v202
	v_lshlrev_b64 v[176:177], 9, v[156:157]
	v_lshl_add_u64 v[176:177], v[142:143], 0, v[176:177]
	v_fmamk_f32 v160, v160, 0x3a800000, v172
	v_rsq_f32_e32 v164, v160
	s_nop 0
	v_pk_mul_f32 v[162:163], v[78:79], v[164:165] op_sel_hi:[1,0]
	v_pk_mul_f32 v[160:161], v[76:77], v[164:165] op_sel_hi:[1,0]
	v_pk_mul_f32 v[178:179], v[74:75], v[164:165] op_sel_hi:[1,0]
	v_pk_mul_f32 v[180:181], v[72:73], v[164:165] op_sel_hi:[1,0]
	v_mul_f32_e32 v165, v161, v161
	v_mul_f32_e32 v175, v163, v163
	v_fmac_f32_e32 v165, v160, v160
	v_fmac_f32_e32 v175, v162, v162
	v_add_f32_e32 v165, v165, v175
	v_mul_f32_e32 v175, v181, v181
	v_mul_f32_e32 v182, v179, v179
	v_cvt_pk_bf16_f32 v160, v160, v161
	v_cvt_pk_bf16_f32 v161, v162, v163
	v_cvt_pk_bf16_f32 v162, v180, v181
	v_cvt_pk_bf16_f32 v163, v178, v179
	v_fmac_f32_e32 v175, v180, v180
	v_fmac_f32_e32 v182, v178, v178
	global_store_dwordx4 v[176:177], v[160:163], off
	v_add_f32_e32 v175, v175, v182
	v_add_f32_e32 v175, v165, v175
	v_pk_mul_f32 v[162:163], v[70:71], v[164:165] op_sel_hi:[1,0]
	v_pk_mul_f32 v[160:161], v[68:69], v[164:165] op_sel_hi:[1,0]
	v_mul_f32_e32 v181, v163, v163
	v_mul_f32_e32 v180, v161, v161
	v_pk_mul_f32 v[178:179], v[66:67], v[164:165] op_sel_hi:[1,0]
	v_pk_mul_f32 v[164:165], v[64:65], v[164:165] op_sel_hi:[1,0]
	v_fmac_f32_e32 v180, v160, v160
	v_fmac_f32_e32 v181, v162, v162
	v_add_f32_e32 v180, v180, v181
	v_mul_f32_e32 v181, v165, v165
	v_mul_f32_e32 v182, v179, v179
	v_fmac_f32_e32 v181, v164, v164
	v_fmac_f32_e32 v182, v178, v178
	v_add_f32_e32 v181, v181, v182
	v_add_f32_e32 v180, v180, v181
	v_add_f32_e32 v175, v175, v180
	v_cvt_pk_bf16_f32 v160, v160, v161
	v_cvt_pk_bf16_f32 v161, v162, v163
	v_cvt_pk_bf16_f32 v162, v164, v165
	v_cvt_pk_bf16_f32 v163, v178, v179
	global_store_dwordx4 v[176:177], v[160:163], off offset:256
	ds_bpermute_b32 v160, v158, v175
	s_waitcnt lgkmcnt(0)
	v_add_f32_e32 v160, v175, v160
	ds_bpermute_b32 v161, v159, v160
	s_and_saveexec_b64 s[0:1], s[38:39]
	s_cbranch_execz .LBB0_392
	v_lshl_add_u64 v[156:157], v[156:157], 2, s[46:47]
	s_waitcnt lgkmcnt(0)
	v_add_f32_e32 v160, v160, v161
	global_atomic_add_f32 v[156:157], v160, off
.LBB0_392:
	s_or_b64 exec, exec, s[0:1]
	s_nop 1
	v_mov_b32_e32 v160, v203
	v_add_u32_e32 v156, 0x80, v152
	v_ashrrev_i32_e32 v157, 31, v156
	v_lshlrev_b64 v[176:177], 9, v[156:157]
	v_lshl_add_u64 v[176:177], v[142:143], 0, v[176:177]
	v_fmamk_f32 v160, v160, 0x3a800000, v172
	s_waitcnt lgkmcnt(0)
	v_rsq_f32_e32 v164, v160
	s_nop 0
	v_pk_mul_f32 v[162:163], v[62:63], v[164:165] op_sel_hi:[1,0]
	v_pk_mul_f32 v[160:161], v[60:61], v[164:165] op_sel_hi:[1,0]
	v_pk_mul_f32 v[178:179], v[58:59], v[164:165] op_sel_hi:[1,0]
	v_pk_mul_f32 v[180:181], v[56:57], v[164:165] op_sel_hi:[1,0]
	v_mul_f32_e32 v165, v161, v161
	v_mul_f32_e32 v175, v163, v163
	v_fmac_f32_e32 v165, v160, v160
	v_fmac_f32_e32 v175, v162, v162
	v_add_f32_e32 v165, v165, v175
	v_mul_f32_e32 v175, v181, v181
	v_mul_f32_e32 v182, v179, v179
	v_cvt_pk_bf16_f32 v160, v160, v161
	v_cvt_pk_bf16_f32 v161, v162, v163
	v_cvt_pk_bf16_f32 v162, v180, v181
	v_cvt_pk_bf16_f32 v163, v178, v179
	v_fmac_f32_e32 v175, v180, v180
	v_fmac_f32_e32 v182, v178, v178
	global_store_dwordx4 v[176:177], v[160:163], off
	v_add_f32_e32 v175, v175, v182
	v_add_f32_e32 v175, v165, v175
	v_pk_mul_f32 v[162:163], v[54:55], v[164:165] op_sel_hi:[1,0]
	v_pk_mul_f32 v[160:161], v[52:53], v[164:165] op_sel_hi:[1,0]
	v_mul_f32_e32 v181, v163, v163
	v_mul_f32_e32 v180, v161, v161
	v_pk_mul_f32 v[178:179], v[50:51], v[164:165] op_sel_hi:[1,0]
	v_pk_mul_f32 v[164:165], v[48:49], v[164:165] op_sel_hi:[1,0]
	v_fmac_f32_e32 v180, v160, v160
	v_fmac_f32_e32 v181, v162, v162
	v_add_f32_e32 v180, v180, v181
	v_mul_f32_e32 v181, v165, v165
	v_mul_f32_e32 v182, v179, v179
	v_fmac_f32_e32 v181, v164, v164
	v_fmac_f32_e32 v182, v178, v178
	v_add_f32_e32 v181, v181, v182
	v_add_f32_e32 v180, v180, v181
	v_add_f32_e32 v175, v175, v180
	v_cvt_pk_bf16_f32 v160, v160, v161
	v_cvt_pk_bf16_f32 v161, v162, v163
	v_cvt_pk_bf16_f32 v162, v164, v165
	v_cvt_pk_bf16_f32 v163, v178, v179
	global_store_dwordx4 v[176:177], v[160:163], off offset:256
	ds_bpermute_b32 v160, v158, v175
	s_waitcnt lgkmcnt(0)
	v_add_f32_e32 v160, v175, v160
	ds_bpermute_b32 v161, v159, v160
	s_and_saveexec_b64 s[0:1], s[38:39]
	s_cbranch_execz .LBB0_394
	v_lshl_add_u64 v[156:157], v[156:157], 2, s[46:47]
	s_waitcnt lgkmcnt(0)
	v_add_f32_e32 v160, v160, v161
	global_atomic_add_f32 v[156:157], v160, off
; __device__ __forceinline__ float sq4(f32x4 a) { return (a.x * a.x + a.y * a.y) + (a.z * a.z + a.w * a.w); }
; __device__ __forceinline__ u32x4 pack8(f32x4 a, f32x4 b) { u32x4 o; o.x = cvt_pk(a.x, a.y); o.y = cvt_pk(a.z, a.w); o.z = cvt_pk(b.x, b.y); o.w = cvt_pk(b.z, b.w); return o; }
; __device__ __forceinline__ float rstd_of(const float* SS, int row, float invw) { return 1.0f / sqrtf(SS[row] * invw + EPS); }
; __device__ __forceinline__ void row_stat_add(float* SS, int row, float v, int fq) {
;     v += __shfl_xor(v, 16); v += __shfl_xor(v, 32);
;     if (fq == 0) unsafeAtomicAdd(SS + row, v);
; }
;     __device__ __forceinline__ void operator()(const f32x4 (&acc)[2][2][4][2], const pg8::Unit& u, int wr, int wc, int fr, int fq) const {
;     ...
; #pragma unroll
;             for (int ai = 0; ai < 2; ++ai)
; #pragma unroll
;                 for (int m = 0; m < 4; ++m) {
;                     const int row = row0 + ai * 128 + m * 16; const float r = rstd_of(SS1, row, 1.f / 1024.f); float ssq = 0.f;
; #pragma unroll
;                     for (int bj = 0; bj < 2; ++bj) {
;                         const f32x4 a = acc[ai][bj][m][0] * r, b = acc[ai][bj][m][1] * r; ssq += sq4(a) + sq4(b);
;                         *(u32x4*)(CQ + (size_t)row * 256 + bj * 128 + colw) = pack8(a, b);
;                     }
;                     row_stat_add(SSQ, row, ssq, fq);
;                 }
.LBB0_394:
	s_or_b64 exec, exec, s[0:1]
	s_nop 1
	v_mov_b32_e32 v160, v204
	v_add_u32_e32 v156, 0x90, v152
	v_ashrrev_i32_e32 v157, 31, v156
	v_lshlrev_b64 v[176:177], 9, v[156:157]
	v_lshl_add_u64 v[176:177], v[142:143], 0, v[176:177]
	v_fmamk_f32 v160, v160, 0x3a800000, v172
	s_waitcnt lgkmcnt(0)
	v_rsq_f32_e32 v164, v160
	s_nop 0
	v_pk_mul_f32 v[162:163], v[46:47], v[164:165] op_sel_hi:[1,0]
	v_pk_mul_f32 v[160:161], v[44:45], v[164:165] op_sel_hi:[1,0]
	v_pk_mul_f32 v[178:179], v[42:43], v[164:165] op_sel_hi:[1,0]
	v_pk_mul_f32 v[180:181], v[40:41], v[164:165] op_sel_hi:[1,0]
	v_mul_f32_e32 v165, v161, v161
	v_mul_f32_e32 v175, v163, v163
	v_fmac_f32_e32 v165, v160, v160
	v_fmac_f32_e32 v175, v162, v162
	v_add_f32_e32 v165, v165, v175
	v_mul_f32_e32 v175, v181, v181
	v_mul_f32_e32 v182, v179, v179
	v_cvt_pk_bf16_f32 v160, v160, v161
	v_cvt_pk_bf16_f32 v161, v162, v163
	v_cvt_pk_bf16_f32 v162, v180, v181
	v_cvt_pk_bf16_f32 v163, v178, v179
	v_fmac_f32_e32 v175, v180, v180
	v_fmac_f32_e32 v182, v178, v178
	global_store_dwordx4 v[176:177], v[160:163], off
	v_add_f32_e32 v175, v175, v182
	v_add_f32_e32 v175, v165, v175
	v_pk_mul_f32 v[162:163], v[38:39], v[164:165] op_sel_hi:[1,0]
	v_pk_mul_f32 v[160:161], v[36:37], v[164:165] op_sel_hi:[1,0]
	v_mul_f32_e32 v181, v163, v163
	v_mul_f32_e32 v180, v161, v161
	v_pk_mul_f32 v[178:179], v[34:35], v[164:165] op_sel_hi:[1,0]
	v_pk_mul_f32 v[164:165], v[32:33], v[164:165] op_sel_hi:[1,0]
	v_fmac_f32_e32 v180, v160, v160
	v_fmac_f32_e32 v181, v162, v162
	v_add_f32_e32 v180, v180, v181
	v_mul_f32_e32 v181, v165, v165
	v_mul_f32_e32 v182, v179, v179
	v_fmac_f32_e32 v181, v164, v164
	v_fmac_f32_e32 v182, v178, v178
	v_add_f32_e32 v181, v181, v182
	v_add_f32_e32 v180, v180, v181
	v_add_f32_e32 v175, v175, v180
	v_cvt_pk_bf16_f32 v160, v160, v161
	v_cvt_pk_bf16_f32 v161, v162, v163
	v_cvt_pk_bf16_f32 v162, v164, v165
	v_cvt_pk_bf16_f32 v163, v178, v179
	global_store_dwordx4 v[176:177], v[160:163], off offset:256
	ds_bpermute_b32 v160, v158, v175
	s_waitcnt lgkmcnt(0)
	v_add_f32_e32 v160, v175, v160
	ds_bpermute_b32 v161, v159, v160
	s_and_saveexec_b64 s[0:1], s[38:39]
	s_cbranch_execz .LBB0_396
	v_lshl_add_u64 v[156:157], v[156:157], 2, s[46:47]
	s_waitcnt lgkmcnt(0)
	v_add_f32_e32 v160, v160, v161
	global_atomic_add_f32 v[156:157], v160, off
.LBB0_396:
	s_or_b64 exec, exec, s[0:1]
	s_nop 1
	v_mov_b32_e32 v160, v205
	v_add_u32_e32 v156, 0xa0, v152
	v_ashrrev_i32_e32 v157, 31, v156
	v_lshlrev_b64 v[176:177], 9, v[156:157]
	v_lshl_add_u64 v[176:177], v[142:143], 0, v[176:177]
	v_fmamk_f32 v160, v160, 0x3a800000, v172
	s_waitcnt lgkmcnt(0)
	v_rsq_f32_e32 v164, v160
	s_nop 0
	v_pk_mul_f32 v[162:163], v[30:31], v[164:165] op_sel_hi:[1,0]
	v_pk_mul_f32 v[160:161], v[28:29], v[164:165] op_sel_hi:[1,0]
	v_pk_mul_f32 v[178:179], v[26:27], v[164:165] op_sel_hi:[1,0]
	v_pk_mul_f32 v[180:181], v[24:25], v[164:165] op_sel_hi:[1,0]
	v_mul_f32_e32 v165, v161, v161
	v_mul_f32_e32 v175, v163, v163
	v_fmac_f32_e32 v165, v160, v160
	v_fmac_f32_e32 v175, v162, v162
	v_add_f32_e32 v165, v165, v175
	v_mul_f32_e32 v175, v181, v181
	v_mul_f32_e32 v182, v179, v179
	v_cvt_pk_bf16_f32 v160, v160, v161
	v_cvt_pk_bf16_f32 v161, v162, v163
	v_cvt_pk_bf16_f32 v162, v180, v181
	v_cvt_pk_bf16_f32 v163, v178, v179
	v_fmac_f32_e32 v175, v180, v180
	v_fmac_f32_e32 v182, v178, v178
	global_store_dwordx4 v[176:177], v[160:163], off
	v_add_f32_e32 v175, v175, v182
	v_add_f32_e32 v175, v165, v175
	v_pk_mul_f32 v[162:163], v[22:23], v[164:165] op_sel_hi:[1,0]
	v_pk_mul_f32 v[160:161], v[20:21], v[164:165] op_sel_hi:[1,0]
	v_mul_f32_e32 v181, v163, v163
	v_mul_f32_e32 v180, v161, v161
	v_pk_mul_f32 v[178:179], v[18:19], v[164:165] op_sel_hi:[1,0]
	v_pk_mul_f32 v[164:165], v[16:17], v[164:165] op_sel_hi:[1,0]
	v_fmac_f32_e32 v180, v160, v160
	v_fmac_f32_e32 v181, v162, v162
	v_add_f32_e32 v180, v180, v181
	v_mul_f32_e32 v181, v165, v165
	v_mul_f32_e32 v182, v179, v179
	v_fmac_f32_e32 v181, v164, v164
	v_fmac_f32_e32 v182, v178, v178
	v_add_f32_e32 v181, v181, v182
	v_add_f32_e32 v180, v180, v181
	v_add_f32_e32 v175, v175, v180
	v_cvt_pk_bf16_f32 v160, v160, v161
	v_cvt_pk_bf16_f32 v161, v162, v163
	v_cvt_pk_bf16_f32 v162, v164, v165
	v_cvt_pk_bf16_f32 v163, v178, v179
	global_store_dwordx4 v[176:177], v[160:163], off offset:256
	ds_bpermute_b32 v160, v158, v175
	s_waitcnt lgkmcnt(0)
	v_add_f32_e32 v160, v175, v160
	ds_bpermute_b32 v161, v159, v160
	s_and_saveexec_b64 s[0:1], s[38:39]
	s_cbranch_execz .LBB0_398
	v_lshl_add_u64 v[156:157], v[156:157], 2, s[46:47]
	s_waitcnt lgkmcnt(0)
	v_add_f32_e32 v160, v160, v161
	global_atomic_add_f32 v[156:157], v160, off
.LBB0_398:
	s_or_b64 exec, exec, s[0:1]
	s_nop 1
	v_mov_b32_e32 v154, v206
	v_add_u32_e32 v156, 0xb0, v152
	v_ashrrev_i32_e32 v157, 31, v156
	v_lshlrev_b64 v[164:165], 9, v[156:157]
	v_lshl_add_u64 v[164:165], v[142:143], 0, v[164:165]
	v_fmamk_f32 v154, v154, 0x3a800000, v172
	s_waitcnt lgkmcnt(0)
	v_rsq_f32_e32 v154, v154
	s_nop 0
	v_pk_mul_f32 v[162:163], v[14:15], v[154:155] op_sel_hi:[1,0]
	v_pk_mul_f32 v[160:161], v[12:13], v[154:155] op_sel_hi:[1,0]
	v_pk_mul_f32 v[176:177], v[10:11], v[154:155] op_sel_hi:[1,0]
	v_pk_mul_f32 v[178:179], v[8:9], v[154:155] op_sel_hi:[1,0]
	v_mul_f32_e32 v155, v161, v161
	v_mul_f32_e32 v175, v163, v163
	v_fmac_f32_e32 v155, v160, v160
	v_fmac_f32_e32 v175, v162, v162
	v_add_f32_e32 v155, v155, v175
	v_mul_f32_e32 v175, v179, v179
	v_mul_f32_e32 v180, v177, v177
	v_cvt_pk_bf16_f32 v160, v160, v161
	v_cvt_pk_bf16_f32 v161, v162, v163
	v_cvt_pk_bf16_f32 v162, v178, v179
	v_cvt_pk_bf16_f32 v163, v176, v177
	v_fmac_f32_e32 v175, v178, v178
	v_fmac_f32_e32 v180, v176, v176
	global_store_dwordx4 v[164:165], v[160:163], off
	v_add_f32_e32 v175, v175, v180
	v_add_f32_e32 v175, v155, v175
	v_pk_mul_f32 v[162:163], v[6:7], v[154:155] op_sel_hi:[1,0]
	v_pk_mul_f32 v[160:161], v[4:5], v[154:155] op_sel_hi:[1,0]
	v_mul_f32_e32 v179, v163, v163
	v_mul_f32_e32 v178, v161, v161
	v_pk_mul_f32 v[176:177], v[2:3], v[154:155] op_sel_hi:[1,0]
	v_pk_mul_f32 v[154:155], v[0:1], v[154:155] op_sel_hi:[1,0]
	v_fmac_f32_e32 v178, v160, v160
	v_fmac_f32_e32 v179, v162, v162
	v_add_f32_e32 v178, v178, v179
	v_mul_f32_e32 v179, v155, v155
	v_mul_f32_e32 v180, v177, v177
	v_fmac_f32_e32 v179, v154, v154
	v_fmac_f32_e32 v180, v176, v176
	v_add_f32_e32 v179, v179, v180
	v_add_f32_e32 v178, v178, v179
	v_add_f32_e32 v175, v175, v178
	v_cvt_pk_bf16_f32 v160, v160, v161
	v_cvt_pk_bf16_f32 v161, v162, v163
	v_cvt_pk_bf16_f32 v162, v154, v155
	ds_bpermute_b32 v154, v158, v175
	v_cvt_pk_bf16_f32 v163, v176, v177
	global_store_dwordx4 v[164:165], v[160:163], off offset:256
	s_waitcnt lgkmcnt(0)
	v_add_f32_e32 v154, v175, v154
	ds_bpermute_b32 v155, v159, v154
	s_and_saveexec_b64 s[0:1], s[38:39]
	s_cbranch_execz .LBB0_400
	v_lshl_add_u64 v[156:157], v[156:157], 2, s[46:47]
	s_waitcnt lgkmcnt(0)
	v_add_f32_e32 v154, v154, v155
	global_atomic_add_f32 v[156:157], v154, off

; __device__ __forceinline__ unsigned cvt_pk(float lo, float hi) { unsigned r; asm volatile("v_cvt_pk_bf16_f32 %0, %1, %2" : "=v"(r) : "v"(lo), "v"(hi)); return r; }
; __device__ __forceinline__ float gelu_f(float x) {
;     const float t = x * (1.f + 0.044715f * x * x);
;     return x * __builtin_amdgcn_rcpf(1.f + __builtin_amdgcn_exp2f(-2.3022081986f * t));
; }
; __device__ __forceinline__ float sq4(f32x4 a) { return (a.x * a.x + a.y * a.y) + (a.z * a.z + a.w * a.w); }
; __device__ __forceinline__ u32x4 pack8(f32x4 a, f32x4 b) { u32x4 o; o.x = cvt_pk(a.x, a.y); o.y = cvt_pk(a.z, a.w); o.z = cvt_pk(b.x, b.y); o.w = cvt_pk(b.z, b.w); return o; }
; __device__ __forceinline__ float rstd_of(const float* SS, int row, float invw) { return 1.0f / sqrtf(SS[row] * invw + EPS); }
;     __device__ __forceinline__ void operator()(const f32x4 (&acc)[2][2][4][2], const pg8::Unit& u, int wr, int wc, int fr, int fq) const {
;     ...
;         if (u.pn < 4) {
;             bf16_t* dst = (u.pn < 2 ? GU : GV) + (u.pn & 1) * 256 + colw;
; #pragma unroll
;             for (int ai = 0; ai < 2; ++ai)
; #pragma unroll
;                 for (int m = 0; m < 4; ++m) {
;                     const int row = row0 + ai * 128 + m * 16; const float r = rstd_of(SS1, row, 1.f / 1024.f);
; #pragma unroll
;                     for (int bj = 0; bj < 2; ++bj) {
;                         const f32x4 a = acc[ai][bj][m][0] * r, b = acc[ai][bj][m][1] * r;
;                         f32x4 ga, gb; ga.x = gelu_f(a.x); ga.y = gelu_f(a.y); ga.z = gelu_f(a.z); ga.w = gelu_f(a.w);
;                         gb.x = gelu_f(b.x); gb.y = gelu_f(b.y); gb.z = gelu_f(b.z); gb.w = gelu_f(b.w);
;                         *(u32x4*)(dst + (size_t)row * 512 + bj * 128) = pack8(ga, gb);
;                     }
;                 }
.LBB0_404:
	v_lshl_add_u64 v[156:157], v[152:153], 2, s[48:49]
	global_load_dword v200, v[156:157], off
	global_load_dword v201, v[156:157], off offset:64
	global_load_dword v202, v[156:157], off offset:128
	global_load_dword v203, v[156:157], off offset:192
	global_load_dword v204, v[156:157], off offset:512
	global_load_dword v205, v[156:157], off offset:576
	global_load_dword v206, v[156:157], off offset:640
	global_load_dword v207, v[156:157], off offset:704
	s_cmp_lt_i32 s58, 2
	s_cselect_b32 s1, s65, s23
	s_cselect_b32 s0, s64, s22
	s_lshl_b32 s4, s58, 9
	s_and_b32 s4, s4, 0x200
	s_add_u32 s0, s0, s4
	s_addc_u32 s1, s1, 0
	v_lshl_add_u64 v[158:159], s[0:1], 0, v[136:137]
	v_mov_b32_e32 v208, 0xbdd2d3e7
	v_mov_b32_e32 v209, 0xbdd2d3e7
	v_mov_b32_e32 v210, 0xc0135761
	v_mov_b32_e32 v211, 0xc0135761
	v_mov_b32_e32 v212, 1.0
	v_mov_b32_e32 v213, 1.0
	v_lshlrev_b64 v[154:155], 10, v[152:153]
	v_lshl_add_u64 v[154:155], v[158:159], 0, v[154:155]
	v_add_co_u32_e32 v214, vcc, 0x4000, v154
	v_addc_co_u32_e32 v215, vcc, 0, v155, vcc
	v_add_co_u32_e32 v216, vcc, 0x8000, v154
	v_addc_co_u32_e32 v217, vcc, 0, v155, vcc
	v_add_co_u32_e32 v218, vcc, 0xc000, v154
	v_addc_co_u32_e32 v219, vcc, 0, v155, vcc
	v_add_co_u32_e32 v220, vcc, 0x20000, v154
	v_addc_co_u32_e32 v221, vcc, 0, v155, vcc
	v_add_co_u32_e32 v222, vcc, 0x24000, v154
	v_addc_co_u32_e32 v223, vcc, 0, v155, vcc
	v_add_co_u32_e32 v224, vcc, 0x28000, v154
	v_addc_co_u32_e32 v225, vcc, 0, v155, vcc
	v_add_co_u32_e32 v226, vcc, 0x2c000, v154
	v_addc_co_u32_e32 v227, vcc, 0, v155, vcc
	s_waitcnt vmcnt(0) lgkmcnt(0)
	v_fmamk_f32 v200, v200, 0x3a800000, v172
	v_fmamk_f32 v201, v201, 0x3a800000, v172
	v_fmamk_f32 v202, v202, 0x3a800000, v172
	v_fmamk_f32 v203, v203, 0x3a800000, v172
	v_fmamk_f32 v204, v204, 0x3a800000, v172
	v_fmamk_f32 v205, v205, 0x3a800000, v172
	v_fmamk_f32 v206, v206, 0x3a800000, v172
	v_fmamk_f32 v207, v207, 0x3a800000, v172
	v_rsq_f32_e32 v200, v200
	v_rsq_f32_e32 v201, v201
	v_rsq_f32_e32 v202, v202
	v_rsq_f32_e32 v203, v203
	v_rsq_f32_e32 v204, v204
	v_rsq_f32_e32 v205, v205
	v_rsq_f32_e32 v206, v206
	v_rsq_f32_e32 v207, v207
	v_pk_mul_f32 v[124:125], v[124:125], v[200:201] op_sel_hi:[1,0]
	v_pk_mul_f32 v[126:127], v[126:127], v[200:201] op_sel_hi:[1,0]
	v_pk_mul_f32 v[120:121], v[120:121], v[200:201] op_sel_hi:[1,0]
	v_pk_mul_f32 v[122:123], v[122:123], v[200:201] op_sel_hi:[1,0]
	v_pk_mul_f32 v[116:117], v[116:117], v[200:201] op_sel_hi:[1,0]
	v_pk_mul_f32 v[118:119], v[118:119], v[200:201] op_sel_hi:[1,0]
	v_pk_mul_f32 v[112:113], v[112:113], v[200:201] op_sel_hi:[1,0]
	v_pk_mul_f32 v[114:115], v[114:115], v[200:201] op_sel_hi:[1,0]
	v_pk_mul_f32 v[176:177], v[124:125], v[124:125]
	v_pk_mul_f32 v[178:179], v[126:127], v[126:127]
	v_pk_mul_f32 v[180:181], v[120:121], v[120:121]
	v_pk_mul_f32 v[182:183], v[122:123], v[122:123]
	v_pk_mul_f32 v[184:185], v[116:117], v[116:117]
	v_pk_mul_f32 v[186:187], v[118:119], v[118:119]
	v_pk_mul_f32 v[188:189], v[112:113], v[112:113]
	v_pk_mul_f32 v[190:191], v[114:115], v[114:115]
	v_pk_fma_f32 v[176:177], v[176:177], v[208:209], v[210:211]
	v_pk_fma_f32 v[178:179], v[178:179], v[208:209], v[210:211]
	v_pk_fma_f32 v[180:181], v[180:181], v[208:209], v[210:211]
	v_pk_fma_f32 v[182:183], v[182:183], v[208:209], v[210:211]
	v_pk_fma_f32 v[184:185], v[184:185], v[208:209], v[210:211]
	v_pk_fma_f32 v[186:187], v[186:187], v[208:209], v[210:211]
	v_pk_fma_f32 v[188:189], v[188:189], v[208:209], v[210:211]
	v_pk_fma_f32 v[190:191], v[190:191], v[208:209], v[210:211]
	v_pk_mul_f32 v[176:177], v[124:125], v[176:177]
	v_pk_mul_f32 v[178:179], v[126:127], v[178:179]
	v_pk_mul_f32 v[180:181], v[120:121], v[180:181]
	v_pk_mul_f32 v[182:183], v[122:123], v[182:183]
	v_pk_mul_f32 v[184:185], v[116:117], v[184:185]
	v_pk_mul_f32 v[186:187], v[118:119], v[186:187]
	v_pk_mul_f32 v[188:189], v[112:113], v[188:189]
	v_pk_mul_f32 v[190:191], v[114:115], v[190:191]
	v_exp_f32_e32 v176, v176
	v_exp_f32_e32 v177, v177
	v_exp_f32_e32 v178, v178
	v_exp_f32_e32 v179, v179
	v_exp_f32_e32 v180, v180
	v_exp_f32_e32 v181, v181
	v_exp_f32_e32 v182, v182
	v_exp_f32_e32 v183, v183
	v_exp_f32_e32 v184, v184
	v_exp_f32_e32 v185, v185
	v_exp_f32_e32 v186, v186
	v_exp_f32_e32 v187, v187
	v_exp_f32_e32 v188, v188
	v_exp_f32_e32 v189, v189
	v_exp_f32_e32 v190, v190
	v_exp_f32_e32 v191, v191
	v_pk_add_f32 v[176:177], v[176:177], v[212:213]
	v_pk_add_f32 v[178:179], v[178:179], v[212:213]
	v_pk_add_f32 v[180:181], v[180:181], v[212:213]
	v_pk_add_f32 v[182:183], v[182:183], v[212:213]
	v_pk_add_f32 v[184:185], v[184:185], v[212:213]
	v_pk_add_f32 v[186:187], v[186:187], v[212:213]
	v_pk_add_f32 v[188:189], v[188:189], v[212:213]
	v_pk_add_f32 v[190:191], v[190:191], v[212:213]
	v_rcp_f32_e32 v176, v176
	v_rcp_f32_e32 v177, v177
	v_rcp_f32_e32 v178, v178
	v_rcp_f32_e32 v179, v179
	v_rcp_f32_e32 v180, v180
	v_rcp_f32_e32 v181, v181
	v_rcp_f32_e32 v182, v182
	v_rcp_f32_e32 v183, v183
	v_rcp_f32_e32 v184, v184
	v_rcp_f32_e32 v185, v185
	v_rcp_f32_e32 v186, v186
	v_rcp_f32_e32 v187, v187
	v_rcp_f32_e32 v188, v188
	v_rcp_f32_e32 v189, v189
	v_rcp_f32_e32 v190, v190
	v_rcp_f32_e32 v191, v191
	v_pk_mul_f32 v[124:125], v[124:125], v[176:177]
	v_pk_mul_f32 v[126:127], v[126:127], v[178:179]
	v_pk_mul_f32 v[120:121], v[120:121], v[180:181]
	v_pk_mul_f32 v[122:123], v[122:123], v[182:183]
	v_pk_mul_f32 v[116:117], v[116:117], v[184:185]
	v_pk_mul_f32 v[118:119], v[118:119], v[186:187]
	v_pk_mul_f32 v[112:113], v[112:113], v[188:189]
	v_pk_mul_f32 v[114:115], v[114:115], v[190:191]
	v_cvt_pk_bf16_f32 v124, v124, v125
	v_cvt_pk_bf16_f32 v125, v126, v127
	v_cvt_pk_bf16_f32 v126, v120, v121
; __device__ __forceinline__ u32x4 pack8(f32x4 a, f32x4 b) { u32x4 o; o.x = cvt_pk(a.x, a.y); o.y = cvt_pk(a.z, a.w); o.z = cvt_pk(b.x, b.y); o.w = cvt_pk(b.z, b.w); return o; }
; __device__ __forceinline__ float rstd_of(const float* SS, int row, float invw) { return 1.0f / sqrtf(SS[row] * invw + EPS); }
; __device__ __forceinline__ float gelu_f(float x) {
;     const float t = x * (1.f + 0.044715f * x * x);
;     return x * __builtin_amdgcn_rcpf(1.f + __builtin_amdgcn_exp2f(-2.3022081986f * t));
; }
;     __device__ __forceinline__ void operator()(const f32x4 (&acc)[2][2][4][2], const pg8::Unit& u, int wr, int wc, int fr, int fq) const {
;     ...
;             for (int ai = 0; ai < 2; ++ai)
; #pragma unroll
;                 for (int m = 0; m < 4; ++m) {
;                     const int row = row0 + ai * 128 + m * 16; const float r = rstd_of(SS1, row, 1.f / 1024.f);
; #pragma unroll
;                     for (int bj = 0; bj < 2; ++bj) {
;                         const f32x4 a = acc[ai][bj][m][0] * r, b = acc[ai][bj][m][1] * r;
;                         f32x4 ga, gb; ga.x = gelu_f(a.x); ga.y = gelu_f(a.y); ga.z = gelu_f(a.z); ga.w = gelu_f(a.w);
;                         gb.x = gelu_f(b.x); gb.y = gelu_f(b.y); gb.z = gelu_f(b.z); gb.w = gelu_f(b.w);
;                         *(u32x4*)(dst + (size_t)row * 512 + bj * 128) = pack8(ga, gb);
;                     }
;                 }
	v_cvt_pk_bf16_f32 v127, v122, v123
	global_store_dwordx4 v[154:155], v[124:127], off
	v_cvt_pk_bf16_f32 v116, v116, v117
	v_cvt_pk_bf16_f32 v117, v118, v119
	v_cvt_pk_bf16_f32 v118, v112, v113
	v_cvt_pk_bf16_f32 v119, v114, v115
	global_store_dwordx4 v[154:155], v[116:119], off offset:256
	v_pk_mul_f32 v[108:109], v[108:109], v[200:201] op_sel:[0,1] op_sel_hi:[1,1]
	v_pk_mul_f32 v[110:111], v[110:111], v[200:201] op_sel:[0,1] op_sel_hi:[1,1]
	v_pk_mul_f32 v[104:105], v[104:105], v[200:201] op_sel:[0,1] op_sel_hi:[1,1]
	v_pk_mul_f32 v[106:107], v[106:107], v[200:201] op_sel:[0,1] op_sel_hi:[1,1]
	v_pk_mul_f32 v[100:101], v[100:101], v[200:201] op_sel:[0,1] op_sel_hi:[1,1]
	v_pk_mul_f32 v[102:103], v[102:103], v[200:201] op_sel:[0,1] op_sel_hi:[1,1]
	v_pk_mul_f32 v[96:97], v[96:97], v[200:201] op_sel:[0,1] op_sel_hi:[1,1]
	v_pk_mul_f32 v[98:99], v[98:99], v[200:201] op_sel:[0,1] op_sel_hi:[1,1]
	v_pk_mul_f32 v[176:177], v[108:109], v[108:109]
	v_pk_mul_f32 v[178:179], v[110:111], v[110:111]
	v_pk_mul_f32 v[180:181], v[104:105], v[104:105]
	v_pk_mul_f32 v[182:183], v[106:107], v[106:107]
	v_pk_mul_f32 v[184:185], v[100:101], v[100:101]
	v_pk_mul_f32 v[186:187], v[102:103], v[102:103]
	v_pk_mul_f32 v[188:189], v[96:97], v[96:97]
	v_pk_mul_f32 v[190:191], v[98:99], v[98:99]
	v_pk_fma_f32 v[176:177], v[176:177], v[208:209], v[210:211]
	v_pk_fma_f32 v[178:179], v[178:179], v[208:209], v[210:211]
	v_pk_fma_f32 v[180:181], v[180:181], v[208:209], v[210:211]
	v_pk_fma_f32 v[182:183], v[182:183], v[208:209], v[210:211]
	v_pk_fma_f32 v[184:185], v[184:185], v[208:209], v[210:211]
	v_pk_fma_f32 v[186:187], v[186:187], v[208:209], v[210:211]
	v_pk_fma_f32 v[188:189], v[188:189], v[208:209], v[210:211]
	v_pk_fma_f32 v[190:191], v[190:191], v[208:209], v[210:211]
	v_pk_mul_f32 v[176:177], v[108:109], v[176:177]
	v_pk_mul_f32 v[178:179], v[110:111], v[178:179]
	v_pk_mul_f32 v[180:181], v[104:105], v[180:181]
	v_pk_mul_f32 v[182:183], v[106:107], v[182:183]
	v_pk_mul_f32 v[184:185], v[100:101], v[184:185]
	v_pk_mul_f32 v[186:187], v[102:103], v[186:187]
	v_pk_mul_f32 v[188:189], v[96:97], v[188:189]
	v_pk_mul_f32 v[190:191], v[98:99], v[190:191]
	v_exp_f32_e32 v176, v176
	v_exp_f32_e32 v177, v177
	v_exp_f32_e32 v178, v178
	v_exp_f32_e32 v179, v179
	v_exp_f32_e32 v180, v180
	v_exp_f32_e32 v181, v181
	v_exp_f32_e32 v182, v182
	v_exp_f32_e32 v183, v183
	v_exp_f32_e32 v184, v184
	v_exp_f32_e32 v185, v185
	v_exp_f32_e32 v186, v186
	v_exp_f32_e32 v187, v187
	v_exp_f32_e32 v188, v188
	v_exp_f32_e32 v189, v189
	v_exp_f32_e32 v190, v190
	v_exp_f32_e32 v191, v191
	v_pk_add_f32 v[176:177], v[176:177], v[212:213]
	v_pk_add_f32 v[178:179], v[178:179], v[212:213]
	v_pk_add_f32 v[180:181], v[180:181], v[212:213]
	v_pk_add_f32 v[182:183], v[182:183], v[212:213]
	v_pk_add_f32 v[184:185], v[184:185], v[212:213]
	v_pk_add_f32 v[186:187], v[186:187], v[212:213]
	v_pk_add_f32 v[188:189], v[188:189], v[212:213]
	v_pk_add_f32 v[190:191], v[190:191], v[212:213]
	v_rcp_f32_e32 v176, v176
	v_rcp_f32_e32 v177, v177
	v_rcp_f32_e32 v178, v178
	v_rcp_f32_e32 v179, v179
	v_rcp_f32_e32 v180, v180
	v_rcp_f32_e32 v181, v181
	v_rcp_f32_e32 v182, v182
	v_rcp_f32_e32 v183, v183
	v_rcp_f32_e32 v184, v184
	v_rcp_f32_e32 v185, v185
	v_rcp_f32_e32 v186, v186
	v_rcp_f32_e32 v187, v187
	v_rcp_f32_e32 v188, v188
	v_rcp_f32_e32 v189, v189
	v_rcp_f32_e32 v190, v190
	v_rcp_f32_e32 v191, v191
	v_pk_mul_f32 v[108:109], v[108:109], v[176:177]
	v_pk_mul_f32 v[110:111], v[110:111], v[178:179]
	v_pk_mul_f32 v[104:105], v[104:105], v[180:181]
	v_pk_mul_f32 v[106:107], v[106:107], v[182:183]
	v_pk_mul_f32 v[100:101], v[100:101], v[184:185]
	v_pk_mul_f32 v[102:103], v[102:103], v[186:187]
	v_pk_mul_f32 v[96:97], v[96:97], v[188:189]
	v_pk_mul_f32 v[98:99], v[98:99], v[190:191]
	v_cvt_pk_bf16_f32 v108, v108, v109
	v_cvt_pk_bf16_f32 v109, v110, v111
	v_cvt_pk_bf16_f32 v110, v104, v105
	v_cvt_pk_bf16_f32 v111, v106, v107
	global_store_dwordx4 v[214:215], v[108:111], off
	v_cvt_pk_bf16_f32 v100, v100, v101
	v_cvt_pk_bf16_f32 v101, v102, v103
	v_cvt_pk_bf16_f32 v102, v96, v97
	v_cvt_pk_bf16_f32 v103, v98, v99
	global_store_dwordx4 v[214:215], v[100:103], off offset:256
	v_pk_mul_f32 v[92:93], v[92:93], v[202:203] op_sel_hi:[1,0]
	v_pk_mul_f32 v[94:95], v[94:95], v[202:203] op_sel_hi:[1,0]
	v_pk_mul_f32 v[88:89], v[88:89], v[202:203] op_sel_hi:[1,0]
	v_pk_mul_f32 v[90:91], v[90:91], v[202:203] op_sel_hi:[1,0]
	v_pk_mul_f32 v[84:85], v[84:85], v[202:203] op_sel_hi:[1,0]
	v_pk_mul_f32 v[86:87], v[86:87], v[202:203] op_sel_hi:[1,0]
	v_pk_mul_f32 v[80:81], v[80:81], v[202:203] op_sel_hi:[1,0]
	v_pk_mul_f32 v[82:83], v[82:83], v[202:203] op_sel_hi:[1,0]
	v_pk_mul_f32 v[176:177], v[92:93], v[92:93]
	v_pk_mul_f32 v[178:179], v[94:95], v[94:95]
	v_pk_mul_f32 v[180:181], v[88:89], v[88:89]
	v_pk_mul_f32 v[182:183], v[90:91], v[90:91]
	v_pk_mul_f32 v[184:185], v[84:85], v[84:85]
	v_pk_mul_f32 v[186:187], v[86:87], v[86:87]
	v_pk_mul_f32 v[188:189], v[80:81], v[80:81]
	v_pk_mul_f32 v[190:191], v[82:83], v[82:83]
	v_pk_fma_f32 v[176:177], v[176:177], v[208:209], v[210:211]
	v_pk_fma_f32 v[178:179], v[178:179], v[208:209], v[210:211]
	v_pk_fma_f32 v[180:181], v[180:181], v[208:209], v[210:211]
	v_pk_fma_f32 v[182:183], v[182:183], v[208:209], v[210:211]
	v_pk_fma_f32 v[184:185], v[184:185], v[208:209], v[210:211]
	v_pk_fma_f32 v[186:187], v[186:187], v[208:209], v[210:211]
	v_pk_fma_f32 v[188:189], v[188:189], v[208:209], v[210:211]
	v_pk_fma_f32 v[190:191], v[190:191], v[208:209], v[210:211]
	v_pk_mul_f32 v[176:177], v[92:93], v[176:177]
	v_pk_mul_f32 v[178:179], v[94:95], v[178:179]
	v_pk_mul_f32 v[180:181], v[88:89], v[180:181]
; __device__ __forceinline__ u32x4 pack8(f32x4 a, f32x4 b) { u32x4 o; o.x = cvt_pk(a.x, a.y); o.y = cvt_pk(a.z, a.w); o.z = cvt_pk(b.x, b.y); o.w = cvt_pk(b.z, b.w); return o; }
; __device__ __forceinline__ float rstd_of(const float* SS, int row, float invw) { return 1.0f / sqrtf(SS[row] * invw + EPS); }
; __device__ __forceinline__ float gelu_f(float x) {
;     const float t = x * (1.f + 0.044715f * x * x);
;     return x * __builtin_amdgcn_rcpf(1.f + __builtin_amdgcn_exp2f(-2.3022081986f * t));
; }
;     __device__ __forceinline__ void operator()(const f32x4 (&acc)[2][2][4][2], const pg8::Unit& u, int wr, int wc, int fr, int fq) const {
;     ...
;             for (int ai = 0; ai < 2; ++ai)
; #pragma unroll
;                 for (int m = 0; m < 4; ++m) {
;                     const int row = row0 + ai * 128 + m * 16; const float r = rstd_of(SS1, row, 1.f / 1024.f);
; #pragma unroll
;                     for (int bj = 0; bj < 2; ++bj) {
;                         const f32x4 a = acc[ai][bj][m][0] * r, b = acc[ai][bj][m][1] * r;
;                         f32x4 ga, gb; ga.x = gelu_f(a.x); ga.y = gelu_f(a.y); ga.z = gelu_f(a.z); ga.w = gelu_f(a.w);
;                         gb.x = gelu_f(b.x); gb.y = gelu_f(b.y); gb.z = gelu_f(b.z); gb.w = gelu_f(b.w);
;                         *(u32x4*)(dst + (size_t)row * 512 + bj * 128) = pack8(ga, gb);
;                     }
;                 }
	v_pk_mul_f32 v[182:183], v[90:91], v[182:183]
	v_pk_mul_f32 v[184:185], v[84:85], v[184:185]
	v_pk_mul_f32 v[186:187], v[86:87], v[186:187]
	v_pk_mul_f32 v[188:189], v[80:81], v[188:189]
	v_pk_mul_f32 v[190:191], v[82:83], v[190:191]
	v_exp_f32_e32 v176, v176
	v_exp_f32_e32 v177, v177
	v_exp_f32_e32 v178, v178
	v_exp_f32_e32 v179, v179
	v_exp_f32_e32 v180, v180
	v_exp_f32_e32 v181, v181
	v_exp_f32_e32 v182, v182
	v_exp_f32_e32 v183, v183
	v_exp_f32_e32 v184, v184
	v_exp_f32_e32 v185, v185
	v_exp_f32_e32 v186, v186
	v_exp_f32_e32 v187, v187
	v_exp_f32_e32 v188, v188
	v_exp_f32_e32 v189, v189
	v_exp_f32_e32 v190, v190
	v_exp_f32_e32 v191, v191
	v_pk_add_f32 v[176:177], v[176:177], v[212:213]
	v_pk_add_f32 v[178:179], v[178:179], v[212:213]
	v_pk_add_f32 v[180:181], v[180:181], v[212:213]
	v_pk_add_f32 v[182:183], v[182:183], v[212:213]
	v_pk_add_f32 v[184:185], v[184:185], v[212:213]
	v_pk_add_f32 v[186:187], v[186:187], v[212:213]
	v_pk_add_f32 v[188:189], v[188:189], v[212:213]
	v_pk_add_f32 v[190:191], v[190:191], v[212:213]
	v_rcp_f32_e32 v176, v176
	v_rcp_f32_e32 v177, v177
	v_rcp_f32_e32 v178, v178
	v_rcp_f32_e32 v179, v179
	v_rcp_f32_e32 v180, v180
	v_rcp_f32_e32 v181, v181
	v_rcp_f32_e32 v182, v182
	v_rcp_f32_e32 v183, v183
	v_rcp_f32_e32 v184, v184
	v_rcp_f32_e32 v185, v185
	v_rcp_f32_e32 v186, v186
	v_rcp_f32_e32 v187, v187
	v_rcp_f32_e32 v188, v188
	v_rcp_f32_e32 v189, v189
	v_rcp_f32_e32 v190, v190
	v_rcp_f32_e32 v191, v191
	v_pk_mul_f32 v[92:93], v[92:93], v[176:177]
	v_pk_mul_f32 v[94:95], v[94:95], v[178:179]
	v_pk_mul_f32 v[88:89], v[88:89], v[180:181]
	v_pk_mul_f32 v[90:91], v[90:91], v[182:183]
	v_pk_mul_f32 v[84:85], v[84:85], v[184:185]
	v_pk_mul_f32 v[86:87], v[86:87], v[186:187]
	v_pk_mul_f32 v[80:81], v[80:81], v[188:189]
	v_pk_mul_f32 v[82:83], v[82:83], v[190:191]
	v_cvt_pk_bf16_f32 v92, v92, v93
	v_cvt_pk_bf16_f32 v93, v94, v95
	v_cvt_pk_bf16_f32 v94, v88, v89
	v_cvt_pk_bf16_f32 v95, v90, v91
	global_store_dwordx4 v[216:217], v[92:95], off
	v_cvt_pk_bf16_f32 v84, v84, v85
	v_cvt_pk_bf16_f32 v85, v86, v87
	v_cvt_pk_bf16_f32 v86, v80, v81
	v_cvt_pk_bf16_f32 v87, v82, v83
	global_store_dwordx4 v[216:217], v[84:87], off offset:256
	v_pk_mul_f32 v[76:77], v[76:77], v[202:203] op_sel:[0,1] op_sel_hi:[1,1]
	v_pk_mul_f32 v[78:79], v[78:79], v[202:203] op_sel:[0,1] op_sel_hi:[1,1]
	v_pk_mul_f32 v[72:73], v[72:73], v[202:203] op_sel:[0,1] op_sel_hi:[1,1]
	v_pk_mul_f32 v[74:75], v[74:75], v[202:203] op_sel:[0,1] op_sel_hi:[1,1]
	v_pk_mul_f32 v[68:69], v[68:69], v[202:203] op_sel:[0,1] op_sel_hi:[1,1]
	v_pk_mul_f32 v[70:71], v[70:71], v[202:203] op_sel:[0,1] op_sel_hi:[1,1]
	v_pk_mul_f32 v[64:65], v[64:65], v[202:203] op_sel:[0,1] op_sel_hi:[1,1]
	v_pk_mul_f32 v[66:67], v[66:67], v[202:203] op_sel:[0,1] op_sel_hi:[1,1]
	v_pk_mul_f32 v[176:177], v[76:77], v[76:77]
	v_pk_mul_f32 v[178:179], v[78:79], v[78:79]
	v_pk_mul_f32 v[180:181], v[72:73], v[72:73]
	v_pk_mul_f32 v[182:183], v[74:75], v[74:75]
	v_pk_mul_f32 v[184:185], v[68:69], v[68:69]
	v_pk_mul_f32 v[186:187], v[70:71], v[70:71]
	v_pk_mul_f32 v[188:189], v[64:65], v[64:65]
	v_pk_mul_f32 v[190:191], v[66:67], v[66:67]
	v_pk_fma_f32 v[176:177], v[176:177], v[208:209], v[210:211]
	v_pk_fma_f32 v[178:179], v[178:179], v[208:209], v[210:211]
	v_pk_fma_f32 v[180:181], v[180:181], v[208:209], v[210:211]
	v_pk_fma_f32 v[182:183], v[182:183], v[208:209], v[210:211]
	v_pk_fma_f32 v[184:185], v[184:185], v[208:209], v[210:211]
	v_pk_fma_f32 v[186:187], v[186:187], v[208:209], v[210:211]
	v_pk_fma_f32 v[188:189], v[188:189], v[208:209], v[210:211]
	v_pk_fma_f32 v[190:191], v[190:191], v[208:209], v[210:211]
	v_pk_mul_f32 v[176:177], v[76:77], v[176:177]
	v_pk_mul_f32 v[178:179], v[78:79], v[178:179]
	v_pk_mul_f32 v[180:181], v[72:73], v[180:181]
	v_pk_mul_f32 v[182:183], v[74:75], v[182:183]
	v_pk_mul_f32 v[184:185], v[68:69], v[184:185]
	v_pk_mul_f32 v[186:187], v[70:71], v[186:187]
	v_pk_mul_f32 v[188:189], v[64:65], v[188:189]
	v_pk_mul_f32 v[190:191], v[66:67], v[190:191]
	v_exp_f32_e32 v176, v176
	v_exp_f32_e32 v177, v177
	v_exp_f32_e32 v178, v178
	v_exp_f32_e32 v179, v179
	v_exp_f32_e32 v180, v180
	v_exp_f32_e32 v181, v181
	v_exp_f32_e32 v182, v182
	v_exp_f32_e32 v183, v183
	v_exp_f32_e32 v184, v184
	v_exp_f32_e32 v185, v185
	v_exp_f32_e32 v186, v186
	v_exp_f32_e32 v187, v187
	v_exp_f32_e32 v188, v188
	v_exp_f32_e32 v189, v189
	v_exp_f32_e32 v190, v190
	v_exp_f32_e32 v191, v191
	v_pk_add_f32 v[176:177], v[176:177], v[212:213]
	v_pk_add_f32 v[178:179], v[178:179], v[212:213]
	v_pk_add_f32 v[180:181], v[180:181], v[212:213]
	v_pk_add_f32 v[182:183], v[182:183], v[212:213]
	v_pk_add_f32 v[184:185], v[184:185], v[212:213]
	v_pk_add_f32 v[186:187], v[186:187], v[212:213]
	v_pk_add_f32 v[188:189], v[188:189], v[212:213]
	v_pk_add_f32 v[190:191], v[190:191], v[212:213]
	v_rcp_f32_e32 v176, v176
	v_rcp_f32_e32 v177, v177
	v_rcp_f32_e32 v178, v178
	v_rcp_f32_e32 v179, v179
	v_rcp_f32_e32 v180, v180
	v_rcp_f32_e32 v181, v181
	v_rcp_f32_e32 v182, v182
	v_rcp_f32_e32 v183, v183
	v_rcp_f32_e32 v184, v184
	v_rcp_f32_e32 v185, v185
	v_rcp_f32_e32 v186, v186
	v_rcp_f32_e32 v187, v187
	v_rcp_f32_e32 v188, v188
	v_rcp_f32_e32 v189, v189
	v_rcp_f32_e32 v190, v190
	v_rcp_f32_e32 v191, v191
	v_pk_mul_f32 v[76:77], v[76:77], v[176:177]
	v_pk_mul_f32 v[78:79], v[78:79], v[178:179]
	v_pk_mul_f32 v[72:73], v[72:73], v[180:181]
	v_pk_mul_f32 v[74:75], v[74:75], v[182:183]
	v_pk_mul_f32 v[68:69], v[68:69], v[184:185]
	v_pk_mul_f32 v[70:71], v[70:71], v[186:187]
	v_pk_mul_f32 v[64:65], v[64:65], v[188:189]
	v_pk_mul_f32 v[66:67], v[66:67], v[190:191]
	v_cvt_pk_bf16_f32 v76, v76, v77
	v_cvt_pk_bf16_f32 v77, v78, v79
; __device__ __forceinline__ u32x4 pack8(f32x4 a, f32x4 b) { u32x4 o; o.x = cvt_pk(a.x, a.y); o.y = cvt_pk(a.z, a.w); o.z = cvt_pk(b.x, b.y); o.w = cvt_pk(b.z, b.w); return o; }
; __device__ __forceinline__ float rstd_of(const float* SS, int row, float invw) { return 1.0f / sqrtf(SS[row] * invw + EPS); }
; __device__ __forceinline__ float gelu_f(float x) {
;     const float t = x * (1.f + 0.044715f * x * x);
;     return x * __builtin_amdgcn_rcpf(1.f + __builtin_amdgcn_exp2f(-2.3022081986f * t));
; }
;     __device__ __forceinline__ void operator()(const f32x4 (&acc)[2][2][4][2], const pg8::Unit& u, int wr, int wc, int fr, int fq) const {
;     ...
;             for (int ai = 0; ai < 2; ++ai)
; #pragma unroll
;                 for (int m = 0; m < 4; ++m) {
;                     const int row = row0 + ai * 128 + m * 16; const float r = rstd_of(SS1, row, 1.f / 1024.f);
; #pragma unroll
;                     for (int bj = 0; bj < 2; ++bj) {
;                         const f32x4 a = acc[ai][bj][m][0] * r, b = acc[ai][bj][m][1] * r;
;                         f32x4 ga, gb; ga.x = gelu_f(a.x); ga.y = gelu_f(a.y); ga.z = gelu_f(a.z); ga.w = gelu_f(a.w);
;                         gb.x = gelu_f(b.x); gb.y = gelu_f(b.y); gb.z = gelu_f(b.z); gb.w = gelu_f(b.w);
;                         *(u32x4*)(dst + (size_t)row * 512 + bj * 128) = pack8(ga, gb);
;                     }
;                 }
	v_cvt_pk_bf16_f32 v78, v72, v73
	v_cvt_pk_bf16_f32 v79, v74, v75
	global_store_dwordx4 v[218:219], v[76:79], off
	v_cvt_pk_bf16_f32 v68, v68, v69
	v_cvt_pk_bf16_f32 v69, v70, v71
	v_cvt_pk_bf16_f32 v70, v64, v65
	v_cvt_pk_bf16_f32 v71, v66, v67
	global_store_dwordx4 v[218:219], v[68:71], off offset:256
	v_pk_mul_f32 v[60:61], v[60:61], v[204:205] op_sel_hi:[1,0]
	v_pk_mul_f32 v[62:63], v[62:63], v[204:205] op_sel_hi:[1,0]
	v_pk_mul_f32 v[56:57], v[56:57], v[204:205] op_sel_hi:[1,0]
	v_pk_mul_f32 v[58:59], v[58:59], v[204:205] op_sel_hi:[1,0]
	v_pk_mul_f32 v[52:53], v[52:53], v[204:205] op_sel_hi:[1,0]
	v_pk_mul_f32 v[54:55], v[54:55], v[204:205] op_sel_hi:[1,0]
	v_pk_mul_f32 v[48:49], v[48:49], v[204:205] op_sel_hi:[1,0]
	v_pk_mul_f32 v[50:51], v[50:51], v[204:205] op_sel_hi:[1,0]
	v_pk_mul_f32 v[176:177], v[60:61], v[60:61]
	v_pk_mul_f32 v[178:179], v[62:63], v[62:63]
	v_pk_mul_f32 v[180:181], v[56:57], v[56:57]
	v_pk_mul_f32 v[182:183], v[58:59], v[58:59]
	v_pk_mul_f32 v[184:185], v[52:53], v[52:53]
	v_pk_mul_f32 v[186:187], v[54:55], v[54:55]
	v_pk_mul_f32 v[188:189], v[48:49], v[48:49]
	v_pk_mul_f32 v[190:191], v[50:51], v[50:51]
	v_pk_fma_f32 v[176:177], v[176:177], v[208:209], v[210:211]
	v_pk_fma_f32 v[178:179], v[178:179], v[208:209], v[210:211]
	v_pk_fma_f32 v[180:181], v[180:181], v[208:209], v[210:211]
	v_pk_fma_f32 v[182:183], v[182:183], v[208:209], v[210:211]
	v_pk_fma_f32 v[184:185], v[184:185], v[208:209], v[210:211]
	v_pk_fma_f32 v[186:187], v[186:187], v[208:209], v[210:211]
	v_pk_fma_f32 v[188:189], v[188:189], v[208:209], v[210:211]
	v_pk_fma_f32 v[190:191], v[190:191], v[208:209], v[210:211]
	v_pk_mul_f32 v[176:177], v[60:61], v[176:177]
	v_pk_mul_f32 v[178:179], v[62:63], v[178:179]
	v_pk_mul_f32 v[180:181], v[56:57], v[180:181]
	v_pk_mul_f32 v[182:183], v[58:59], v[182:183]
	v_pk_mul_f32 v[184:185], v[52:53], v[184:185]
	v_pk_mul_f32 v[186:187], v[54:55], v[186:187]
	v_pk_mul_f32 v[188:189], v[48:49], v[188:189]
	v_pk_mul_f32 v[190:191], v[50:51], v[190:191]
	v_exp_f32_e32 v176, v176
	v_exp_f32_e32 v177, v177
	v_exp_f32_e32 v178, v178
	v_exp_f32_e32 v179, v179
	v_exp_f32_e32 v180, v180
	v_exp_f32_e32 v181, v181
	v_exp_f32_e32 v182, v182
	v_exp_f32_e32 v183, v183
	v_exp_f32_e32 v184, v184
	v_exp_f32_e32 v185, v185
	v_exp_f32_e32 v186, v186
	v_exp_f32_e32 v187, v187
	v_exp_f32_e32 v188, v188
	v_exp_f32_e32 v189, v189
	v_exp_f32_e32 v190, v190
	v_exp_f32_e32 v191, v191
	v_pk_add_f32 v[176:177], v[176:177], v[212:213]
	v_pk_add_f32 v[178:179], v[178:179], v[212:213]
	v_pk_add_f32 v[180:181], v[180:181], v[212:213]
	v_pk_add_f32 v[182:183], v[182:183], v[212:213]
	v_pk_add_f32 v[184:185], v[184:185], v[212:213]
	v_pk_add_f32 v[186:187], v[186:187], v[212:213]
	v_pk_add_f32 v[188:189], v[188:189], v[212:213]
	v_pk_add_f32 v[190:191], v[190:191], v[212:213]
	v_rcp_f32_e32 v176, v176
	v_rcp_f32_e32 v177, v177
	v_rcp_f32_e32 v178, v178
	v_rcp_f32_e32 v179, v179
	v_rcp_f32_e32 v180, v180
	v_rcp_f32_e32 v181, v181
	v_rcp_f32_e32 v182, v182
	v_rcp_f32_e32 v183, v183
	v_rcp_f32_e32 v184, v184
	v_rcp_f32_e32 v185, v185
	v_rcp_f32_e32 v186, v186
	v_rcp_f32_e32 v187, v187
	v_rcp_f32_e32 v188, v188
	v_rcp_f32_e32 v189, v189
	v_rcp_f32_e32 v190, v190
	v_rcp_f32_e32 v191, v191
	v_pk_mul_f32 v[60:61], v[60:61], v[176:177]
	v_pk_mul_f32 v[62:63], v[62:63], v[178:179]
	v_pk_mul_f32 v[56:57], v[56:57], v[180:181]
	v_pk_mul_f32 v[58:59], v[58:59], v[182:183]
	v_pk_mul_f32 v[52:53], v[52:53], v[184:185]
	v_pk_mul_f32 v[54:55], v[54:55], v[186:187]
	v_pk_mul_f32 v[48:49], v[48:49], v[188:189]
	v_pk_mul_f32 v[50:51], v[50:51], v[190:191]
	v_cvt_pk_bf16_f32 v60, v60, v61
	v_cvt_pk_bf16_f32 v61, v62, v63
	v_cvt_pk_bf16_f32 v62, v56, v57
	v_cvt_pk_bf16_f32 v63, v58, v59
	global_store_dwordx4 v[220:221], v[60:63], off
	v_cvt_pk_bf16_f32 v52, v52, v53
	v_cvt_pk_bf16_f32 v53, v54, v55
	v_cvt_pk_bf16_f32 v54, v48, v49
	v_cvt_pk_bf16_f32 v55, v50, v51
	global_store_dwordx4 v[220:221], v[52:55], off offset:256
	v_pk_mul_f32 v[44:45], v[44:45], v[204:205] op_sel:[0,1] op_sel_hi:[1,1]
	v_pk_mul_f32 v[46:47], v[46:47], v[204:205] op_sel:[0,1] op_sel_hi:[1,1]
	v_pk_mul_f32 v[40:41], v[40:41], v[204:205] op_sel:[0,1] op_sel_hi:[1,1]
	v_pk_mul_f32 v[42:43], v[42:43], v[204:205] op_sel:[0,1] op_sel_hi:[1,1]
	v_pk_mul_f32 v[36:37], v[36:37], v[204:205] op_sel:[0,1] op_sel_hi:[1,1]
	v_pk_mul_f32 v[38:39], v[38:39], v[204:205] op_sel:[0,1] op_sel_hi:[1,1]
	v_pk_mul_f32 v[32:33], v[32:33], v[204:205] op_sel:[0,1] op_sel_hi:[1,1]
	v_pk_mul_f32 v[34:35], v[34:35], v[204:205] op_sel:[0,1] op_sel_hi:[1,1]
	v_pk_mul_f32 v[176:177], v[44:45], v[44:45]
	v_pk_mul_f32 v[178:179], v[46:47], v[46:47]
	v_pk_mul_f32 v[180:181], v[40:41], v[40:41]
	v_pk_mul_f32 v[182:183], v[42:43], v[42:43]
	v_pk_mul_f32 v[184:185], v[36:37], v[36:37]
	v_pk_mul_f32 v[186:187], v[38:39], v[38:39]
	v_pk_mul_f32 v[188:189], v[32:33], v[32:33]
	v_pk_mul_f32 v[190:191], v[34:35], v[34:35]
	v_pk_fma_f32 v[176:177], v[176:177], v[208:209], v[210:211]
	v_pk_fma_f32 v[178:179], v[178:179], v[208:209], v[210:211]
	v_pk_fma_f32 v[180:181], v[180:181], v[208:209], v[210:211]
	v_pk_fma_f32 v[182:183], v[182:183], v[208:209], v[210:211]
	v_pk_fma_f32 v[184:185], v[184:185], v[208:209], v[210:211]
	v_pk_fma_f32 v[186:187], v[186:187], v[208:209], v[210:211]
	v_pk_fma_f32 v[188:189], v[188:189], v[208:209], v[210:211]
	v_pk_fma_f32 v[190:191], v[190:191], v[208:209], v[210:211]
	v_pk_mul_f32 v[176:177], v[44:45], v[176:177]
	v_pk_mul_f32 v[178:179], v[46:47], v[178:179]
	v_pk_mul_f32 v[180:181], v[40:41], v[180:181]
	v_pk_mul_f32 v[182:183], v[42:43], v[182:183]
	v_pk_mul_f32 v[184:185], v[36:37], v[184:185]
; __device__ __forceinline__ u32x4 pack8(f32x4 a, f32x4 b) { u32x4 o; o.x = cvt_pk(a.x, a.y); o.y = cvt_pk(a.z, a.w); o.z = cvt_pk(b.x, b.y); o.w = cvt_pk(b.z, b.w); return o; }
; __device__ __forceinline__ float rstd_of(const float* SS, int row, float invw) { return 1.0f / sqrtf(SS[row] * invw + EPS); }
; __device__ __forceinline__ float gelu_f(float x) {
;     const float t = x * (1.f + 0.044715f * x * x);
;     return x * __builtin_amdgcn_rcpf(1.f + __builtin_amdgcn_exp2f(-2.3022081986f * t));
; }
;     __device__ __forceinline__ void operator()(const f32x4 (&acc)[2][2][4][2], const pg8::Unit& u, int wr, int wc, int fr, int fq) const {
;     ...
;             for (int ai = 0; ai < 2; ++ai)
; #pragma unroll
;                 for (int m = 0; m < 4; ++m) {
;                     const int row = row0 + ai * 128 + m * 16; const float r = rstd_of(SS1, row, 1.f / 1024.f);
; #pragma unroll
;                     for (int bj = 0; bj < 2; ++bj) {
;                         const f32x4 a = acc[ai][bj][m][0] * r, b = acc[ai][bj][m][1] * r;
;                         f32x4 ga, gb; ga.x = gelu_f(a.x); ga.y = gelu_f(a.y); ga.z = gelu_f(a.z); ga.w = gelu_f(a.w);
;                         gb.x = gelu_f(b.x); gb.y = gelu_f(b.y); gb.z = gelu_f(b.z); gb.w = gelu_f(b.w);
;                         *(u32x4*)(dst + (size_t)row * 512 + bj * 128) = pack8(ga, gb);
;                     }
;                 }
	v_pk_mul_f32 v[186:187], v[38:39], v[186:187]
	v_pk_mul_f32 v[188:189], v[32:33], v[188:189]
	v_pk_mul_f32 v[190:191], v[34:35], v[190:191]
	v_exp_f32_e32 v176, v176
	v_exp_f32_e32 v177, v177
	v_exp_f32_e32 v178, v178
	v_exp_f32_e32 v179, v179
	v_exp_f32_e32 v180, v180
	v_exp_f32_e32 v181, v181
	v_exp_f32_e32 v182, v182
	v_exp_f32_e32 v183, v183
	v_exp_f32_e32 v184, v184
	v_exp_f32_e32 v185, v185
	v_exp_f32_e32 v186, v186
	v_exp_f32_e32 v187, v187
	v_exp_f32_e32 v188, v188
	v_exp_f32_e32 v189, v189
	v_exp_f32_e32 v190, v190
	v_exp_f32_e32 v191, v191
	v_pk_add_f32 v[176:177], v[176:177], v[212:213]
	v_pk_add_f32 v[178:179], v[178:179], v[212:213]
	v_pk_add_f32 v[180:181], v[180:181], v[212:213]
	v_pk_add_f32 v[182:183], v[182:183], v[212:213]
	v_pk_add_f32 v[184:185], v[184:185], v[212:213]
	v_pk_add_f32 v[186:187], v[186:187], v[212:213]
	v_pk_add_f32 v[188:189], v[188:189], v[212:213]
	v_pk_add_f32 v[190:191], v[190:191], v[212:213]
	v_rcp_f32_e32 v176, v176
	v_rcp_f32_e32 v177, v177
	v_rcp_f32_e32 v178, v178
	v_rcp_f32_e32 v179, v179
	v_rcp_f32_e32 v180, v180
	v_rcp_f32_e32 v181, v181
	v_rcp_f32_e32 v182, v182
	v_rcp_f32_e32 v183, v183
	v_rcp_f32_e32 v184, v184
	v_rcp_f32_e32 v185, v185
	v_rcp_f32_e32 v186, v186
	v_rcp_f32_e32 v187, v187
	v_rcp_f32_e32 v188, v188
	v_rcp_f32_e32 v189, v189
	v_rcp_f32_e32 v190, v190
	v_rcp_f32_e32 v191, v191
	v_pk_mul_f32 v[44:45], v[44:45], v[176:177]
	v_pk_mul_f32 v[46:47], v[46:47], v[178:179]
	v_pk_mul_f32 v[40:41], v[40:41], v[180:181]
	v_pk_mul_f32 v[42:43], v[42:43], v[182:183]
	v_pk_mul_f32 v[36:37], v[36:37], v[184:185]
	v_pk_mul_f32 v[38:39], v[38:39], v[186:187]
	v_pk_mul_f32 v[32:33], v[32:33], v[188:189]
	v_pk_mul_f32 v[34:35], v[34:35], v[190:191]
	v_cvt_pk_bf16_f32 v44, v44, v45
	v_cvt_pk_bf16_f32 v45, v46, v47
	v_cvt_pk_bf16_f32 v46, v40, v41
	v_cvt_pk_bf16_f32 v47, v42, v43
	global_store_dwordx4 v[222:223], v[44:47], off
	v_cvt_pk_bf16_f32 v36, v36, v37
	v_cvt_pk_bf16_f32 v37, v38, v39
	v_cvt_pk_bf16_f32 v38, v32, v33
	v_cvt_pk_bf16_f32 v39, v34, v35
	global_store_dwordx4 v[222:223], v[36:39], off offset:256
	v_pk_mul_f32 v[28:29], v[28:29], v[206:207] op_sel_hi:[1,0]
	v_pk_mul_f32 v[30:31], v[30:31], v[206:207] op_sel_hi:[1,0]
	v_pk_mul_f32 v[24:25], v[24:25], v[206:207] op_sel_hi:[1,0]
	v_pk_mul_f32 v[26:27], v[26:27], v[206:207] op_sel_hi:[1,0]
	v_pk_mul_f32 v[20:21], v[20:21], v[206:207] op_sel_hi:[1,0]
	v_pk_mul_f32 v[22:23], v[22:23], v[206:207] op_sel_hi:[1,0]
	v_pk_mul_f32 v[16:17], v[16:17], v[206:207] op_sel_hi:[1,0]
	v_pk_mul_f32 v[18:19], v[18:19], v[206:207] op_sel_hi:[1,0]
	v_pk_mul_f32 v[176:177], v[28:29], v[28:29]
	v_pk_mul_f32 v[178:179], v[30:31], v[30:31]
	v_pk_mul_f32 v[180:181], v[24:25], v[24:25]
	v_pk_mul_f32 v[182:183], v[26:27], v[26:27]
	v_pk_mul_f32 v[184:185], v[20:21], v[20:21]
	v_pk_mul_f32 v[186:187], v[22:23], v[22:23]
	v_pk_mul_f32 v[188:189], v[16:17], v[16:17]
	v_pk_mul_f32 v[190:191], v[18:19], v[18:19]
	v_pk_fma_f32 v[176:177], v[176:177], v[208:209], v[210:211]
	v_pk_fma_f32 v[178:179], v[178:179], v[208:209], v[210:211]
	v_pk_fma_f32 v[180:181], v[180:181], v[208:209], v[210:211]
	v_pk_fma_f32 v[182:183], v[182:183], v[208:209], v[210:211]
	v_pk_fma_f32 v[184:185], v[184:185], v[208:209], v[210:211]
	v_pk_fma_f32 v[186:187], v[186:187], v[208:209], v[210:211]
	v_pk_fma_f32 v[188:189], v[188:189], v[208:209], v[210:211]
	v_pk_fma_f32 v[190:191], v[190:191], v[208:209], v[210:211]
	v_pk_mul_f32 v[176:177], v[28:29], v[176:177]
	v_pk_mul_f32 v[178:179], v[30:31], v[178:179]
	v_pk_mul_f32 v[180:181], v[24:25], v[180:181]
	v_pk_mul_f32 v[182:183], v[26:27], v[182:183]
	v_pk_mul_f32 v[184:185], v[20:21], v[184:185]
	v_pk_mul_f32 v[186:187], v[22:23], v[186:187]
	v_pk_mul_f32 v[188:189], v[16:17], v[188:189]
	v_pk_mul_f32 v[190:191], v[18:19], v[190:191]
	v_exp_f32_e32 v176, v176
	v_exp_f32_e32 v177, v177
	v_exp_f32_e32 v178, v178
	v_exp_f32_e32 v179, v179
	v_exp_f32_e32 v180, v180
	v_exp_f32_e32 v181, v181
	v_exp_f32_e32 v182, v182
	v_exp_f32_e32 v183, v183
	v_exp_f32_e32 v184, v184
	v_exp_f32_e32 v185, v185
	v_exp_f32_e32 v186, v186
	v_exp_f32_e32 v187, v187
	v_exp_f32_e32 v188, v188
	v_exp_f32_e32 v189, v189
	v_exp_f32_e32 v190, v190
	v_exp_f32_e32 v191, v191
	v_pk_add_f32 v[176:177], v[176:177], v[212:213]
	v_pk_add_f32 v[178:179], v[178:179], v[212:213]
	v_pk_add_f32 v[180:181], v[180:181], v[212:213]
	v_pk_add_f32 v[182:183], v[182:183], v[212:213]
	v_pk_add_f32 v[184:185], v[184:185], v[212:213]
	v_pk_add_f32 v[186:187], v[186:187], v[212:213]
	v_pk_add_f32 v[188:189], v[188:189], v[212:213]
	v_pk_add_f32 v[190:191], v[190:191], v[212:213]
	v_rcp_f32_e32 v176, v176
	v_rcp_f32_e32 v177, v177
	v_rcp_f32_e32 v178, v178
	v_rcp_f32_e32 v179, v179
	v_rcp_f32_e32 v180, v180
	v_rcp_f32_e32 v181, v181
; __device__ __forceinline__ u32x4 pack8(f32x4 a, f32x4 b) { u32x4 o; o.x = cvt_pk(a.x, a.y); o.y = cvt_pk(a.z, a.w); o.z = cvt_pk(b.x, b.y); o.w = cvt_pk(b.z, b.w); return o; }
; __device__ __forceinline__ float rstd_of(const float* SS, int row, float invw) { return 1.0f / sqrtf(SS[row] * invw + EPS); }
; template <class Epi, class Sched, bool ALIGN_EPI = false, bool SP2 = false, bool ABLK = false>
; __device__ __forceinline__ void gemm_phase(PG8_LAS unsigned char* lds, const Gemm g, const Sched& S, const Epi& E) {
;     ...
;         if constexpr (!Epi::AFTER_DRAIN) { E(acc, cur, wr, wc, fr, fq); S.done(cur); }
;         if (!has_next) break;
; __device__ __forceinline__ float gelu_f(float x) {
;     const float t = x * (1.f + 0.044715f * x * x);
;     return x * __builtin_amdgcn_rcpf(1.f + __builtin_amdgcn_exp2f(-2.3022081986f * t));
; }
;     __device__ __forceinline__ void operator()(const f32x4 (&acc)[2][2][4][2], const pg8::Unit& u, int wr, int wc, int fr, int fq) const {
;     ...
;             for (int ai = 0; ai < 2; ++ai)
; #pragma unroll
;                 for (int m = 0; m < 4; ++m) {
;                     const int row = row0 + ai * 128 + m * 16; const float r = rstd_of(SS1, row, 1.f / 1024.f);
; #pragma unroll
;                     for (int bj = 0; bj < 2; ++bj) {
;                         const f32x4 a = acc[ai][bj][m][0] * r, b = acc[ai][bj][m][1] * r;
;                         f32x4 ga, gb; ga.x = gelu_f(a.x); ga.y = gelu_f(a.y); ga.z = gelu_f(a.z); ga.w = gelu_f(a.w);
;                         gb.x = gelu_f(b.x); gb.y = gelu_f(b.y); gb.z = gelu_f(b.z); gb.w = gelu_f(b.w);
;                         *(u32x4*)(dst + (size_t)row * 512 + bj * 128) = pack8(ga, gb);
;                     }
;                 }
	v_rcp_f32_e32 v182, v182
	v_rcp_f32_e32 v183, v183
	v_rcp_f32_e32 v184, v184
	v_rcp_f32_e32 v185, v185
	v_rcp_f32_e32 v186, v186
	v_rcp_f32_e32 v187, v187
	v_rcp_f32_e32 v188, v188
	v_rcp_f32_e32 v189, v189
	v_rcp_f32_e32 v190, v190
	v_rcp_f32_e32 v191, v191
	v_pk_mul_f32 v[28:29], v[28:29], v[176:177]
	v_pk_mul_f32 v[30:31], v[30:31], v[178:179]
	v_pk_mul_f32 v[24:25], v[24:25], v[180:181]
	v_pk_mul_f32 v[26:27], v[26:27], v[182:183]
	v_pk_mul_f32 v[20:21], v[20:21], v[184:185]
	v_pk_mul_f32 v[22:23], v[22:23], v[186:187]
	v_pk_mul_f32 v[16:17], v[16:17], v[188:189]
	v_pk_mul_f32 v[18:19], v[18:19], v[190:191]
	v_cvt_pk_bf16_f32 v28, v28, v29
	v_cvt_pk_bf16_f32 v29, v30, v31
	v_cvt_pk_bf16_f32 v30, v24, v25
	v_cvt_pk_bf16_f32 v31, v26, v27
	global_store_dwordx4 v[224:225], v[28:31], off
	v_cvt_pk_bf16_f32 v20, v20, v21
	v_cvt_pk_bf16_f32 v21, v22, v23
	v_cvt_pk_bf16_f32 v22, v16, v17
	v_cvt_pk_bf16_f32 v23, v18, v19
	global_store_dwordx4 v[224:225], v[20:23], off offset:256
	v_pk_mul_f32 v[12:13], v[12:13], v[206:207] op_sel:[0,1] op_sel_hi:[1,1]
	v_pk_mul_f32 v[14:15], v[14:15], v[206:207] op_sel:[0,1] op_sel_hi:[1,1]
	v_pk_mul_f32 v[8:9], v[8:9], v[206:207] op_sel:[0,1] op_sel_hi:[1,1]
	v_pk_mul_f32 v[10:11], v[10:11], v[206:207] op_sel:[0,1] op_sel_hi:[1,1]
	v_pk_mul_f32 v[4:5], v[4:5], v[206:207] op_sel:[0,1] op_sel_hi:[1,1]
	v_pk_mul_f32 v[6:7], v[6:7], v[206:207] op_sel:[0,1] op_sel_hi:[1,1]
	v_pk_mul_f32 v[0:1], v[0:1], v[206:207] op_sel:[0,1] op_sel_hi:[1,1]
	v_pk_mul_f32 v[2:3], v[2:3], v[206:207] op_sel:[0,1] op_sel_hi:[1,1]
	v_pk_mul_f32 v[176:177], v[12:13], v[12:13]
	v_pk_mul_f32 v[178:179], v[14:15], v[14:15]
	v_pk_mul_f32 v[180:181], v[8:9], v[8:9]
	v_pk_mul_f32 v[182:183], v[10:11], v[10:11]
	v_pk_mul_f32 v[184:185], v[4:5], v[4:5]
	v_pk_mul_f32 v[186:187], v[6:7], v[6:7]
	v_pk_mul_f32 v[188:189], v[0:1], v[0:1]
	v_pk_mul_f32 v[190:191], v[2:3], v[2:3]
	v_pk_fma_f32 v[176:177], v[176:177], v[208:209], v[210:211]
	v_pk_fma_f32 v[178:179], v[178:179], v[208:209], v[210:211]
	v_pk_fma_f32 v[180:181], v[180:181], v[208:209], v[210:211]
	v_pk_fma_f32 v[182:183], v[182:183], v[208:209], v[210:211]
	v_pk_fma_f32 v[184:185], v[184:185], v[208:209], v[210:211]
	v_pk_fma_f32 v[186:187], v[186:187], v[208:209], v[210:211]
	v_pk_fma_f32 v[188:189], v[188:189], v[208:209], v[210:211]
	v_pk_fma_f32 v[190:191], v[190:191], v[208:209], v[210:211]
	v_pk_mul_f32 v[176:177], v[12:13], v[176:177]
	v_pk_mul_f32 v[178:179], v[14:15], v[178:179]
	v_pk_mul_f32 v[180:181], v[8:9], v[180:181]
	v_pk_mul_f32 v[182:183], v[10:11], v[182:183]
	v_pk_mul_f32 v[184:185], v[4:5], v[184:185]
	v_pk_mul_f32 v[186:187], v[6:7], v[186:187]
	v_pk_mul_f32 v[188:189], v[0:1], v[188:189]
	v_pk_mul_f32 v[190:191], v[2:3], v[190:191]
	v_exp_f32_e32 v176, v176
	v_exp_f32_e32 v177, v177
	v_exp_f32_e32 v178, v178
	v_exp_f32_e32 v179, v179
	v_exp_f32_e32 v180, v180
	v_exp_f32_e32 v181, v181
	v_exp_f32_e32 v182, v182
	v_exp_f32_e32 v183, v183
	v_exp_f32_e32 v184, v184
	v_exp_f32_e32 v185, v185
	v_exp_f32_e32 v186, v186
	v_exp_f32_e32 v187, v187
	v_exp_f32_e32 v188, v188
	v_exp_f32_e32 v189, v189
	v_exp_f32_e32 v190, v190
	v_exp_f32_e32 v191, v191
	v_pk_add_f32 v[176:177], v[176:177], v[212:213]
	v_pk_add_f32 v[178:179], v[178:179], v[212:213]
	v_pk_add_f32 v[180:181], v[180:181], v[212:213]
	v_pk_add_f32 v[182:183], v[182:183], v[212:213]
	v_pk_add_f32 v[184:185], v[184:185], v[212:213]
	v_pk_add_f32 v[186:187], v[186:187], v[212:213]
	v_pk_add_f32 v[188:189], v[188:189], v[212:213]
	v_pk_add_f32 v[190:191], v[190:191], v[212:213]
	v_rcp_f32_e32 v176, v176
	v_rcp_f32_e32 v177, v177
	v_rcp_f32_e32 v178, v178
	v_rcp_f32_e32 v179, v179
	v_rcp_f32_e32 v180, v180
	v_rcp_f32_e32 v181, v181
	v_rcp_f32_e32 v182, v182
	v_rcp_f32_e32 v183, v183
	v_rcp_f32_e32 v184, v184
	v_rcp_f32_e32 v185, v185
	v_rcp_f32_e32 v186, v186
	v_rcp_f32_e32 v187, v187
	v_rcp_f32_e32 v188, v188
	v_rcp_f32_e32 v189, v189
	v_rcp_f32_e32 v190, v190
	v_rcp_f32_e32 v191, v191
	v_pk_mul_f32 v[12:13], v[12:13], v[176:177]
	v_pk_mul_f32 v[14:15], v[14:15], v[178:179]
	v_pk_mul_f32 v[8:9], v[8:9], v[180:181]
	v_pk_mul_f32 v[10:11], v[10:11], v[182:183]
	v_pk_mul_f32 v[4:5], v[4:5], v[184:185]
	v_pk_mul_f32 v[6:7], v[6:7], v[186:187]
	v_pk_mul_f32 v[0:1], v[0:1], v[188:189]
	v_pk_mul_f32 v[2:3], v[2:3], v[190:191]
	v_cvt_pk_bf16_f32 v12, v12, v13
	v_cvt_pk_bf16_f32 v13, v14, v15
	v_cvt_pk_bf16_f32 v14, v8, v9
	v_cvt_pk_bf16_f32 v15, v10, v11
	global_store_dwordx4 v[226:227], v[12:15], off
	v_cvt_pk_bf16_f32 v4, v4, v5
	v_cvt_pk_bf16_f32 v5, v6, v7
	v_cvt_pk_bf16_f32 v6, v0, v1
	v_cvt_pk_bf16_f32 v7, v2, v3
	global_store_dwordx4 v[226:227], v[4:7], off offset:256
	s_andn2_b64 vcc, exec, s[40:41]
	s_mov_b64 s[0:1], -1
	s_cbranch_vccnz .LBB0_341

; __device__ __forceinline__ u32x4 pack8(f32x4 a, f32x4 b) { u32x4 o; o.x = cvt_pk(a.x, a.y); o.y = cvt_pk(a.z, a.w); o.z = cvt_pk(b.x, b.y); o.w = cvt_pk(b.z, b.w); return o; }
; __device__ __forceinline__ float rstd_of(const float* SS, int row, float invw) { return 1.0f / sqrtf(SS[row] * invw + EPS); }
;     __device__ __forceinline__ void operator()(const f32x4 (&acc)[2][2][4][2], const pg8::Unit& u, int wr, int wc, int fr, int fq) const {
;         const int row0 = u.pm * 256 + wr * 64 + fr, col0 = u.pn * 256 + wc * 32 + 8 * fq;
; #pragma unroll
;         for (int ai = 0; ai < 2; ++ai)
; #pragma unroll
;             for (int m = 0; m < 4; ++m) {
;                 const int row = row0 + ai * 128 + m * 16; const float r = rstd_of(SS, row, invw);
; #pragma unroll
;                 for (int bj = 0; bj < 2; ++bj)
;                     *(u32x4*)(O + (size_t)row * ldc + col0 + bj * 128) = pack8(acc[ai][bj][m][0] * r, acc[ai][bj][m][1] * r);
;             }
;     }
.LBB0_475:
	v_lshl_add_u32 v140, s0, 8, v144
	v_ashrrev_i32_e32 v141, 31, v140
	v_lshl_add_u64 v[142:143], v[140:141], 2, s[46:47]
	global_load_dword v200, v[142:143], off
	global_load_dword v201, v[142:143], off offset:64
	global_load_dword v202, v[142:143], off offset:128
	global_load_dword v203, v[142:143], off offset:192
	global_load_dword v204, v[142:143], off offset:512
	global_load_dword v205, v[142:143], off offset:576
	global_load_dword v206, v[142:143], off offset:640
	global_load_dword v207, v[142:143], off offset:704
	v_lshl_or_b32 v152, s1, 8, v146
	v_ashrrev_i32_e32 v153, 31, v152
	s_waitcnt vmcnt(0)
	v_mov_b32_e32 v141, v200
	v_fmamk_f32 v141, v141, 0x3b800000, v150
	v_rsq_f32_e32 v154, v141
	s_nop 0
	v_pk_mul_f32 v[126:127], v[126:127], v[154:155] op_sel_hi:[1,0]
	v_pk_mul_f32 v[124:125], v[124:125], v[154:155] op_sel_hi:[1,0]
	v_pk_mul_f32 v[120:121], v[120:121], v[154:155] op_sel_hi:[1,0]
	v_pk_mul_f32 v[122:123], v[122:123], v[154:155] op_sel_hi:[1,0]
	v_cvt_pk_bf16_f32 v124, v124, v125
	v_cvt_pk_bf16_f32 v125, v126, v127
	v_cvt_pk_bf16_f32 v126, v120, v121
	v_mov_b64_e32 v[120:121], s[34:35]
	v_cvt_pk_bf16_f32 v127, v122, v123
	v_mad_i64_i32 v[156:157], s[0:1], v140, s10, v[120:121]
	v_lshlrev_b64 v[122:123], 1, v[152:153]
	v_lshl_add_u64 v[152:153], v[156:157], 0, v[122:123]
	global_store_dwordx4 v[152:153], v[124:127], off
	v_pk_mul_f32 v[116:117], v[116:117], v[154:155] op_sel_hi:[1,0]
	v_pk_mul_f32 v[118:119], v[118:119], v[154:155] op_sel_hi:[1,0]
	v_pk_mul_f32 v[124:125], v[114:115], v[154:155] op_sel_hi:[1,0]
	v_pk_mul_f32 v[114:115], v[112:113], v[154:155] op_sel_hi:[1,0]
	v_cvt_pk_bf16_f32 v112, v116, v117
	v_cvt_pk_bf16_f32 v113, v118, v119
	s_nop 0
	v_cvt_pk_bf16_f32 v114, v114, v115
	v_cvt_pk_bf16_f32 v115, v124, v125
	global_store_dwordx4 v[152:153], v[112:115], off offset:256
	s_nop 1
	v_or_b32_e32 v112, 16, v140
	v_ashrrev_i32_e32 v113, 31, v112
	v_lshl_add_u64 v[114:115], v[112:113], 2, s[46:47]
	s_nop 1
	v_mov_b32_e32 v113, v201
	v_fmamk_f32 v113, v113, 0x3b800000, v150
	v_rsq_f32_e32 v114, v113
	s_nop 0
	v_pk_mul_f32 v[108:109], v[108:109], v[114:115] op_sel_hi:[1,0]
	v_pk_mul_f32 v[116:117], v[106:107], v[114:115] op_sel_hi:[1,0]
	v_pk_mul_f32 v[106:107], v[104:105], v[114:115] op_sel_hi:[1,0]
	v_cvt_pk_bf16_f32 v104, v108, v109
	v_mad_i64_i32 v[108:109], s[0:1], v112, s10, v[120:121]
	v_pk_mul_f32 v[110:111], v[110:111], v[114:115] op_sel_hi:[1,0]
	v_lshl_add_u64 v[108:109], v[108:109], 0, v[122:123]
	v_cvt_pk_bf16_f32 v105, v110, v111
	v_cvt_pk_bf16_f32 v106, v106, v107
	v_cvt_pk_bf16_f32 v107, v116, v117
	global_store_dwordx4 v[108:109], v[104:107], off
	v_pk_mul_f32 v[100:101], v[100:101], v[114:115] op_sel_hi:[1,0]
	v_pk_mul_f32 v[102:103], v[102:103], v[114:115] op_sel_hi:[1,0]
	v_pk_mul_f32 v[104:105], v[98:99], v[114:115] op_sel_hi:[1,0]
	v_pk_mul_f32 v[98:99], v[96:97], v[114:115] op_sel_hi:[1,0]
	v_cvt_pk_bf16_f32 v96, v100, v101
	v_cvt_pk_bf16_f32 v97, v102, v103
	s_nop 0
	v_cvt_pk_bf16_f32 v98, v98, v99
	v_cvt_pk_bf16_f32 v99, v104, v105
	global_store_dwordx4 v[108:109], v[96:99], off offset:256
	s_nop 1
	v_or_b32_e32 v96, 32, v140
	v_ashrrev_i32_e32 v97, 31, v96
	v_lshl_add_u64 v[98:99], v[96:97], 2, s[46:47]
	s_nop 1
	v_mov_b32_e32 v97, v202
	v_fmamk_f32 v97, v97, 0x3b800000, v150
	v_rsq_f32_e32 v98, v97
	s_nop 0
	v_pk_mul_f32 v[92:93], v[92:93], v[98:99] op_sel_hi:[1,0]
	v_pk_mul_f32 v[100:101], v[90:91], v[98:99] op_sel_hi:[1,0]
	v_pk_mul_f32 v[90:91], v[88:89], v[98:99] op_sel_hi:[1,0]
	v_cvt_pk_bf16_f32 v88, v92, v93
	v_mad_i64_i32 v[92:93], s[0:1], v96, s10, v[120:121]
	v_pk_mul_f32 v[94:95], v[94:95], v[98:99] op_sel_hi:[1,0]
	v_lshl_add_u64 v[92:93], v[92:93], 0, v[122:123]
	v_cvt_pk_bf16_f32 v89, v94, v95
	v_cvt_pk_bf16_f32 v90, v90, v91
	v_cvt_pk_bf16_f32 v91, v100, v101
	global_store_dwordx4 v[92:93], v[88:91], off
	v_pk_mul_f32 v[84:85], v[84:85], v[98:99] op_sel_hi:[1,0]
	v_pk_mul_f32 v[86:87], v[86:87], v[98:99] op_sel_hi:[1,0]
	v_pk_mul_f32 v[88:89], v[82:83], v[98:99] op_sel_hi:[1,0]
	v_pk_mul_f32 v[82:83], v[80:81], v[98:99] op_sel_hi:[1,0]
	v_cvt_pk_bf16_f32 v80, v84, v85
	v_cvt_pk_bf16_f32 v81, v86, v87
	s_nop 0
	v_cvt_pk_bf16_f32 v82, v82, v83
	v_cvt_pk_bf16_f32 v83, v88, v89
	global_store_dwordx4 v[92:93], v[80:83], off offset:256
	s_nop 1
	v_or_b32_e32 v80, 48, v140
	v_ashrrev_i32_e32 v81, 31, v80
	v_lshl_add_u64 v[82:83], v[80:81], 2, s[46:47]
	s_nop 1
	v_mov_b32_e32 v81, v203
	v_fmamk_f32 v81, v81, 0x3b800000, v150
	v_rsq_f32_e32 v82, v81
	s_nop 0
	v_pk_mul_f32 v[76:77], v[76:77], v[82:83] op_sel_hi:[1,0]
	v_pk_mul_f32 v[84:85], v[74:75], v[82:83] op_sel_hi:[1,0]
	v_pk_mul_f32 v[74:75], v[72:73], v[82:83] op_sel_hi:[1,0]
	v_cvt_pk_bf16_f32 v72, v76, v77
	v_mad_i64_i32 v[76:77], s[0:1], v80, s10, v[120:121]
	v_pk_mul_f32 v[78:79], v[78:79], v[82:83] op_sel_hi:[1,0]
	v_lshl_add_u64 v[76:77], v[76:77], 0, v[122:123]
	v_cvt_pk_bf16_f32 v73, v78, v79
	v_cvt_pk_bf16_f32 v74, v74, v75
	v_cvt_pk_bf16_f32 v75, v84, v85
; __device__ __forceinline__ u32x4 pack8(f32x4 a, f32x4 b) { u32x4 o; o.x = cvt_pk(a.x, a.y); o.y = cvt_pk(a.z, a.w); o.z = cvt_pk(b.x, b.y); o.w = cvt_pk(b.z, b.w); return o; }
; __device__ __forceinline__ float rstd_of(const float* SS, int row, float invw) { return 1.0f / sqrtf(SS[row] * invw + EPS); }
;     __device__ __forceinline__ void operator()(const f32x4 (&acc)[2][2][4][2], const pg8::Unit& u, int wr, int wc, int fr, int fq) const {
;         const int row0 = u.pm * 256 + wr * 64 + fr, col0 = u.pn * 256 + wc * 32 + 8 * fq;
; #pragma unroll
;         for (int ai = 0; ai < 2; ++ai)
; #pragma unroll
;             for (int m = 0; m < 4; ++m) {
;                 const int row = row0 + ai * 128 + m * 16; const float r = rstd_of(SS, row, invw);
; #pragma unroll
;                 for (int bj = 0; bj < 2; ++bj)
;                     *(u32x4*)(O + (size_t)row * ldc + col0 + bj * 128) = pack8(acc[ai][bj][m][0] * r, acc[ai][bj][m][1] * r);
;             }
;     }
	global_store_dwordx4 v[76:77], v[72:75], off
	v_pk_mul_f32 v[70:71], v[70:71], v[82:83] op_sel_hi:[1,0]
	v_pk_mul_f32 v[68:69], v[68:69], v[82:83] op_sel_hi:[1,0]
	v_pk_mul_f32 v[72:73], v[66:67], v[82:83] op_sel_hi:[1,0]
	v_pk_mul_f32 v[66:67], v[64:65], v[82:83] op_sel_hi:[1,0]
	v_cvt_pk_bf16_f32 v64, v68, v69
	v_cvt_pk_bf16_f32 v65, v70, v71
	s_nop 0
	v_cvt_pk_bf16_f32 v66, v66, v67
	v_cvt_pk_bf16_f32 v67, v72, v73
	global_store_dwordx4 v[76:77], v[64:67], off offset:256
	s_nop 1
	s_nop 0
	v_add_u32_e32 v65, 0x80, v140
	v_mov_b32_e32 v64, v204
	v_fmamk_f32 v64, v64, 0x3b800000, v150
	v_rsq_f32_e32 v64, v64
	s_nop 0
	v_pk_mul_f32 v[60:61], v[60:61], v[64:65] op_sel_hi:[1,0]
	v_pk_mul_f32 v[66:67], v[58:59], v[64:65] op_sel_hi:[1,0]
	v_pk_mul_f32 v[58:59], v[56:57], v[64:65] op_sel_hi:[1,0]
	v_cvt_pk_bf16_f32 v56, v60, v61
	v_mad_i64_i32 v[60:61], s[0:1], v65, s10, v[120:121]
	v_pk_mul_f32 v[62:63], v[62:63], v[64:65] op_sel_hi:[1,0]
	v_lshl_add_u64 v[60:61], v[60:61], 0, v[122:123]
	v_cvt_pk_bf16_f32 v57, v62, v63
	v_cvt_pk_bf16_f32 v58, v58, v59
	v_cvt_pk_bf16_f32 v59, v66, v67
	global_store_dwordx4 v[60:61], v[56:59], off
	v_pk_mul_f32 v[54:55], v[54:55], v[64:65] op_sel_hi:[1,0]
	v_pk_mul_f32 v[52:53], v[52:53], v[64:65] op_sel_hi:[1,0]
	v_pk_mul_f32 v[56:57], v[50:51], v[64:65] op_sel_hi:[1,0]
	v_pk_mul_f32 v[50:51], v[48:49], v[64:65] op_sel_hi:[1,0]
	v_cvt_pk_bf16_f32 v48, v52, v53
	v_cvt_pk_bf16_f32 v49, v54, v55
	s_nop 0
	v_cvt_pk_bf16_f32 v50, v50, v51
	v_cvt_pk_bf16_f32 v51, v56, v57
	global_store_dwordx4 v[60:61], v[48:51], off offset:256
	s_nop 1
	s_nop 0
	v_add_u32_e32 v49, 0x90, v140
	v_mov_b32_e32 v48, v205
	v_fmamk_f32 v48, v48, 0x3b800000, v150
	v_rsq_f32_e32 v48, v48
	s_nop 0
	v_pk_mul_f32 v[44:45], v[44:45], v[48:49] op_sel_hi:[1,0]
	v_pk_mul_f32 v[50:51], v[42:43], v[48:49] op_sel_hi:[1,0]
	v_pk_mul_f32 v[42:43], v[40:41], v[48:49] op_sel_hi:[1,0]
	v_cvt_pk_bf16_f32 v40, v44, v45
	v_mad_i64_i32 v[44:45], s[0:1], v49, s10, v[120:121]
	v_pk_mul_f32 v[46:47], v[46:47], v[48:49] op_sel_hi:[1,0]
	v_lshl_add_u64 v[44:45], v[44:45], 0, v[122:123]
	v_cvt_pk_bf16_f32 v41, v46, v47
	v_cvt_pk_bf16_f32 v42, v42, v43
	v_cvt_pk_bf16_f32 v43, v50, v51
	global_store_dwordx4 v[44:45], v[40:43], off
	v_pk_mul_f32 v[38:39], v[38:39], v[48:49] op_sel_hi:[1,0]
	v_pk_mul_f32 v[36:37], v[36:37], v[48:49] op_sel_hi:[1,0]
	v_pk_mul_f32 v[40:41], v[34:35], v[48:49] op_sel_hi:[1,0]
	v_pk_mul_f32 v[34:35], v[32:33], v[48:49] op_sel_hi:[1,0]
	v_cvt_pk_bf16_f32 v32, v36, v37
	v_cvt_pk_bf16_f32 v33, v38, v39
	s_nop 0
	v_cvt_pk_bf16_f32 v34, v34, v35
	v_cvt_pk_bf16_f32 v35, v40, v41
	global_store_dwordx4 v[44:45], v[32:35], off offset:256
	s_nop 1
	s_nop 0
	v_add_u32_e32 v33, 0xa0, v140
	v_mov_b32_e32 v32, v206
	v_fmamk_f32 v32, v32, 0x3b800000, v150
	v_rsq_f32_e32 v32, v32
	s_nop 0
	v_pk_mul_f32 v[28:29], v[28:29], v[32:33] op_sel_hi:[1,0]
	v_pk_mul_f32 v[34:35], v[26:27], v[32:33] op_sel_hi:[1,0]
	v_pk_mul_f32 v[26:27], v[24:25], v[32:33] op_sel_hi:[1,0]
	v_cvt_pk_bf16_f32 v24, v28, v29
	v_mad_i64_i32 v[28:29], s[0:1], v33, s10, v[120:121]
	v_pk_mul_f32 v[30:31], v[30:31], v[32:33] op_sel_hi:[1,0]
	v_lshl_add_u64 v[28:29], v[28:29], 0, v[122:123]
	v_cvt_pk_bf16_f32 v25, v30, v31
	v_cvt_pk_bf16_f32 v26, v26, v27
	v_cvt_pk_bf16_f32 v27, v34, v35
	global_store_dwordx4 v[28:29], v[24:27], off
	v_pk_mul_f32 v[22:23], v[22:23], v[32:33] op_sel_hi:[1,0]
	v_pk_mul_f32 v[20:21], v[20:21], v[32:33] op_sel_hi:[1,0]
	v_pk_mul_f32 v[24:25], v[18:19], v[32:33] op_sel_hi:[1,0]
	v_pk_mul_f32 v[18:19], v[16:17], v[32:33] op_sel_hi:[1,0]
	v_cvt_pk_bf16_f32 v16, v20, v21
	v_cvt_pk_bf16_f32 v17, v22, v23
	s_nop 0
	v_cvt_pk_bf16_f32 v18, v18, v19
	v_cvt_pk_bf16_f32 v19, v24, v25
	global_store_dwordx4 v[28:29], v[16:19], off offset:256
	s_nop 1
	s_nop 0
	v_add_u32_e32 v17, 0xb0, v140
	v_mov_b32_e32 v16, v207
	v_fmamk_f32 v16, v16, 0x3b800000, v150
	v_rsq_f32_e32 v16, v16
	s_nop 0
	v_pk_mul_f32 v[12:13], v[12:13], v[16:17] op_sel_hi:[1,0]
	v_pk_mul_f32 v[18:19], v[10:11], v[16:17] op_sel_hi:[1,0]
	v_pk_mul_f32 v[10:11], v[8:9], v[16:17] op_sel_hi:[1,0]
	v_cvt_pk_bf16_f32 v8, v12, v13
	v_mad_i64_i32 v[12:13], s[0:1], v17, s10, v[120:121]
	v_pk_mul_f32 v[14:15], v[14:15], v[16:17] op_sel_hi:[1,0]
	v_lshl_add_u64 v[12:13], v[12:13], 0, v[122:123]
	v_cvt_pk_bf16_f32 v9, v14, v15
	v_cvt_pk_bf16_f32 v10, v10, v11
	v_cvt_pk_bf16_f32 v11, v18, v19
	global_store_dwordx4 v[12:13], v[8:11], off
	s_mov_b64 s[0:1], -1
	s_andn2_b64 vcc, exec, s[38:39]
	v_pk_mul_f32 v[8:9], v[2:3], v[16:17] op_sel_hi:[1,0]
	v_pk_mul_f32 v[2:3], v[0:1], v[16:17] op_sel_hi:[1,0]
	v_pk_mul_f32 v[6:7], v[6:7], v[16:17] op_sel_hi:[1,0]
	v_pk_mul_f32 v[4:5], v[4:5], v[16:17] op_sel_hi:[1,0]
	s_nop 0
	v_cvt_pk_bf16_f32 v0, v4, v5
	v_cvt_pk_bf16_f32 v1, v6, v7
	v_cvt_pk_bf16_f32 v2, v2, v3
	v_cvt_pk_bf16_f32 v3, v8, v9
	global_store_dwordx4 v[12:13], v[0:3], off offset:256
	s_cbranch_vccnz .LBB0_468
	s_andn2_b64 vcc, exec, s[30:31]
	s_cbranch_vccnz .LBB0_467
	s_barrier
	s_branch .LBB0_467

; __device__ __forceinline__ u32x4 pack8(f32x4 a, f32x4 b) { u32x4 o; o.x = cvt_pk(a.x, a.y); o.y = cvt_pk(a.z, a.w); o.z = cvt_pk(b.x, b.y); o.w = cvt_pk(b.z, b.w); return o; }
; __device__ __forceinline__ float rstd_of(const float* SS, int row, float invw) { return 1.0f / sqrtf(SS[row] * invw + EPS); }
;     __device__ __forceinline__ void operator()(const f32x4 (&acc)[2][2][4][2], const pg8::Unit& u, int wr, int wc, int fr, int fq) const {
;         const int row0 = u.pm * 256 + wr * 64 + fr, col0 = u.pn * 256 + wc * 32 + 8 * fq;
; #pragma unroll
;         for (int ai = 0; ai < 2; ++ai)
; #pragma unroll
;             for (int m = 0; m < 4; ++m) {
;                 const int row = row0 + ai * 128 + m * 16; const float r = rstd_of(SS, row, invw);
; #pragma unroll
;                 for (int bj = 0; bj < 2; ++bj)
;                     *(u32x4*)(O + (size_t)row * ldc + col0 + bj * 128) = pack8(acc[ai][bj][m][0] * r, acc[ai][bj][m][1] * r);
;             }
;     }
.LBB0_493:
	v_lshl_add_u32 v142, s0, 8, v144
	v_ashrrev_i32_e32 v143, 31, v142
	v_lshl_add_u64 v[140:141], v[142:143], 2, s[44:45]
	global_load_dword v200, v[140:141], off
	global_load_dword v201, v[140:141], off offset:64
	global_load_dword v202, v[140:141], off offset:128
	global_load_dword v203, v[140:141], off offset:192
	global_load_dword v204, v[140:141], off offset:512
	global_load_dword v205, v[140:141], off offset:576
	global_load_dword v206, v[140:141], off offset:640
	global_load_dword v207, v[140:141], off offset:704
	v_lshl_or_b32 v152, s1, 8, v146
	v_ashrrev_i32_e32 v153, 31, v152
	s_waitcnt vmcnt(0)
	v_mov_b32_e32 v154, v200
	v_fmamk_f32 v154, v154, 0x3c000000, v150
	v_rsq_f32_e32 v154, v154
	s_nop 0
	v_pk_mul_f32 v[112:113], v[112:113], v[154:155] op_sel_hi:[1,0]
	v_pk_mul_f32 v[114:115], v[114:115], v[154:155] op_sel_hi:[1,0]
	v_pk_mul_f32 v[156:157], v[118:119], v[154:155] op_sel_hi:[1,0]
	v_pk_mul_f32 v[118:119], v[116:117], v[154:155] op_sel_hi:[1,0]
	v_cvt_pk_bf16_f32 v116, v112, v113
	v_lshlrev_b64 v[112:113], 11, v[142:143]
	v_cvt_pk_bf16_f32 v117, v114, v115
	v_lshl_add_u64 v[112:113], s[12:13], 0, v[112:113]
	v_lshlrev_b64 v[114:115], 1, v[152:153]
	v_lshl_add_u64 v[112:113], v[112:113], 0, v[114:115]
	v_cvt_pk_bf16_f32 v118, v118, v119
	v_cvt_pk_bf16_f32 v119, v156, v157
	global_store_dwordx4 v[112:113], v[116:119], off
	s_nop 1
	v_pk_mul_f32 v[116:117], v[120:121], v[154:155] op_sel_hi:[1,0]
	v_pk_mul_f32 v[118:119], v[122:123], v[154:155] op_sel_hi:[1,0]
	v_cvt_pk_bf16_f32 v116, v116, v117
	v_pk_mul_f32 v[120:121], v[126:127], v[154:155] op_sel_hi:[1,0]
	v_pk_mul_f32 v[122:123], v[124:125], v[154:155] op_sel_hi:[1,0]
	v_cvt_pk_bf16_f32 v117, v118, v119
	s_nop 0
	v_cvt_pk_bf16_f32 v118, v122, v123
	v_cvt_pk_bf16_f32 v119, v120, v121
	global_store_dwordx4 v[112:113], v[116:119], off offset:256
	s_nop 1
	v_or_b32_e32 v116, 16, v142
	v_ashrrev_i32_e32 v117, 31, v116
	v_lshl_add_u64 v[118:119], v[116:117], 2, s[44:45]
	s_nop 1
	v_mov_b32_e32 v118, v201
	v_fmamk_f32 v118, v118, 0x3c000000, v150
	v_rsq_f32_e32 v118, v118
	s_nop 0
	v_pk_mul_f32 v[98:99], v[98:99], v[118:119] op_sel_hi:[1,0]
	v_pk_mul_f32 v[96:97], v[96:97], v[118:119] op_sel_hi:[1,0]
	v_pk_mul_f32 v[100:101], v[100:101], v[118:119] op_sel_hi:[1,0]
	v_cvt_pk_bf16_f32 v96, v96, v97
	v_cvt_pk_bf16_f32 v97, v98, v99
	v_pk_mul_f32 v[102:103], v[102:103], v[118:119] op_sel_hi:[1,0]
	v_cvt_pk_bf16_f32 v98, v100, v101
	v_lshlrev_b64 v[100:101], 11, v[116:117]
	v_lshl_add_u64 v[100:101], s[12:13], 0, v[100:101]
	v_lshl_add_u64 v[100:101], v[100:101], 0, v[114:115]
	v_cvt_pk_bf16_f32 v99, v102, v103
	global_store_dwordx4 v[100:101], v[96:99], off
	v_pk_mul_f32 v[102:103], v[110:111], v[118:119] op_sel_hi:[1,0]
	s_nop 0
	v_pk_mul_f32 v[96:97], v[104:105], v[118:119] op_sel_hi:[1,0]
	v_pk_mul_f32 v[98:99], v[106:107], v[118:119] op_sel_hi:[1,0]
	v_cvt_pk_bf16_f32 v96, v96, v97
	v_pk_mul_f32 v[104:105], v[108:109], v[118:119] op_sel_hi:[1,0]
	v_cvt_pk_bf16_f32 v97, v98, v99
	s_nop 0
	v_cvt_pk_bf16_f32 v98, v104, v105
	v_cvt_pk_bf16_f32 v99, v102, v103
	global_store_dwordx4 v[100:101], v[96:99], off offset:256
	s_nop 1
	v_or_b32_e32 v96, 32, v142
	v_ashrrev_i32_e32 v97, 31, v96
	v_lshl_add_u64 v[98:99], v[96:97], 2, s[44:45]
	s_nop 1
	v_mov_b32_e32 v98, v202
	v_fmamk_f32 v98, v98, 0x3c000000, v150
	v_rsq_f32_e32 v98, v98
	s_nop 0
	v_pk_mul_f32 v[82:83], v[82:83], v[98:99] op_sel_hi:[1,0]
	v_pk_mul_f32 v[80:81], v[80:81], v[98:99] op_sel_hi:[1,0]
	v_pk_mul_f32 v[84:85], v[84:85], v[98:99] op_sel_hi:[1,0]
	v_cvt_pk_bf16_f32 v80, v80, v81
	v_cvt_pk_bf16_f32 v81, v82, v83
	v_pk_mul_f32 v[86:87], v[86:87], v[98:99] op_sel_hi:[1,0]
	v_cvt_pk_bf16_f32 v82, v84, v85
	v_lshlrev_b64 v[84:85], 11, v[96:97]
	v_lshl_add_u64 v[84:85], s[12:13], 0, v[84:85]
	v_lshl_add_u64 v[84:85], v[84:85], 0, v[114:115]
	v_cvt_pk_bf16_f32 v83, v86, v87
	global_store_dwordx4 v[84:85], v[80:83], off
	v_pk_mul_f32 v[86:87], v[94:95], v[98:99] op_sel_hi:[1,0]
	s_nop 0
	v_pk_mul_f32 v[80:81], v[88:89], v[98:99] op_sel_hi:[1,0]
	v_pk_mul_f32 v[82:83], v[90:91], v[98:99] op_sel_hi:[1,0]
	v_cvt_pk_bf16_f32 v80, v80, v81
	v_pk_mul_f32 v[88:89], v[92:93], v[98:99] op_sel_hi:[1,0]
	v_cvt_pk_bf16_f32 v81, v82, v83
	s_nop 0
	v_cvt_pk_bf16_f32 v82, v88, v89
	v_cvt_pk_bf16_f32 v83, v86, v87
	global_store_dwordx4 v[84:85], v[80:83], off offset:256
	s_nop 1
	v_or_b32_e32 v80, 48, v142
	v_ashrrev_i32_e32 v81, 31, v80
	v_lshl_add_u64 v[82:83], v[80:81], 2, s[44:45]
	s_nop 1
	v_mov_b32_e32 v82, v203
	v_fmamk_f32 v82, v82, 0x3c000000, v150
	v_rsq_f32_e32 v82, v82
	s_nop 0
	v_pk_mul_f32 v[74:75], v[74:75], v[82:83] op_sel_hi:[1,0]
	v_pk_mul_f32 v[72:73], v[72:73], v[82:83] op_sel_hi:[1,0]
	v_pk_mul_f32 v[76:77], v[76:77], v[82:83] op_sel_hi:[1,0]
	v_cvt_pk_bf16_f32 v72, v72, v73
	v_cvt_pk_bf16_f32 v73, v74, v75
	v_pk_mul_f32 v[78:79], v[78:79], v[82:83] op_sel_hi:[1,0]
	v_cvt_pk_bf16_f32 v74, v76, v77
	v_lshlrev_b64 v[76:77], 11, v[80:81]
	v_lshl_add_u64 v[76:77], s[12:13], 0, v[76:77]
	v_lshl_add_u64 v[76:77], v[76:77], 0, v[114:115]
	v_cvt_pk_bf16_f32 v75, v78, v79
	global_store_dwordx4 v[76:77], v[72:75], off
; __device__ __forceinline__ u32x4 pack8(f32x4 a, f32x4 b) { u32x4 o; o.x = cvt_pk(a.x, a.y); o.y = cvt_pk(a.z, a.w); o.z = cvt_pk(b.x, b.y); o.w = cvt_pk(b.z, b.w); return o; }
; __device__ __forceinline__ float rstd_of(const float* SS, int row, float invw) { return 1.0f / sqrtf(SS[row] * invw + EPS); }
;     __device__ __forceinline__ void operator()(const f32x4 (&acc)[2][2][4][2], const pg8::Unit& u, int wr, int wc, int fr, int fq) const {
;         const int row0 = u.pm * 256 + wr * 64 + fr, col0 = u.pn * 256 + wc * 32 + 8 * fq;
; #pragma unroll
;         for (int ai = 0; ai < 2; ++ai)
; #pragma unroll
;             for (int m = 0; m < 4; ++m) {
;                 const int row = row0 + ai * 128 + m * 16; const float r = rstd_of(SS, row, invw);
; #pragma unroll
;                 for (int bj = 0; bj < 2; ++bj)
;                     *(u32x4*)(O + (size_t)row * ldc + col0 + bj * 128) = pack8(acc[ai][bj][m][0] * r, acc[ai][bj][m][1] * r);
;             }
;     }
	v_pk_mul_f32 v[70:71], v[70:71], v[82:83] op_sel_hi:[1,0]
	v_pk_mul_f32 v[68:69], v[68:69], v[82:83] op_sel_hi:[1,0]
	v_pk_mul_f32 v[72:73], v[66:67], v[82:83] op_sel_hi:[1,0]
	v_pk_mul_f32 v[66:67], v[64:65], v[82:83] op_sel_hi:[1,0]
	v_cvt_pk_bf16_f32 v64, v68, v69
	v_cvt_pk_bf16_f32 v65, v70, v71
	s_nop 0
	v_cvt_pk_bf16_f32 v66, v66, v67
	v_cvt_pk_bf16_f32 v67, v72, v73
	global_store_dwordx4 v[76:77], v[64:67], off offset:256
	s_nop 1
	v_mov_b32_e32 v64, v204
	v_fmamk_f32 v64, v64, 0x3c000000, v150
	s_mov_b64 s[0:1], 0x40000
	v_rsq_f32_e32 v64, v64
	s_nop 0
	v_pk_mul_f32 v[56:57], v[56:57], v[64:65] op_sel_hi:[1,0]
	v_pk_mul_f32 v[66:67], v[58:59], v[64:65] op_sel_hi:[1,0]
	v_pk_mul_f32 v[62:63], v[62:63], v[64:65] op_sel_hi:[1,0]
	v_pk_mul_f32 v[60:61], v[60:61], v[64:65] op_sel_hi:[1,0]
	v_cvt_pk_bf16_f32 v58, v56, v57
	v_lshl_add_u64 v[56:57], v[112:113], 0, s[0:1]
	s_mov_b32 s0, 0x40000
	v_cvt_pk_bf16_f32 v59, v66, v67
	v_cvt_pk_bf16_f32 v60, v60, v61
	v_cvt_pk_bf16_f32 v61, v62, v63
	v_add_co_u32_e32 v62, vcc, s0, v112
	v_pk_mul_f32 v[54:55], v[54:55], v[64:65] op_sel_hi:[1,0]
	s_nop 0
	v_addc_co_u32_e32 v63, vcc, 0, v113, vcc
	global_store_dwordx4 v[62:63], v[58:61], off
	v_pk_mul_f32 v[52:53], v[52:53], v[64:65] op_sel_hi:[1,0]
	s_nop 0
	v_pk_mul_f32 v[58:59], v[50:51], v[64:65] op_sel_hi:[1,0]
	v_pk_mul_f32 v[50:51], v[48:49], v[64:65] op_sel_hi:[1,0]
	v_cvt_pk_bf16_f32 v48, v52, v53
	v_cvt_pk_bf16_f32 v49, v54, v55
	s_nop 0
	v_cvt_pk_bf16_f32 v50, v50, v51
	v_cvt_pk_bf16_f32 v51, v58, v59
	global_store_dwordx4 v[56:57], v[48:51], off offset:256
	s_nop 1
	v_mov_b32_e32 v48, v205
	v_fmamk_f32 v48, v48, 0x3c000000, v150
	s_mov_b64 s[0:1], 0x48000
	v_rsq_f32_e32 v48, v48
	s_nop 0
	v_pk_mul_f32 v[40:41], v[40:41], v[48:49] op_sel_hi:[1,0]
	v_pk_mul_f32 v[50:51], v[42:43], v[48:49] op_sel_hi:[1,0]
	v_pk_mul_f32 v[46:47], v[46:47], v[48:49] op_sel_hi:[1,0]
	v_pk_mul_f32 v[44:45], v[44:45], v[48:49] op_sel_hi:[1,0]
	v_cvt_pk_bf16_f32 v42, v40, v41
	v_lshl_add_u64 v[40:41], v[112:113], 0, s[0:1]
	s_mov_b32 s0, 0x48000
	v_cvt_pk_bf16_f32 v43, v50, v51
	v_cvt_pk_bf16_f32 v44, v44, v45
	v_cvt_pk_bf16_f32 v45, v46, v47
	v_add_co_u32_e32 v46, vcc, s0, v112
	v_pk_mul_f32 v[38:39], v[38:39], v[48:49] op_sel_hi:[1,0]
	s_nop 0
	v_addc_co_u32_e32 v47, vcc, 0, v113, vcc
	global_store_dwordx4 v[46:47], v[42:45], off
	v_pk_mul_f32 v[36:37], v[36:37], v[48:49] op_sel_hi:[1,0]
	s_nop 0
	v_pk_mul_f32 v[42:43], v[34:35], v[48:49] op_sel_hi:[1,0]
	v_pk_mul_f32 v[34:35], v[32:33], v[48:49] op_sel_hi:[1,0]
	v_cvt_pk_bf16_f32 v32, v36, v37
	v_cvt_pk_bf16_f32 v33, v38, v39
	s_nop 0
	v_cvt_pk_bf16_f32 v34, v34, v35
	v_cvt_pk_bf16_f32 v35, v42, v43
	global_store_dwordx4 v[40:41], v[32:35], off offset:256
	s_nop 1
	v_mov_b32_e32 v32, v206
	v_fmamk_f32 v32, v32, 0x3c000000, v150
	s_mov_b64 s[0:1], 0x50000
	v_rsq_f32_e32 v32, v32
	s_nop 0
	v_pk_mul_f32 v[24:25], v[24:25], v[32:33] op_sel_hi:[1,0]
	v_pk_mul_f32 v[34:35], v[26:27], v[32:33] op_sel_hi:[1,0]
	v_pk_mul_f32 v[30:31], v[30:31], v[32:33] op_sel_hi:[1,0]
	v_pk_mul_f32 v[28:29], v[28:29], v[32:33] op_sel_hi:[1,0]
	v_cvt_pk_bf16_f32 v26, v24, v25
	v_lshl_add_u64 v[24:25], v[112:113], 0, s[0:1]
	s_mov_b32 s0, 0x50000
	v_cvt_pk_bf16_f32 v27, v34, v35
	v_cvt_pk_bf16_f32 v28, v28, v29
	v_cvt_pk_bf16_f32 v29, v30, v31
	v_add_co_u32_e32 v30, vcc, s0, v112
	v_pk_mul_f32 v[22:23], v[22:23], v[32:33] op_sel_hi:[1,0]
	s_nop 0
	v_addc_co_u32_e32 v31, vcc, 0, v113, vcc
	global_store_dwordx4 v[30:31], v[26:29], off
	v_pk_mul_f32 v[20:21], v[20:21], v[32:33] op_sel_hi:[1,0]
	s_nop 0
	v_pk_mul_f32 v[26:27], v[18:19], v[32:33] op_sel_hi:[1,0]
	v_pk_mul_f32 v[18:19], v[16:17], v[32:33] op_sel_hi:[1,0]
	v_cvt_pk_bf16_f32 v16, v20, v21
	v_cvt_pk_bf16_f32 v17, v22, v23
	s_nop 0
	v_cvt_pk_bf16_f32 v18, v18, v19
	v_cvt_pk_bf16_f32 v19, v26, v27
	global_store_dwordx4 v[24:25], v[16:19], off offset:256
	s_nop 1
	v_mov_b32_e32 v16, v207
	v_fmamk_f32 v16, v16, 0x3c000000, v150
	s_mov_b64 s[0:1], 0x58000
	v_rsq_f32_e32 v16, v16
	s_nop 0
	v_pk_mul_f32 v[10:11], v[10:11], v[16:17] op_sel_hi:[1,0]
	v_pk_mul_f32 v[8:9], v[8:9], v[16:17] op_sel_hi:[1,0]
	v_pk_mul_f32 v[12:13], v[12:13], v[16:17] op_sel_hi:[1,0]
	v_pk_mul_f32 v[14:15], v[14:15], v[16:17] op_sel_hi:[1,0]
	v_cvt_pk_bf16_f32 v8, v8, v9
	v_cvt_pk_bf16_f32 v9, v10, v11
	v_cvt_pk_bf16_f32 v10, v12, v13
	v_lshl_add_u64 v[12:13], v[112:113], 0, s[0:1]
	s_mov_b32 s0, 0x58000
	v_cvt_pk_bf16_f32 v11, v14, v15
	v_add_co_u32_e32 v14, vcc, s0, v112
	v_pk_mul_f32 v[2:3], v[2:3], v[16:17] op_sel_hi:[1,0]
	s_nop 0
	v_addc_co_u32_e32 v15, vcc, 0, v113, vcc
	v_pk_mul_f32 v[0:1], v[0:1], v[16:17] op_sel_hi:[1,0]
	s_mov_b64 s[0:1], -1
	s_andn2_b64 vcc, exec, s[38:39]
	global_store_dwordx4 v[14:15], v[8:11], off
	v_pk_mul_f32 v[6:7], v[6:7], v[16:17] op_sel_hi:[1,0]
	v_pk_mul_f32 v[4:5], v[4:5], v[16:17] op_sel_hi:[1,0]
	v_cvt_pk_bf16_f32 v0, v0, v1
	v_cvt_pk_bf16_f32 v1, v2, v3
	s_nop 0
	v_cvt_pk_bf16_f32 v2, v4, v5
	v_cvt_pk_bf16_f32 v3, v6, v7
	global_store_dwordx4 v[12:13], v[0:3], off offset:256
	s_cbranch_vccnz .LBB0_484
	s_andn2_b64 vcc, exec, s[30:31]
	s_cbranch_vccnz .LBB0_483
	s_barrier
	s_branch .LBB0_483

; __device__ __forceinline__ float sq4(f32x4 a) { return (a.x * a.x + a.y * a.y) + (a.z * a.z + a.w * a.w); }
; __device__ __forceinline__ u32x4 pack8(f32x4 a, f32x4 b) { u32x4 o; o.x = cvt_pk(a.x, a.y); o.y = cvt_pk(a.z, a.w); o.z = cvt_pk(b.x, b.y); o.w = cvt_pk(b.z, b.w); return o; }
; __device__ __forceinline__ float rstd_of(const float* SS, int row, float invw) { return 1.0f / sqrtf(SS[row] * invw + EPS); }
; __device__ __forceinline__ void row_stat_add(float* SS, int row, float v, int fq) {
;     v += __shfl_xor(v, 16); v += __shfl_xor(v, 32);
;     if (fq == 0) unsafeAtomicAdd(SS + row, v);
; }
;     __device__ __forceinline__ void operator()(const f32x4 (&acc)[2][2][4][2], const pg8::Unit& u, int wr, int wc, int fr, int fq) const {
;         const int row0 = u.pm * 256 + wr * 64 + fr, col0 = u.pn * 256 + wc * 32 + 8 * fq;
; #pragma unroll
;         for (int ai = 0; ai < 2; ++ai)
; #pragma unroll
;             for (int m = 0; m < 4; ++m) {
;                 const int row = row0 + ai * 128 + m * 16; float ssq = 0.f;
;                 const float rb = rstd_of(SSB, row, 1.f / 512.f);
; #pragma unroll
;                 for (int bj = 0; bj < 2; ++bj) {
;                     const size_t idx = (size_t)row * D + col0 + bj * 128;
;                     const u32x4 w = *(const u32x4*)(X + idx);
;                     const f32x4 r0 = {bflo(w.x), bfhi(w.x), bflo(w.y), bfhi(w.y)}, r1 = {bflo(w.z), bfhi(w.z), bflo(w.w), bfhi(w.w)};
;                     const f32x4 v0 = r0 + acc[ai][bj][m][0] * rb, v1 = r1 + acc[ai][bj][m][1] * rb;
;                     ssq += sq4(v0) + sq4(v1);
;                     *(u32x4*)(X + idx) = pack8(v0, v1);
;                 }
;                 row_stat_add(SS, row, ssq, fq);
;             }
;     }
.LBB0_740:
	v_lshl_add_u32 v150, s70, 8, v149
	v_ashrrev_i32_e32 v151, 31, v150
	v_lshl_add_u64 v[152:153], v[150:151], 2, s[34:35]
	global_load_dword v1, v[152:153], off
	v_lshl_or_b32 v2, s60, 8, v161
	v_lshlrev_b64 v[154:155], 11, v[150:151]
	v_ashrrev_i32_e32 v3, 31, v2
	v_lshl_add_u64 v[154:155], s[96:97], 0, v[154:155]
	v_lshl_add_u64 v[168:169], v[2:3], 1, v[154:155]
	global_load_dwordx4 v[154:157], v[168:169], off
	s_waitcnt vmcnt(0)
	v_fmamk_f32 v1, v1, 0x3b000000, v148
	v_lshlrev_b32_e32 v170, 16, v154
	s_nop 0
	v_and_b32_e32 v171, 0xffff0000, v154
	v_lshlrev_b32_e32 v154, 16, v155
	v_and_b32_e32 v155, 0xffff0000, v155
	v_rsq_f32_e32 v174, v1
	s_nop 0
	v_lshlrev_b32_e32 v172, 16, v156
	v_and_b32_e32 v173, 0xffff0000, v156
	v_lshlrev_b32_e32 v156, 16, v157
	v_and_b32_e32 v157, 0xffff0000, v157
	v_pk_fma_f32 v[154:155], v[130:131], v[174:175], v[154:155] op_sel_hi:[1,0,1]
	v_pk_fma_f32 v[170:171], v[128:129], v[174:175], v[170:171] op_sel_hi:[1,0,1]
	v_pk_fma_f32 v[156:157], v[126:127], v[174:175], v[156:157] op_sel_hi:[1,0,1]
	v_pk_fma_f32 v[172:173], v[124:125], v[174:175], v[172:173] op_sel_hi:[1,0,1]
	v_cvt_pk_bf16_f32 v124, v170, v171
	v_cvt_pk_bf16_f32 v125, v154, v155
	v_mul_f32_e32 v171, v171, v171
	v_cvt_pk_bf16_f32 v126, v172, v173
	v_cvt_pk_bf16_f32 v127, v156, v157
	global_load_dwordx4 v[128:131], v[168:169], off offset:256
	v_mul_f32_e32 v155, v155, v155
	v_mul_f32_e32 v173, v173, v173
	v_mul_f32_e32 v157, v157, v157
	v_fmac_f32_e32 v171, v170, v170
	v_fmac_f32_e32 v155, v154, v154
	v_fmac_f32_e32 v173, v172, v172
	v_fmac_f32_e32 v157, v156, v156
	v_add_f32_e32 v154, v171, v155
	v_add_f32_e32 v155, v173, v157
	v_add_f32_e32 v170, v154, v155
	v_and_b32_e32 v165, 64, v164
	v_xor_b32_e32 v1, 16, v164
	v_add_u32_e32 v165, 64, v165
	v_cmp_lt_i32_e32 vcc, v1, v165
	v_xor_b32_e32 v167, 32, v164
	global_store_dwordx4 v[168:169], v[124:127], off
	v_cndmask_b32_e32 v1, v164, v1, vcc
	v_lshlrev_b32_e32 v1, 2, v1
	v_cmp_lt_i32_e32 vcc, v167, v165
	s_waitcnt vmcnt(1)
	v_lshlrev_b32_e32 v154, 16, v128
	v_and_b32_e32 v155, 0xffff0000, v128
	v_lshlrev_b32_e32 v128, 16, v129
	v_and_b32_e32 v129, 0xffff0000, v129
	v_lshlrev_b32_e32 v156, 16, v130
	v_and_b32_e32 v157, 0xffff0000, v130
	v_lshlrev_b32_e32 v130, 16, v131
	v_and_b32_e32 v131, 0xffff0000, v131
	v_pk_fma_f32 v[122:123], v[122:123], v[174:175], v[128:129] op_sel_hi:[1,0,1]
	v_pk_fma_f32 v[120:121], v[120:121], v[174:175], v[154:155] op_sel_hi:[1,0,1]
	v_pk_fma_f32 v[128:129], v[118:119], v[174:175], v[130:131] op_sel_hi:[1,0,1]
	v_pk_fma_f32 v[130:131], v[116:117], v[174:175], v[156:157] op_sel_hi:[1,0,1]
	v_mul_f32_e32 v116, v121, v121
	v_mul_f32_e32 v117, v123, v123
	v_mul_f32_e32 v118, v131, v131
	v_mul_f32_e32 v119, v129, v129
	v_fmac_f32_e32 v116, v120, v120
	v_fmac_f32_e32 v117, v122, v122
	v_fmac_f32_e32 v118, v130, v130
	v_fmac_f32_e32 v119, v128, v128
	v_add_f32_e32 v116, v116, v117
	v_add_f32_e32 v117, v118, v119
	v_add_f32_e32 v116, v116, v117
	v_add_f32_e32 v116, v170, v116
	ds_bpermute_b32 v117, v1, v116
	v_cndmask_b32_e32 v118, v164, v167, vcc
	v_lshlrev_b32_e32 v118, 2, v118
	v_cvt_pk_bf16_f32 v120, v120, v121
	v_cvt_pk_bf16_f32 v121, v122, v123
	s_waitcnt lgkmcnt(0)
	v_add_f32_e32 v116, v116, v117
	ds_bpermute_b32 v117, v118, v116
	v_cvt_pk_bf16_f32 v122, v130, v131
	v_cvt_pk_bf16_f32 v123, v128, v129
	global_store_dwordx4 v[168:169], v[120:123], off offset:256
	s_and_saveexec_b64 s[0:1], s[40:41]
	s_cbranch_execz .LBB0_742
	v_lshl_add_u64 v[120:121], v[150:151], 2, s[44:45]
	s_waitcnt lgkmcnt(0)
	v_add_f32_e32 v116, v116, v117
	global_atomic_add_f32 v[120:121], v116, off
.LBB0_742:
	s_or_b64 exec, exec, s[0:1]
	v_or_b32_e32 v116, 16, v150
	s_waitcnt lgkmcnt(0)
	v_ashrrev_i32_e32 v117, 31, v116
	v_lshl_add_u64 v[120:121], v[116:117], 2, s[34:35]
	global_load_dword v119, v[120:121], off
	v_lshlrev_b64 v[120:121], 11, v[116:117]
	v_lshl_add_u64 v[120:121], s[96:97], 0, v[120:121]
	v_lshl_add_u64 v[124:125], v[2:3], 1, v[120:121]
	global_load_dwordx4 v[120:123], v[124:125], off
	s_waitcnt vmcnt(1)
	v_fmamk_f32 v119, v119, 0x3b000000, v148
	s_waitcnt vmcnt(0)
	v_and_b32_e32 v127, 0xffff0000, v120
	v_rsq_f32_e32 v130, v119
	s_nop 0
	v_lshlrev_b32_e32 v126, 16, v120
	v_lshlrev_b32_e32 v120, 16, v121
	v_and_b32_e32 v121, 0xffff0000, v121
	v_lshlrev_b32_e32 v128, 16, v122
	v_and_b32_e32 v129, 0xffff0000, v122
	v_lshlrev_b32_e32 v122, 16, v123
	v_and_b32_e32 v123, 0xffff0000, v123
	v_pk_fma_f32 v[120:121], v[114:115], v[130:131], v[120:121] op_sel_hi:[1,0,1]
	v_pk_fma_f32 v[126:127], v[112:113], v[130:131], v[126:127] op_sel_hi:[1,0,1]
	v_pk_fma_f32 v[122:123], v[110:111], v[130:131], v[122:123] op_sel_hi:[1,0,1]
	v_pk_fma_f32 v[128:129], v[108:109], v[130:131], v[128:129] op_sel_hi:[1,0,1]
	v_cvt_pk_bf16_f32 v108, v126, v127
	v_cvt_pk_bf16_f32 v109, v120, v121
	v_mul_f32_e32 v119, v127, v127
	v_cvt_pk_bf16_f32 v110, v128, v129
	v_cvt_pk_bf16_f32 v111, v122, v123
	global_load_dwordx4 v[112:115], v[124:125], off offset:256
	v_mul_f32_e32 v121, v121, v121
	v_mul_f32_e32 v127, v129, v129
	v_mul_f32_e32 v123, v123, v123
	v_fmac_f32_e32 v119, v126, v126
	v_fmac_f32_e32 v121, v120, v120
	v_fmac_f32_e32 v127, v128, v128
	v_fmac_f32_e32 v123, v122, v122
	v_add_f32_e32 v119, v119, v121
	v_add_f32_e32 v120, v127, v123
	v_add_f32_e32 v119, v119, v120
	global_store_dwordx4 v[124:125], v[108:111], off
	s_waitcnt vmcnt(1)
	v_lshlrev_b32_e32 v120, 16, v112
	v_and_b32_e32 v121, 0xffff0000, v112
	v_lshlrev_b32_e32 v112, 16, v113
	v_and_b32_e32 v113, 0xffff0000, v113
	v_lshlrev_b32_e32 v122, 16, v114
	v_and_b32_e32 v123, 0xffff0000, v114
	v_lshlrev_b32_e32 v114, 16, v115
	v_and_b32_e32 v115, 0xffff0000, v115
	v_pk_fma_f32 v[106:107], v[106:107], v[130:131], v[112:113] op_sel_hi:[1,0,1]
	v_pk_fma_f32 v[104:105], v[104:105], v[130:131], v[120:121] op_sel_hi:[1,0,1]
	v_pk_fma_f32 v[112:113], v[102:103], v[130:131], v[114:115] op_sel_hi:[1,0,1]
	v_pk_fma_f32 v[114:115], v[100:101], v[130:131], v[122:123] op_sel_hi:[1,0,1]
	v_mul_f32_e32 v100, v105, v105
	v_mul_f32_e32 v101, v107, v107
	v_mul_f32_e32 v102, v115, v115
	v_mul_f32_e32 v103, v113, v113
	v_fmac_f32_e32 v100, v104, v104
	v_fmac_f32_e32 v101, v106, v106
	v_fmac_f32_e32 v102, v114, v114
	v_fmac_f32_e32 v103, v112, v112
	v_add_f32_e32 v100, v100, v101
	v_add_f32_e32 v101, v102, v103
	v_add_f32_e32 v100, v100, v101
	v_add_f32_e32 v100, v119, v100
	ds_bpermute_b32 v101, v1, v100
	v_cvt_pk_bf16_f32 v102, v104, v105
	v_cvt_pk_bf16_f32 v103, v106, v107
	v_cvt_pk_bf16_f32 v104, v114, v115
	v_cvt_pk_bf16_f32 v105, v112, v113
	s_waitcnt lgkmcnt(0)
	v_add_f32_e32 v100, v100, v101
	ds_bpermute_b32 v101, v118, v100
	global_store_dwordx4 v[124:125], v[102:105], off offset:256
	s_and_saveexec_b64 s[0:1], s[40:41]
	s_cbranch_execz .LBB0_744
	v_lshl_add_u64 v[102:103], v[116:117], 2, s[44:45]
	s_waitcnt lgkmcnt(0)
	v_add_f32_e32 v100, v100, v101
	global_atomic_add_f32 v[102:103], v100, off
; __device__ __forceinline__ float sq4(f32x4 a) { return (a.x * a.x + a.y * a.y) + (a.z * a.z + a.w * a.w); }
; __device__ __forceinline__ u32x4 pack8(f32x4 a, f32x4 b) { u32x4 o; o.x = cvt_pk(a.x, a.y); o.y = cvt_pk(a.z, a.w); o.z = cvt_pk(b.x, b.y); o.w = cvt_pk(b.z, b.w); return o; }
; __device__ __forceinline__ float rstd_of(const float* SS, int row, float invw) { return 1.0f / sqrtf(SS[row] * invw + EPS); }
; __device__ __forceinline__ void row_stat_add(float* SS, int row, float v, int fq) {
;     v += __shfl_xor(v, 16); v += __shfl_xor(v, 32);
;     if (fq == 0) unsafeAtomicAdd(SS + row, v);
; }
;     __device__ __forceinline__ void operator()(const f32x4 (&acc)[2][2][4][2], const pg8::Unit& u, int wr, int wc, int fr, int fq) const {
;         const int row0 = u.pm * 256 + wr * 64 + fr, col0 = u.pn * 256 + wc * 32 + 8 * fq;
; #pragma unroll
;         for (int ai = 0; ai < 2; ++ai)
; #pragma unroll
;             for (int m = 0; m < 4; ++m) {
;                 const int row = row0 + ai * 128 + m * 16; float ssq = 0.f;
;                 const float rb = rstd_of(SSB, row, 1.f / 512.f);
; #pragma unroll
;                 for (int bj = 0; bj < 2; ++bj) {
;                     const size_t idx = (size_t)row * D + col0 + bj * 128;
;                     const u32x4 w = *(const u32x4*)(X + idx);
;                     const f32x4 r0 = {bflo(w.x), bfhi(w.x), bflo(w.y), bfhi(w.y)}, r1 = {bflo(w.z), bfhi(w.z), bflo(w.w), bfhi(w.w)};
;                     const f32x4 v0 = r0 + acc[ai][bj][m][0] * rb, v1 = r1 + acc[ai][bj][m][1] * rb;
;                     ssq += sq4(v0) + sq4(v1);
;                     *(u32x4*)(X + idx) = pack8(v0, v1);
;                 }
;                 row_stat_add(SS, row, ssq, fq);
;             }
;     }
.LBB0_744:
	s_or_b64 exec, exec, s[0:1]
	v_or_b32_e32 v100, 32, v150
	s_waitcnt lgkmcnt(0)
	v_ashrrev_i32_e32 v101, 31, v100
	v_lshl_add_u64 v[102:103], v[100:101], 2, s[34:35]
	global_load_dword v108, v[102:103], off
	v_lshlrev_b64 v[102:103], 11, v[100:101]
	v_lshl_add_u64 v[102:103], s[96:97], 0, v[102:103]
	v_lshl_add_u64 v[106:107], v[2:3], 1, v[102:103]
	global_load_dwordx4 v[102:105], v[106:107], off
	s_waitcnt vmcnt(1)
	v_fmamk_f32 v108, v108, 0x3b000000, v148
	s_waitcnt vmcnt(0)
	v_lshlrev_b32_e32 v110, 16, v104
	v_rsq_f32_e32 v112, v108
	s_nop 0
	v_lshlrev_b32_e32 v108, 16, v102
	v_and_b32_e32 v109, 0xffff0000, v102
	v_lshlrev_b32_e32 v102, 16, v103
	v_and_b32_e32 v103, 0xffff0000, v103
	v_and_b32_e32 v111, 0xffff0000, v104
	v_lshlrev_b32_e32 v104, 16, v105
	v_and_b32_e32 v105, 0xffff0000, v105
	v_pk_fma_f32 v[102:103], v[98:99], v[112:113], v[102:103] op_sel_hi:[1,0,1]
	v_pk_fma_f32 v[108:109], v[96:97], v[112:113], v[108:109] op_sel_hi:[1,0,1]
	v_pk_fma_f32 v[104:105], v[94:95], v[112:113], v[104:105] op_sel_hi:[1,0,1]
	v_pk_fma_f32 v[110:111], v[92:93], v[112:113], v[110:111] op_sel_hi:[1,0,1]
	v_cvt_pk_bf16_f32 v92, v108, v109
	v_cvt_pk_bf16_f32 v93, v102, v103
	v_mul_f32_e32 v109, v109, v109
	v_cvt_pk_bf16_f32 v94, v110, v111
	v_cvt_pk_bf16_f32 v95, v104, v105
	global_load_dwordx4 v[96:99], v[106:107], off offset:256
	v_mul_f32_e32 v103, v103, v103
	v_mul_f32_e32 v111, v111, v111
	v_mul_f32_e32 v105, v105, v105
	v_fmac_f32_e32 v109, v108, v108
	v_fmac_f32_e32 v103, v102, v102
	v_fmac_f32_e32 v111, v110, v110
	v_fmac_f32_e32 v105, v104, v104
	v_add_f32_e32 v102, v109, v103
	v_add_f32_e32 v103, v111, v105
	v_add_f32_e32 v108, v102, v103
	global_store_dwordx4 v[106:107], v[92:95], off
	s_waitcnt vmcnt(1)
	v_lshlrev_b32_e32 v102, 16, v96
	v_and_b32_e32 v103, 0xffff0000, v96
	v_lshlrev_b32_e32 v96, 16, v97
	v_and_b32_e32 v97, 0xffff0000, v97
	v_lshlrev_b32_e32 v104, 16, v98
	v_and_b32_e32 v105, 0xffff0000, v98
	v_lshlrev_b32_e32 v98, 16, v99
	v_and_b32_e32 v99, 0xffff0000, v99
	v_pk_fma_f32 v[90:91], v[90:91], v[112:113], v[96:97] op_sel_hi:[1,0,1]
	v_pk_fma_f32 v[88:89], v[88:89], v[112:113], v[102:103] op_sel_hi:[1,0,1]
	v_pk_fma_f32 v[96:97], v[86:87], v[112:113], v[98:99] op_sel_hi:[1,0,1]
	v_pk_fma_f32 v[98:99], v[84:85], v[112:113], v[104:105] op_sel_hi:[1,0,1]
	v_mul_f32_e32 v84, v89, v89
	v_mul_f32_e32 v85, v91, v91
	v_mul_f32_e32 v86, v99, v99
	v_mul_f32_e32 v87, v97, v97
	v_fmac_f32_e32 v84, v88, v88
	v_fmac_f32_e32 v85, v90, v90
	v_fmac_f32_e32 v86, v98, v98
	v_fmac_f32_e32 v87, v96, v96
	v_add_f32_e32 v84, v84, v85
	v_add_f32_e32 v85, v86, v87
	v_add_f32_e32 v84, v84, v85
	v_add_f32_e32 v84, v108, v84
	ds_bpermute_b32 v85, v1, v84
	v_cvt_pk_bf16_f32 v86, v88, v89
	v_cvt_pk_bf16_f32 v87, v90, v91
	v_cvt_pk_bf16_f32 v88, v98, v99
	v_cvt_pk_bf16_f32 v89, v96, v97
	s_waitcnt lgkmcnt(0)
	v_add_f32_e32 v84, v84, v85
	ds_bpermute_b32 v85, v118, v84
	global_store_dwordx4 v[106:107], v[86:89], off offset:256
	s_and_saveexec_b64 s[0:1], s[40:41]
	s_cbranch_execz .LBB0_746
	v_lshl_add_u64 v[86:87], v[100:101], 2, s[44:45]
	s_waitcnt lgkmcnt(0)
	v_add_f32_e32 v84, v84, v85
	global_atomic_add_f32 v[86:87], v84, off
.LBB0_746:
	s_or_b64 exec, exec, s[0:1]
	v_or_b32_e32 v84, 48, v150
	s_waitcnt lgkmcnt(0)
	v_ashrrev_i32_e32 v85, 31, v84
	v_lshl_add_u64 v[86:87], v[84:85], 2, s[34:35]
	global_load_dword v92, v[86:87], off
	v_lshlrev_b64 v[86:87], 11, v[84:85]
	v_lshl_add_u64 v[86:87], s[96:97], 0, v[86:87]
	v_lshl_add_u64 v[90:91], v[2:3], 1, v[86:87]
	global_load_dwordx4 v[86:89], v[90:91], off
	s_waitcnt vmcnt(1)
	v_fmamk_f32 v92, v92, 0x3b000000, v148
	s_waitcnt vmcnt(0)
	v_lshlrev_b32_e32 v94, 16, v88
	v_rsq_f32_e32 v96, v92
	s_nop 0
	v_lshlrev_b32_e32 v92, 16, v86
	v_and_b32_e32 v93, 0xffff0000, v86
	v_lshlrev_b32_e32 v86, 16, v87
	v_and_b32_e32 v87, 0xffff0000, v87
	v_and_b32_e32 v95, 0xffff0000, v88
	v_lshlrev_b32_e32 v88, 16, v89
	v_and_b32_e32 v89, 0xffff0000, v89
	v_pk_fma_f32 v[86:87], v[82:83], v[96:97], v[86:87] op_sel_hi:[1,0,1]
	v_pk_fma_f32 v[92:93], v[80:81], v[96:97], v[92:93] op_sel_hi:[1,0,1]
	v_pk_fma_f32 v[88:89], v[78:79], v[96:97], v[88:89] op_sel_hi:[1,0,1]
	v_pk_fma_f32 v[94:95], v[76:77], v[96:97], v[94:95] op_sel_hi:[1,0,1]
	v_cvt_pk_bf16_f32 v76, v92, v93
	v_cvt_pk_bf16_f32 v77, v86, v87
	v_mul_f32_e32 v93, v93, v93
	v_cvt_pk_bf16_f32 v78, v94, v95
	v_cvt_pk_bf16_f32 v79, v88, v89
	global_load_dwordx4 v[80:83], v[90:91], off offset:256
	v_mul_f32_e32 v87, v87, v87
	v_mul_f32_e32 v95, v95, v95
	v_mul_f32_e32 v89, v89, v89
	v_fmac_f32_e32 v93, v92, v92
	v_fmac_f32_e32 v87, v86, v86
	v_fmac_f32_e32 v95, v94, v94
	v_fmac_f32_e32 v89, v88, v88
	v_add_f32_e32 v86, v93, v87
	v_add_f32_e32 v87, v95, v89
	v_add_f32_e32 v92, v86, v87
	global_store_dwordx4 v[90:91], v[76:79], off
	s_waitcnt vmcnt(1)
	v_lshlrev_b32_e32 v86, 16, v80
	v_and_b32_e32 v87, 0xffff0000, v80
	v_lshlrev_b32_e32 v80, 16, v81
	v_and_b32_e32 v81, 0xffff0000, v81
	v_lshlrev_b32_e32 v88, 16, v82
	v_and_b32_e32 v89, 0xffff0000, v82
	v_lshlrev_b32_e32 v82, 16, v83
	v_and_b32_e32 v83, 0xffff0000, v83
	v_pk_fma_f32 v[74:75], v[74:75], v[96:97], v[80:81] op_sel_hi:[1,0,1]
	v_pk_fma_f32 v[72:73], v[72:73], v[96:97], v[86:87] op_sel_hi:[1,0,1]
	v_pk_fma_f32 v[80:81], v[70:71], v[96:97], v[82:83] op_sel_hi:[1,0,1]
	v_pk_fma_f32 v[82:83], v[68:69], v[96:97], v[88:89] op_sel_hi:[1,0,1]
	v_mul_f32_e32 v68, v73, v73
	v_mul_f32_e32 v69, v75, v75
	v_mul_f32_e32 v70, v83, v83
	v_mul_f32_e32 v71, v81, v81
	v_fmac_f32_e32 v68, v72, v72
	v_fmac_f32_e32 v69, v74, v74
	v_fmac_f32_e32 v70, v82, v82
	v_fmac_f32_e32 v71, v80, v80
	v_add_f32_e32 v68, v68, v69
	v_add_f32_e32 v69, v70, v71
	v_add_f32_e32 v68, v68, v69
	v_add_f32_e32 v68, v92, v68
	ds_bpermute_b32 v69, v1, v68
	v_cvt_pk_bf16_f32 v70, v72, v73
	v_cvt_pk_bf16_f32 v71, v74, v75
	v_cvt_pk_bf16_f32 v72, v82, v83
	v_cvt_pk_bf16_f32 v73, v80, v81
	s_waitcnt lgkmcnt(0)
	v_add_f32_e32 v68, v68, v69
	ds_bpermute_b32 v69, v118, v68
	global_store_dwordx4 v[90:91], v[70:73], off offset:256
	s_and_saveexec_b64 s[0:1], s[40:41]
	s_cbranch_execz .LBB0_748
	v_lshl_add_u64 v[70:71], v[84:85], 2, s[44:45]
	s_waitcnt lgkmcnt(0)
	v_add_f32_e32 v68, v68, v69
	global_atomic_add_f32 v[70:71], v68, off
; __device__ __forceinline__ float sq4(f32x4 a) { return (a.x * a.x + a.y * a.y) + (a.z * a.z + a.w * a.w); }
; __device__ __forceinline__ u32x4 pack8(f32x4 a, f32x4 b) { u32x4 o; o.x = cvt_pk(a.x, a.y); o.y = cvt_pk(a.z, a.w); o.z = cvt_pk(b.x, b.y); o.w = cvt_pk(b.z, b.w); return o; }
; __device__ __forceinline__ float rstd_of(const float* SS, int row, float invw) { return 1.0f / sqrtf(SS[row] * invw + EPS); }
; __device__ __forceinline__ void row_stat_add(float* SS, int row, float v, int fq) {
;     v += __shfl_xor(v, 16); v += __shfl_xor(v, 32);
;     if (fq == 0) unsafeAtomicAdd(SS + row, v);
; }
;     __device__ __forceinline__ void operator()(const f32x4 (&acc)[2][2][4][2], const pg8::Unit& u, int wr, int wc, int fr, int fq) const {
;         const int row0 = u.pm * 256 + wr * 64 + fr, col0 = u.pn * 256 + wc * 32 + 8 * fq;
; #pragma unroll
;         for (int ai = 0; ai < 2; ++ai)
; #pragma unroll
;             for (int m = 0; m < 4; ++m) {
;                 const int row = row0 + ai * 128 + m * 16; float ssq = 0.f;
;                 const float rb = rstd_of(SSB, row, 1.f / 512.f);
; #pragma unroll
;                 for (int bj = 0; bj < 2; ++bj) {
;                     const size_t idx = (size_t)row * D + col0 + bj * 128;
;                     const u32x4 w = *(const u32x4*)(X + idx);
;                     const f32x4 r0 = {bflo(w.x), bfhi(w.x), bflo(w.y), bfhi(w.y)}, r1 = {bflo(w.z), bfhi(w.z), bflo(w.w), bfhi(w.w)};
;                     const f32x4 v0 = r0 + acc[ai][bj][m][0] * rb, v1 = r1 + acc[ai][bj][m][1] * rb;
;                     ssq += sq4(v0) + sq4(v1);
;                     *(u32x4*)(X + idx) = pack8(v0, v1);
;                 }
;                 row_stat_add(SS, row, ssq, fq);
;             }
;     }
.LBB0_748:
	s_or_b64 exec, exec, s[0:1]
	global_load_dword v76, v[152:153], off offset:512
	v_add_u32_e32 v68, 0x80, v150
	s_waitcnt lgkmcnt(0)
	v_ashrrev_i32_e32 v69, 31, v68
	v_lshlrev_b64 v[70:71], 11, v[68:69]
	v_lshl_add_u64 v[70:71], s[96:97], 0, v[70:71]
	v_lshl_add_u64 v[74:75], v[2:3], 1, v[70:71]
	global_load_dwordx4 v[70:73], v[74:75], off
	s_waitcnt vmcnt(1)
	v_fmamk_f32 v76, v76, 0x3b000000, v148
	s_waitcnt vmcnt(0)
	v_lshlrev_b32_e32 v78, 16, v72
	v_rsq_f32_e32 v80, v76
	s_nop 0
	v_lshlrev_b32_e32 v76, 16, v70
	v_and_b32_e32 v77, 0xffff0000, v70
	v_lshlrev_b32_e32 v70, 16, v71
	v_and_b32_e32 v71, 0xffff0000, v71
	v_and_b32_e32 v79, 0xffff0000, v72
	v_lshlrev_b32_e32 v72, 16, v73
	v_and_b32_e32 v73, 0xffff0000, v73
	v_pk_fma_f32 v[70:71], v[66:67], v[80:81], v[70:71] op_sel_hi:[1,0,1]
	v_pk_fma_f32 v[76:77], v[64:65], v[80:81], v[76:77] op_sel_hi:[1,0,1]
	v_pk_fma_f32 v[72:73], v[62:63], v[80:81], v[72:73] op_sel_hi:[1,0,1]
	v_pk_fma_f32 v[78:79], v[60:61], v[80:81], v[78:79] op_sel_hi:[1,0,1]
	v_cvt_pk_bf16_f32 v60, v76, v77
	v_cvt_pk_bf16_f32 v61, v70, v71
	v_mul_f32_e32 v77, v77, v77
	v_cvt_pk_bf16_f32 v62, v78, v79
	v_cvt_pk_bf16_f32 v63, v72, v73
	global_load_dwordx4 v[64:67], v[74:75], off offset:256
	v_mul_f32_e32 v71, v71, v71
	v_mul_f32_e32 v79, v79, v79
	v_mul_f32_e32 v73, v73, v73
	v_fmac_f32_e32 v77, v76, v76
	v_fmac_f32_e32 v71, v70, v70
	v_fmac_f32_e32 v79, v78, v78
	v_fmac_f32_e32 v73, v72, v72
	v_add_f32_e32 v70, v77, v71
	v_add_f32_e32 v71, v79, v73
	v_add_f32_e32 v76, v70, v71
	global_store_dwordx4 v[74:75], v[60:63], off
	s_waitcnt vmcnt(1)
	v_lshlrev_b32_e32 v70, 16, v64
	v_and_b32_e32 v71, 0xffff0000, v64
	v_lshlrev_b32_e32 v64, 16, v65
	v_and_b32_e32 v65, 0xffff0000, v65
	v_lshlrev_b32_e32 v72, 16, v66
	v_and_b32_e32 v73, 0xffff0000, v66
	v_lshlrev_b32_e32 v66, 16, v67
	v_and_b32_e32 v67, 0xffff0000, v67
	v_pk_fma_f32 v[58:59], v[58:59], v[80:81], v[64:65] op_sel_hi:[1,0,1]
	v_pk_fma_f32 v[56:57], v[56:57], v[80:81], v[70:71] op_sel_hi:[1,0,1]
	v_pk_fma_f32 v[64:65], v[54:55], v[80:81], v[66:67] op_sel_hi:[1,0,1]
	v_pk_fma_f32 v[66:67], v[52:53], v[80:81], v[72:73] op_sel_hi:[1,0,1]
	v_mul_f32_e32 v52, v57, v57
	v_mul_f32_e32 v53, v59, v59
	v_mul_f32_e32 v54, v67, v67
	v_mul_f32_e32 v55, v65, v65
	v_fmac_f32_e32 v52, v56, v56
	v_fmac_f32_e32 v53, v58, v58
	v_fmac_f32_e32 v54, v66, v66
	v_fmac_f32_e32 v55, v64, v64
	v_add_f32_e32 v52, v52, v53
	v_add_f32_e32 v53, v54, v55
	v_add_f32_e32 v52, v52, v53
	v_add_f32_e32 v52, v76, v52
	ds_bpermute_b32 v53, v1, v52
	v_cvt_pk_bf16_f32 v54, v56, v57
	v_cvt_pk_bf16_f32 v55, v58, v59
	v_cvt_pk_bf16_f32 v56, v66, v67
	v_cvt_pk_bf16_f32 v57, v64, v65
	s_waitcnt lgkmcnt(0)
	v_add_f32_e32 v52, v52, v53
	ds_bpermute_b32 v53, v118, v52
	global_store_dwordx4 v[74:75], v[54:57], off offset:256
	s_and_saveexec_b64 s[0:1], s[40:41]
	s_cbranch_execz .LBB0_750
	v_lshl_add_u64 v[54:55], v[68:69], 2, s[44:45]
	s_waitcnt lgkmcnt(0)
	v_add_f32_e32 v52, v52, v53
	global_atomic_add_f32 v[54:55], v52, off
; __device__ __forceinline__ float sq4(f32x4 a) { return (a.x * a.x + a.y * a.y) + (a.z * a.z + a.w * a.w); }
; __device__ __forceinline__ u32x4 pack8(f32x4 a, f32x4 b) { u32x4 o; o.x = cvt_pk(a.x, a.y); o.y = cvt_pk(a.z, a.w); o.z = cvt_pk(b.x, b.y); o.w = cvt_pk(b.z, b.w); return o; }
; __device__ __forceinline__ float rstd_of(const float* SS, int row, float invw) { return 1.0f / sqrtf(SS[row] * invw + EPS); }
;     __device__ __forceinline__ void operator()(const f32x4 (&acc)[2][2][4][2], const pg8::Unit& u, int wr, int wc, int fr, int fq) const {
;         const int row0 = u.pm * 256 + wr * 64 + fr, col0 = u.pn * 256 + wc * 32 + 8 * fq;
; #pragma unroll
;         for (int ai = 0; ai < 2; ++ai)
; #pragma unroll
;             for (int m = 0; m < 4; ++m) {
;                 const int row = row0 + ai * 128 + m * 16; float ssq = 0.f;
;                 const float rb = rstd_of(SSB, row, 1.f / 512.f);
; #pragma unroll
;                 for (int bj = 0; bj < 2; ++bj) {
;                     const size_t idx = (size_t)row * D + col0 + bj * 128;
;                     const u32x4 w = *(const u32x4*)(X + idx);
;                     const f32x4 r0 = {bflo(w.x), bfhi(w.x), bflo(w.y), bfhi(w.y)}, r1 = {bflo(w.z), bfhi(w.z), bflo(w.w), bfhi(w.w)};
;                     const f32x4 v0 = r0 + acc[ai][bj][m][0] * rb, v1 = r1 + acc[ai][bj][m][1] * rb;
;                     ssq += sq4(v0) + sq4(v1);
;                     *(u32x4*)(X + idx) = pack8(v0, v1);
;                 }
;                 row_stat_add(SS, row, ssq, fq);
;             }
;     }
.LBB0_750:
	s_or_b64 exec, exec, s[0:1]
	global_load_dword v60, v[152:153], off offset:576
	v_add_u32_e32 v52, 0x90, v150
	s_waitcnt lgkmcnt(0)
	v_ashrrev_i32_e32 v53, 31, v52
	v_lshlrev_b64 v[54:55], 11, v[52:53]
	v_lshl_add_u64 v[54:55], s[96:97], 0, v[54:55]
	v_lshl_add_u64 v[58:59], v[2:3], 1, v[54:55]
	global_load_dwordx4 v[54:57], v[58:59], off
	s_waitcnt vmcnt(1)
	v_fmamk_f32 v60, v60, 0x3b000000, v148
	s_waitcnt vmcnt(0)
	v_lshlrev_b32_e32 v62, 16, v56
	v_rsq_f32_e32 v64, v60
	s_nop 0
	v_lshlrev_b32_e32 v60, 16, v54
	v_and_b32_e32 v61, 0xffff0000, v54
	v_lshlrev_b32_e32 v54, 16, v55
	v_and_b32_e32 v55, 0xffff0000, v55
	v_and_b32_e32 v63, 0xffff0000, v56
	v_lshlrev_b32_e32 v56, 16, v57
	v_and_b32_e32 v57, 0xffff0000, v57
	v_pk_fma_f32 v[54:55], v[50:51], v[64:65], v[54:55] op_sel_hi:[1,0,1]
	v_pk_fma_f32 v[60:61], v[48:49], v[64:65], v[60:61] op_sel_hi:[1,0,1]
	v_pk_fma_f32 v[56:57], v[46:47], v[64:65], v[56:57] op_sel_hi:[1,0,1]
	v_pk_fma_f32 v[62:63], v[44:45], v[64:65], v[62:63] op_sel_hi:[1,0,1]
	v_cvt_pk_bf16_f32 v44, v60, v61
	v_cvt_pk_bf16_f32 v45, v54, v55
	v_mul_f32_e32 v61, v61, v61
	v_cvt_pk_bf16_f32 v46, v62, v63
	v_cvt_pk_bf16_f32 v47, v56, v57
	global_load_dwordx4 v[48:51], v[58:59], off offset:256
	v_mul_f32_e32 v55, v55, v55
	v_mul_f32_e32 v63, v63, v63
	v_mul_f32_e32 v57, v57, v57
	v_fmac_f32_e32 v61, v60, v60
	v_fmac_f32_e32 v55, v54, v54
	v_fmac_f32_e32 v63, v62, v62
	v_fmac_f32_e32 v57, v56, v56
	v_add_f32_e32 v54, v61, v55
	v_add_f32_e32 v55, v63, v57
	v_add_f32_e32 v60, v54, v55
	global_store_dwordx4 v[58:59], v[44:47], off
	s_waitcnt vmcnt(1)
	v_lshlrev_b32_e32 v54, 16, v48
	v_and_b32_e32 v55, 0xffff0000, v48
	v_lshlrev_b32_e32 v48, 16, v49
	v_and_b32_e32 v49, 0xffff0000, v49
	v_lshlrev_b32_e32 v56, 16, v50
	v_and_b32_e32 v57, 0xffff0000, v50
	v_lshlrev_b32_e32 v50, 16, v51
	v_and_b32_e32 v51, 0xffff0000, v51
	v_pk_fma_f32 v[42:43], v[42:43], v[64:65], v[48:49] op_sel_hi:[1,0,1]
	v_pk_fma_f32 v[40:41], v[40:41], v[64:65], v[54:55] op_sel_hi:[1,0,1]
	v_pk_fma_f32 v[48:49], v[38:39], v[64:65], v[50:51] op_sel_hi:[1,0,1]
	v_pk_fma_f32 v[50:51], v[36:37], v[64:65], v[56:57] op_sel_hi:[1,0,1]
	v_mul_f32_e32 v36, v41, v41
	v_mul_f32_e32 v37, v43, v43
	v_mul_f32_e32 v38, v51, v51
	v_mul_f32_e32 v39, v49, v49
	v_fmac_f32_e32 v36, v40, v40
	v_fmac_f32_e32 v37, v42, v42
	v_fmac_f32_e32 v38, v50, v50
	v_fmac_f32_e32 v39, v48, v48
	v_add_f32_e32 v36, v36, v37
	v_add_f32_e32 v37, v38, v39
	v_add_f32_e32 v36, v36, v37
	v_add_f32_e32 v36, v60, v36
	ds_bpermute_b32 v37, v1, v36
	v_cvt_pk_bf16_f32 v38, v40, v41
	v_cvt_pk_bf16_f32 v39, v42, v43
	v_cvt_pk_bf16_f32 v40, v50, v51
	v_cvt_pk_bf16_f32 v41, v48, v49
	s_waitcnt lgkmcnt(0)
	v_add_f32_e32 v36, v36, v37
	ds_bpermute_b32 v37, v118, v36
	global_store_dwordx4 v[58:59], v[38:41], off offset:256
	s_and_saveexec_b64 s[0:1], s[40:41]
	s_cbranch_execz .LBB0_752
	v_lshl_add_u64 v[38:39], v[52:53], 2, s[44:45]
	s_waitcnt lgkmcnt(0)
	v_add_f32_e32 v36, v36, v37
	global_atomic_add_f32 v[38:39], v36, off
.LBB0_752:
	s_or_b64 exec, exec, s[0:1]
	global_load_dword v44, v[152:153], off offset:640
	v_add_u32_e32 v36, 0xa0, v150
	s_waitcnt lgkmcnt(0)
	v_ashrrev_i32_e32 v37, 31, v36
	v_lshlrev_b64 v[38:39], 11, v[36:37]
	v_lshl_add_u64 v[38:39], s[96:97], 0, v[38:39]
	v_lshl_add_u64 v[42:43], v[2:3], 1, v[38:39]
	global_load_dwordx4 v[38:41], v[42:43], off
	s_waitcnt vmcnt(1)
	v_fmamk_f32 v44, v44, 0x3b000000, v148
	s_waitcnt vmcnt(0)
	v_lshlrev_b32_e32 v46, 16, v40
	v_rsq_f32_e32 v48, v44
	s_nop 0
	v_lshlrev_b32_e32 v44, 16, v38
	v_and_b32_e32 v45, 0xffff0000, v38
	v_lshlrev_b32_e32 v38, 16, v39
	v_and_b32_e32 v39, 0xffff0000, v39
	v_and_b32_e32 v47, 0xffff0000, v40
	v_lshlrev_b32_e32 v40, 16, v41
	v_and_b32_e32 v41, 0xffff0000, v41
	v_pk_fma_f32 v[38:39], v[34:35], v[48:49], v[38:39] op_sel_hi:[1,0,1]
	v_pk_fma_f32 v[44:45], v[32:33], v[48:49], v[44:45] op_sel_hi:[1,0,1]
	v_pk_fma_f32 v[40:41], v[30:31], v[48:49], v[40:41] op_sel_hi:[1,0,1]
	v_pk_fma_f32 v[46:47], v[28:29], v[48:49], v[46:47] op_sel_hi:[1,0,1]
	v_cvt_pk_bf16_f32 v28, v44, v45
	v_cvt_pk_bf16_f32 v29, v38, v39
	v_mul_f32_e32 v45, v45, v45
	v_cvt_pk_bf16_f32 v30, v46, v47
	v_cvt_pk_bf16_f32 v31, v40, v41
	global_load_dwordx4 v[32:35], v[42:43], off offset:256
	v_mul_f32_e32 v39, v39, v39
	v_mul_f32_e32 v47, v47, v47
	v_mul_f32_e32 v41, v41, v41
	v_fmac_f32_e32 v45, v44, v44
	v_fmac_f32_e32 v39, v38, v38
	v_fmac_f32_e32 v47, v46, v46
	v_fmac_f32_e32 v41, v40, v40
	v_add_f32_e32 v38, v45, v39
	v_add_f32_e32 v39, v47, v41
	v_add_f32_e32 v44, v38, v39
	global_store_dwordx4 v[42:43], v[28:31], off
	s_waitcnt vmcnt(1)
	v_lshlrev_b32_e32 v38, 16, v32
	v_and_b32_e32 v39, 0xffff0000, v32
	v_lshlrev_b32_e32 v32, 16, v33
	v_and_b32_e32 v33, 0xffff0000, v33
	v_lshlrev_b32_e32 v40, 16, v34
	v_and_b32_e32 v41, 0xffff0000, v34
	v_lshlrev_b32_e32 v34, 16, v35
	v_and_b32_e32 v35, 0xffff0000, v35
	v_pk_fma_f32 v[26:27], v[26:27], v[48:49], v[32:33] op_sel_hi:[1,0,1]
	v_pk_fma_f32 v[24:25], v[24:25], v[48:49], v[38:39] op_sel_hi:[1,0,1]
	v_pk_fma_f32 v[32:33], v[22:23], v[48:49], v[34:35] op_sel_hi:[1,0,1]
	v_pk_fma_f32 v[34:35], v[20:21], v[48:49], v[40:41] op_sel_hi:[1,0,1]
	v_mul_f32_e32 v20, v25, v25
	v_mul_f32_e32 v21, v27, v27
	v_mul_f32_e32 v22, v35, v35
	v_mul_f32_e32 v23, v33, v33
	v_fmac_f32_e32 v20, v24, v24
	v_fmac_f32_e32 v21, v26, v26
	v_fmac_f32_e32 v22, v34, v34
	v_fmac_f32_e32 v23, v32, v32
	v_add_f32_e32 v20, v20, v21
	v_add_f32_e32 v21, v22, v23
	v_add_f32_e32 v20, v20, v21
	v_add_f32_e32 v20, v44, v20
	ds_bpermute_b32 v21, v1, v20
	v_cvt_pk_bf16_f32 v22, v24, v25
	v_cvt_pk_bf16_f32 v23, v26, v27
	v_cvt_pk_bf16_f32 v24, v34, v35
	v_cvt_pk_bf16_f32 v25, v32, v33
	s_waitcnt lgkmcnt(0)
	v_add_f32_e32 v20, v20, v21
	ds_bpermute_b32 v21, v118, v20
	global_store_dwordx4 v[42:43], v[22:25], off offset:256
	s_and_saveexec_b64 s[0:1], s[40:41]
	s_cbranch_execz .LBB0_754
	v_lshl_add_u64 v[22:23], v[36:37], 2, s[44:45]
	s_waitcnt lgkmcnt(0)
	v_add_f32_e32 v20, v20, v21
	global_atomic_add_f32 v[22:23], v20, off
